# v26: v25 plus bf16 packs written straight to their destination register (103 copy instructions removed: phase 2, GLA, mixer)
# speedup vs baseline: 1.0096x; 1.0076x over previous
; __device__ __forceinline__ unsigned pk2(float lo, float hi) { return f2bf(lo) | (f2bf(hi) << 16); }
; __device__ __forceinline__ void phase_prologue(const Params& P, LAS unsigned char* lds) {
;     ...
;     for (int i = blockIdx.x * 512 + tid; i < 8 * 128 * 128 / 4; i += G * 512) {
;         const int e = 4 * i, t = (e >> 7) & 127, s = e & 127; const f32x4 v = *(const f32x4*)(P.w_spatial + e);
;         u32x2 o; o.x = pk2(s <= t ? v[0] : 0.f, s + 1 <= t ? v[1] : 0.f); o.y = pk2(s + 2 <= t ? v[2] : 0.f, s + 3 <= t ? v[3] : 0.f);
;         *(u32x2*)(WsT + e) = o;
;     }
.LBB0_96:
	v_ashrrev_i32_e32 v1, 31, v0
	v_lshl_add_u64 v[4:5], v[0:1], 2, s[50:51]
	global_load_dwordx4 v[4:7], v[4:5], off
	v_bfe_u32 v3, v2, 5, 7
	s_waitcnt vmcnt(36)
	v_and_b32_e32 v10, 0x7c, v0
	v_add_u32_e32 v2, s3, v2
	s_waitcnt vmcnt(35)
	v_or_b32_e32 v11, 2, v10
	v_cmp_lt_i32_e32 vcc, s17, v2
	v_or_b32_e32 v12, 3, v10
	v_cmp_le_u32_e64 s[6:7], v11, v3
	s_or_b64 s[14:15], vcc, s[14:15]
	v_cmp_le_u32_e32 vcc, v10, v3
	v_lshl_add_u64 v[8:9], v[0:1], 1, s[12:13]
	v_cmp_lt_u32_e64 s[4:5], v10, v3
	v_cmp_le_u32_e64 s[8:9], v12, v3
	v_add_u32_e32 v0, s16, v0
	s_waitcnt vmcnt(0)
	v_cndmask_b32_e32 v1, 0, v4, vcc
	v_cndmask_b32_e64 v4, 0, v6, s[6:7]
	v_cndmask_b32_e64 v3, 0, v5, s[4:5]
	v_cndmask_b32_e64 v5, 0, v7, s[8:9]
	v_bfe_u32 v7, v3, 16, 1
	v_cvt_pk_bf16_f32 v210, v1, v3
	v_cvt_pk_bf16_f32 v5, v4, v5
	v_add3_u32 v3, v3, v7, s17
	v_mov_b32_e32 v4, v210
	global_store_dwordx2 v[8:9], v[4:5], off
	s_andn2_b64 exec, exec, s[14:15]
	s_cbranch_execnz .LBB0_96

; __device__ __forceinline__ unsigned pk2(float lo, float hi) { return f2bf(lo) | (f2bf(hi) << 16); }
; __device__ __forceinline__ void phase_gla_pre(const Params& P, LAS unsigned char* lds, bool dry) {
;     ...
;             const int t = 16 * tt + fr, sb = 16 * st + 4 * g;
;             u32x2 o; o.x = pk2(sb <= t ? acc[0] : 0.f, sb + 1 <= t ? acc[1] : 0.f); o.y = pk2(sb + 2 <= t ? acc[2] : 0.f, sb + 3 <= t ? acc[3] : 0.f);
;             if (!dry) *(u32x2*)(PB + (size_t)item * 4096 + t * 64 + sb) = o;
.LBB0_479:
	s_or_b64 exec, exec, s[42:43]
	s_nop 5
	v_cndmask_b32_e64 v20, v20, 0, s[26:27]
	v_cndmask_b32_e64 v21, 0, v21, s[28:29]
	v_cvt_pk_bf16_f32 v20, v20, v21
	v_cndmask_b32_e64 v21, v22, 0, s[30:31]
	v_bfe_u32 v22, v21, 16, 1
	v_add3_u32 v21, v21, v22, s86
	v_cndmask_b32_e64 v22, v23, 0, s[34:35]
	v_bfe_u32 v23, v22, 16, 1
	v_lshrrev_b32_e32 v21, 16, v21
	v_add3_u32 v22, v22, v23, s86
	v_and_or_b32 v21, v22, s87, v21
	s_add_i32 s1, s1, s3
	s_add_i32 s84, s84, s85
	s_andn2_b64 vcc, exec, s[36:37]
	s_mov_b32 s80, s82
	global_store_dwordx2 v[24:25], v[20:21], off offset:32
	s_barrier
	s_cbranch_vccz .LBB0_502

; __device__ __forceinline__ float bf2f(unsigned b) { return __uint_as_float(b << 16); }
; __device__ __forceinline__ unsigned f2bf(float f) { unsigned u = __float_as_uint(f); return (u + 0x7fffu + ((u >> 16) & 1u)) >> 16; }
; __device__ __forceinline__ void split8(const f32x4 x0, const f32x4 x1, bf16x8& hi, bf16x8& lo) {
; #pragma unroll
;     for (int j = 0; j < 8; ++j) { const float x = j < 4 ? x0[j & 3] : x1[j & 3]; const unsigned h = f2bf(x); const unsigned l = f2bf(x - bf2f(h)); hi[j] = (short)h; lo[j] = (short)l; }
; }
; __device__ __forceinline__ void phase_gla_pre(const Params& P, LAS unsigned char* lds, bool dry) {
;     ...
;         if (g < 2) { f32x4 w0, w1;
; #pragma unroll
;             for (int j = 0; j < 4; ++j) { w0[j] = P.w_gate_up[(8 * g + j) * 512 + h * 128 + 16 * w + fr]; w1[j] = P.w_gate_up[(8 * g + 4 + j) * 512 + h * 128 + 16 * w + fr]; }
;             split8(w0, w1, bhi, blo); }
.Lp2_nopf:
	s_ashr_i32 s82, s80, 6
	s_lshl_b32 s36, s82, 7
	s_and_b32 s42, s36, 0x180
	v_mov_b32_e32 v24, 0
	v_mov_b32_e32 v25, 0
	v_mov_b32_e32 v26, 0
	v_mov_b32_e32 v27, 0
	v_mov_b32_e32 v20, 0
	v_mov_b32_e32 v21, 0
	v_mov_b32_e32 v22, 0
	v_mov_b32_e32 v23, 0
	s_cmp_lg_u32 s98, 0
	s_cbranch_scc1 .Lp2_hoisted
	s_and_saveexec_b64 s[36:37], s[6:7]
	s_cbranch_execz .LBB0_484
	v_or_b32_e32 v28, s42, v80
	v_or_b32_e32 v26, 0x400, v28
	v_add_u32_e32 v20, v28, v81
	v_add_u32_e32 v24, v26, v81
	v_add_u32_e32 v26, v26, v82
	v_or_b32_e32 v30, 0x600, v28
	v_ashrrev_i32_e32 v21, 31, v20
	v_add_u32_e32 v22, v28, v82
	v_ashrrev_i32_e32 v25, 31, v24
	v_ashrrev_i32_e32 v27, 31, v26
	v_add_u32_e32 v28, v30, v81
	v_add_u32_e32 v30, v30, v82
	v_lshl_add_u64 v[20:21], v[20:21], 2, s[54:55]
	v_ashrrev_i32_e32 v23, 31, v22
	v_lshl_add_u64 v[24:25], v[24:25], 2, s[54:55]
	v_lshl_add_u64 v[26:27], v[26:27], 2, s[54:55]
	v_ashrrev_i32_e32 v29, 31, v28
	v_ashrrev_i32_e32 v31, 31, v30
	v_lshl_add_u64 v[22:23], v[22:23], 2, s[54:55]
	v_lshl_add_u64 v[28:29], v[28:29], 2, s[54:55]
	v_lshl_add_u64 v[30:31], v[30:31], 2, s[54:55]
	global_load_dword v34, v[20:21], off
	global_load_dword v36, v[22:23], off
	global_load_dword v37, v[22:23], off offset:2048
	s_nop 0
	global_load_dword v24, v[24:25], off
	s_nop 0
	global_load_dword v26, v[26:27], off
	s_nop 0
	global_load_dword v25, v[28:29], off
	global_load_dword v27, v[30:31], off
	global_load_dword v35, v[20:21], off offset:2048
	s_waitcnt vmcnt(7)
	v_and_b32_sdwa v20, v34, v95 dst_sel:DWORD dst_unused:UNUSED_PAD src0_sel:WORD_1 src1_sel:DWORD
	s_waitcnt vmcnt(6)
	v_and_b32_sdwa v22, v36, v95 dst_sel:DWORD dst_unused:UNUSED_PAD src0_sel:WORD_1 src1_sel:DWORD
	s_waitcnt vmcnt(5)
	v_and_b32_sdwa v21, v37, v95 dst_sel:DWORD dst_unused:UNUSED_PAD src0_sel:WORD_1 src1_sel:DWORD
	v_add3_u32 v33, v34, v20, s86
	s_waitcnt vmcnt(4)
	v_and_b32_sdwa v29, v24, v95 dst_sel:DWORD dst_unused:UNUSED_PAD src0_sel:WORD_1 src1_sel:DWORD
	s_waitcnt vmcnt(2)
	v_and_b32_sdwa v20, v25, v95 dst_sel:DWORD dst_unused:UNUSED_PAD src0_sel:WORD_1 src1_sel:DWORD
	s_waitcnt vmcnt(1)
	v_and_b32_sdwa v31, v27, v95 dst_sel:DWORD dst_unused:UNUSED_PAD src0_sel:WORD_1 src1_sel:DWORD
	s_waitcnt vmcnt(0)
	v_and_b32_sdwa v23, v35, v95 dst_sel:DWORD dst_unused:UNUSED_PAD src0_sel:WORD_1 src1_sel:DWORD
	v_and_b32_sdwa v38, v26, v95 dst_sel:DWORD dst_unused:UNUSED_PAD src0_sel:WORD_1 src1_sel:DWORD
	v_add3_u32 v30, v37, v21, s86
	v_add3_u32 v22, v36, v22, s86
	v_add3_u32 v23, v35, v23, s86
	v_add3_u32 v40, v25, v20, s86
	v_add3_u32 v41, v24, v29, s86
	v_add3_u32 v42, v27, v31, s86
	v_add3_u32 v43, v26, v38, s86
	v_and_b32_e32 v28, 0xffff0000, v33
	v_and_b32_e32 v21, 0xffff0000, v30
	v_and_b32_e32 v20, 0xffff0000, v22
	v_cvt_pk_bf16_f32 v22, v36, v37
	v_and_b32_e32 v29, 0xffff0000, v23
	v_and_b32_e32 v31, 0xffff0000, v40
	v_and_b32_e32 v30, 0xffff0000, v41
	v_and_b32_e32 v39, 0xffff0000, v42
	v_and_b32_e32 v38, 0xffff0000, v43
	v_pk_add_f32 v[36:37], v[36:37], v[20:21] neg_lo:[0,1] neg_hi:[0,1]
	v_pk_add_f32 v[28:29], v[34:35], v[28:29] neg_lo:[0,1] neg_hi:[0,1]
	v_cvt_pk_bf16_f32 v21, v24, v25
	v_pk_add_f32 v[24:25], v[24:25], v[30:31] neg_lo:[0,1] neg_hi:[0,1]
	v_cvt_pk_bf16_f32 v23, v26, v27
	v_pk_add_f32 v[26:27], v[26:27], v[38:39] neg_lo:[0,1] neg_hi:[0,1]
	v_cvt_pk_bf16_f32 v20, v34, v35
	v_cvt_pk_bf16_f32 v138, v36, v37
	v_cvt_pk_bf16_f32 v27, v26, v27
	v_cvt_pk_bf16_f32 v25, v24, v25
	v_cvt_pk_bf16_f32 v24, v28, v29
	v_mov_b32_e32 v26, v138

; #define LAS __attribute__((address_space(3)))
; __device__ __forceinline__ void phase_gla_pre(const Params& P, LAS unsigned char* lds, bool dry) {
;     ...
;         for (int tt = 0; tt < 4; ++tt) {
;             bf16x8 ahi = (bf16x8){0, 0, 0, 0, 0, 0, 0, 0}, alo = ahi;
;             if (g < 2) { const f32x4 l0 = *(const LAS f32x4*)(Llr + (16 * tt + fr) * 16 + 8 * g), l1 = *(const LAS f32x4*)(Llr + (16 * tt + fr) * 16 + 8 * g + 4); split8(l0, l1, ahi, alo); }
;             f32x4 acc = (f32x4){bg, bg, bg, bg};
;             acc = __builtin_amdgcn_mfma_f32_16x16x32_bf16(alo, bhi, acc, 0, 0, 0); acc = __builtin_amdgcn_mfma_f32_16x16x32_bf16(ahi, blo, acc, 0, 0, 0); acc = __builtin_amdgcn_mfma_f32_16x16x32_bf16(ahi, bhi, acc, 0, 0, 0);
;             float pr[4];
; #pragma unroll
;             for (int r = 0; r < 4; ++r) { const float lg = acc[r]; const float ls = fminf(lg, 0.f) - __logf(1.0f + __expf(-fabsf(lg))); pr[r] = ls * (1.0f / 16.0f) + (r ? pr[r - 1] : 0.f); }
;             const float T = pr[3];
;             const float u1 = __shfl_up(T, 16), s1 = T + (g >= 1 ? u1 : 0.f);
;             const float u2 = __shfl_up(s1, 32), s2 = s1 + (g >= 2 ? u2 : 0.f);
;             const float base = run + (s2 - T); run += __shfl(s2, 48 + fr);
; #pragma unroll
;             for (int r = 0; r < 4; ++r) *(LAS float*)(Lb + (16 * tt + 4 * g + r) * BP + (16 * w + fr) * 4) = base + pr[r];
;         }
;         __syncthreads();
;         {
;             f32x4 bb[4], bm[4], bl[4];
; #pragma unroll
;             for (int i = 0; i < 4; ++i) { bb[i] = *(const LAS f32x4*)(Lb + te * BP + (16 * kc + 4 * i) * 4); bm[i] = *(const LAS f32x4*)(Lb + 31 * BP + (16 * kc + 4 * i) * 4); bl[i] = *(const LAS f32x4*)(Lb + 63 * BP + (16 * kc + 4 * i) * 4); }
;             unsigned oqi[8], oki[8], oqd[8], oks[8];
; #pragma unroll
;             for (int e2 = 0; e2 < 8; ++e2) {
;                 const unsigned qw = e2 < 4 ? rq[0][e2] : rq[1][e2 - 4], kw = e2 < 4 ? rk[0][e2] : rk[1][e2 - 4];
;                 float vqi[2], vki[2], vqd[2], vks[2];
; #pragma unroll
;                 for (int hh = 0; hh < 2; ++hh) {
;                     const int e = 2 * e2 + hh; const float bv = bb[e >> 2][e & 3], bmv = bm[e >> 2][e & 3], blv = bl[e >> 2][e & 3];
;                     const float qv = hh ? bfhi(qw) : bflo(qw), kv = hh ? bfhi(kw) : bflo(kw);
;                     const float e1 = __expf(bv - bmv);
.LBB0_492:
	s_or_b64 exec, exec, s[36:37]
	s_nop 0
	v_mfma_f32_16x16x32_bf16 v[28:31], v[124:127], v[20:23], v[28:31]
	v_and_b32_e32 v111, 0xffff0000, v5
	v_and_b32_e32 v110, 0xffff0000, v4
	v_and_b32_e32 v117, 0xffff0000, v13
	v_mfma_f32_16x16x32_bf16 v[24:27], v[128:131], v[24:27], v[28:31]
	v_and_b32_e32 v116, 0xffff0000, v12
	v_and_b32_e32 v121, 0xffff0000, v7
	v_and_b32_e32 v120, 0xffff0000, v6
	v_mfma_f32_16x16x32_bf16 v[20:23], v[128:131], v[20:23], v[24:27]
	v_and_b32_e32 v127, 0xffff0000, v17
	v_and_b32_e32 v126, 0xffff0000, v16
	v_lshlrev_b32_e32 v125, 16, v17
	v_lshlrev_b32_e32 v124, 16, v16
	v_lshlrev_b32_e32 v133, 16, v11
	s_nop 2
	v_min_f32_e32 v24, 0, v20
	v_mul_f32_e64 v20, |v20|, s89
	v_exp_f32_e32 v20, v20
	v_mul_f32_e64 v25, |v21|, s89
	v_exp_f32_e32 v25, v25
	v_add_f32_e32 v20, 1.0, v20
	v_add_f32_e32 v25, 1.0, v25
	v_log_f32_e32 v20, v20
	v_log_f32_e32 v25, v25
	v_mul_f32_e32 v27, 0x3f317217, v20
	v_fma_f32 v27, v20, s91, -v27
	v_fmac_f32_e32 v27, 0x3377d1cf, v20
	v_fmac_f32_e32 v27, 0x3f317217, v20
	v_mul_f32_e32 v28, 0x3f317217, v25
	v_sub_f32_e32 v20, v24, v27
	v_fma_f32 v24, v25, s91, -v28
	v_fmac_f32_e32 v24, 0x3377d1cf, v25
	v_fmac_f32_e32 v24, 0x3f317217, v25
	v_min_f32_e32 v21, 0, v21
	v_mul_f32_e64 v25, |v22|, s89
	v_exp_f32_e32 v25, v25
	v_sub_f32_e32 v21, v21, v24
	v_add_f32_e32 v24, 1.0, v25
	v_min_f32_e32 v22, 0, v22
	v_fma_f32 v20, v20, s93, 0
	v_log_f32_e32 v24, v24
	v_fmamk_f32 v21, v21, 0x3d800000, v20
	v_lshlrev_b32_e32 v132, 16, v10
	v_mul_f32_e32 v25, 0x3f317217, v24
	v_fma_f32 v25, v24, s91, -v25
	v_fmac_f32_e32 v25, 0x3377d1cf, v24
	v_fmac_f32_e32 v25, 0x3f317217, v24
	v_and_b32_e32 v135, 0xffff0000, v11
	v_and_b32_e32 v134, 0xffff0000, v10
	v_mov_b32_e32 v24, v25
	v_mul_f32_e64 v25, |v23|, s89
	v_exp_f32_e32 v25, v25
	v_sub_f32_e32 v22, v22, v24
	v_add_f32_e32 v24, 1.0, v25
	v_min_f32_e32 v23, 0, v23
	v_fmamk_f32 v22, v22, 0x3d800000, v21
	v_log_f32_e32 v24, v24
	s_waitcnt lgkmcnt(2)
	v_add_f32_e32 v26, v40, v41
	s_and_b32 s74, s1, 0xfc0
	s_ashr_i32 s83, s82, 31
	v_mul_f32_e32 v25, 0x3f317217, v24
	v_fma_f32 v25, v24, s91, -v25
	v_fmac_f32_e32 v25, 0x3377d1cf, v24
	v_fmac_f32_e32 v25, 0x3f317217, v24
	s_nop 1
	v_sub_f32_e32 v23, v23, v25
	v_fmamk_f32 v23, v23, 0x3d800000, v22
	ds_bpermute_b32 v24, v83, v23
	s_lshl_b64 s[36:37], s[82:83], 20
	s_waitcnt lgkmcnt(0)
	v_cndmask_b32_e64 v24, v24, 0, s[8:9]
	v_add_f32_e32 v24, v24, v23
	ds_bpermute_b32 v25, v84, v24
	s_waitcnt lgkmcnt(0)
	v_cndmask_b32_e64 v25, 0, v25, s[10:11]
	v_add_f32_e32 v24, v25, v24
	v_sub_f32_e32 v24, v24, v23
	v_add_f32_e32 v24, v26, v24
	v_add_f32_e32 v20, v20, v24
	v_add_f32_e32 v21, v21, v24
	v_add_u32_e32 v25, 0xea00, v98
	ds_write2_b32 v25, v20, v21 offset0:64 offset1:196
	v_add_f32_e32 v20, v22, v24
	v_add_f32_e32 v21, v23, v24
	v_add_u32_e32 v22, 0xee00, v98
	ds_write2_b32 v22, v20, v21 offset0:72 offset1:204
	v_add_u32_e32 v22, s94, v87
	s_waitcnt lgkmcnt(0)
	s_barrier
	v_add_u32_e32 v20, v86, v87
	v_add_u32_e32 v21, 0, v87
	ds_read_b128 v[32:35], v22
	ds_read_b128 v[24:27], v89
	ds_read_b128 v[60:63], v21 offset:51184
	ds_read_b128 v[64:67], v20 offset:34816
	ds_read_b128 v[74:77], v20 offset:34832
	ds_read_b128 v[44:47], v20 offset:34848
	ds_read_b128 v[36:39], v20 offset:34864
	ds_read_b128 v[100:103], v21 offset:51200
	s_waitcnt lgkmcnt(4)
	v_sub_f32_e32 v61, v65, v61
	v_mul_f32_e32 v61, 0x3fb8aa3b, v61
	v_sub_f32_e32 v63, v67, v63
	v_exp_f32_e32 v72, v61
	v_sub_f32_e32 v61, v32, v64
	v_mul_f32_e32 v63, 0x3fb8aa3b, v63
	v_mul_f32_e32 v61, 0x3fb8aa3b, v61
	v_exp_f32_e32 v73, v63
	v_exp_f32_e32 v78, v61
	v_mul_f32_e32 v61, 0x3fb8aa3b, v65
	v_sub_f32_e32 v20, v64, v60
	v_exp_f32_e32 v108, v61
	v_sub_f32_e32 v61, v66, v62
	v_mul_f32_e32 v20, 0x3fb8aa3b, v20
	v_mul_f32_e32 v69, 0x3fb8aa3b, v64
	v_mul_f32_e32 v61, 0x3fb8aa3b, v61
	v_sub_f32_e32 v62, v33, v65
	v_mul_f32_e32 v65, 0x3fb8aa3b, v66
	v_sub_f32_e32 v63, v34, v66
	v_exp_f32_e32 v60, v20
	v_exp_f32_e32 v70, v69
	v_rcp_f32_e32 v64, v72
	v_exp_f32_e32 v61, v61
	v_exp_f32_e32 v71, v65
	v_mul_f32_e32 v63, 0x3fb8aa3b, v63
	v_rcp_f32_e32 v65, v73
	v_exp_f32_e32 v79, v63
	v_mul_f32_e32 v63, 0x3fb8aa3b, v67
	v_exp_f32_e32 v109, v63
	v_sub_f32_e32 v63, v35, v67
	v_lshlrev_b32_e32 v67, 16, v5
	v_lshlrev_b32_e32 v66, 16, v4
	v_pk_mul_f32 v[112:113], v[60:61], v[66:67]
	v_pk_mul_f32 v[114:115], v[72:73], v[110:111]
	v_pk_mul_f32 v[72:73], v[64:65], v[116:117]
	v_pk_mul_f32 v[64:65], v[70:71], v[66:67]
	s_waitcnt lgkmcnt(0)
	v_sub_f32_e32 v66, v74, v100
	v_mul_f32_e32 v66, 0x3fb8aa3b, v66
	v_mul_f32_e32 v71, 0x3fb8aa3b, v74
	v_exp_f32_e32 v70, v66
	v_pk_mul_f32 v[66:67], v[108:109], v[110:111]
	v_exp_f32_e32 v108, v71
	v_sub_f32_e32 v71, v75, v101
	v_mul_f32_e32 v71, 0x3fb8aa3b, v71
	v_mul_f32_e32 v62, 0x3fb8aa3b, v62
	v_mul_f32_e32 v63, 0x3fb8aa3b, v63
	v_exp_f32_e32 v100, v71
	v_sub_f32_e32 v71, v24, v74
	v_exp_f32_e32 v62, v62
	v_exp_f32_e32 v63, v63
	v_mul_f32_e32 v71, 0x3fb8aa3b, v71
	v_exp_f32_e32 v74, v71
	v_mul_f32_e32 v71, 0x3fb8aa3b, v75
	v_sub_f32_e32 v75, v25, v75
	v_mul_f32_e32 v75, 0x3fb8aa3b, v75
	v_exp_f32_e32 v118, v75
	v_mul_f32_e32 v75, 0x3fb8aa3b, v76
	v_pk_mul_f32 v[62:63], v[62:63], v[116:117]
	v_exp_f32_e32 v116, v71
	v_sub_f32_e32 v71, v76, v102
	v_exp_f32_e32 v109, v75
	v_sub_f32_e32 v75, v77, v103
	v_mul_f32_e32 v71, 0x3fb8aa3b, v71
	v_mul_f32_e32 v75, 0x3fb8aa3b, v75
	v_rcp_f32_e32 v68, v60
	v_rcp_f32_e32 v69, v61
	v_exp_f32_e32 v71, v71
	v_exp_f32_e32 v101, v75
	v_sub_f32_e32 v75, v26, v76
	v_mul_f32_e32 v76, 0x3fb8aa3b, v77
	v_exp_f32_e32 v117, v76
	v_sub_f32_e32 v76, v27, v77
	v_mul_f32_e32 v76, 0x3fb8aa3b, v76
	v_lshlrev_b32_e32 v61, 16, v13
	v_lshlrev_b32_e32 v60, 16, v12
	v_exp_f32_e32 v119, v76
	v_lshlrev_b32_e32 v77, 16, v7
	v_lshlrev_b32_e32 v76, 16, v6
	v_pk_mul_f32 v[68:69], v[68:69], v[60:61]
	v_pk_mul_f32 v[60:61], v[78:79], v[60:61]
	v_rcp_f32_e32 v78, v70
	v_rcp_f32_e32 v110, v100
	v_rcp_f32_e32 v79, v71
	v_rcp_f32_e32 v111, v101
	v_pk_mul_f32 v[70:71], v[70:71], v[76:77]
	v_pk_mul_f32 v[100:101], v[100:101], v[120:121]
	v_cvt_pk_bf16_f32 v224, v112, v114
	v_cvt_pk_bf16_f32 v222, v113, v115
	v_cvt_pk_bf16_f32 v102, v70, v100
	v_cvt_pk_bf16_f32 v103, v71, v101
	ds_read_b128 v[104:107], v21 offset:51216
	ds_read_b128 v[40:43], v21 offset:51232
	ds_read_b128 v[28:31], v90
	ds_read_b128 v[20:23], v91
	v_lshlrev_b32_e32 v71, 16, v15
	v_lshlrev_b32_e32 v70, 16, v14
	v_mul_f32_e32 v75, 0x3fb8aa3b, v75
	v_mov_b32_e32 v101, v222
	v_mov_b32_e32 v100, v224
	v_pk_mul_f32 v[114:115], v[78:79], v[70:71]
	s_waitcnt lgkmcnt(3)
; #define LAS __attribute__((address_space(3)))
; __device__ __forceinline__ unsigned pk2(float lo, float hi) { return f2bf(lo) | (f2bf(hi) << 16); }
; __device__ __forceinline__ void phase_gla_pre(const Params& P, LAS unsigned char* lds, bool dry) {
;     ...
;                 oqi[e2] = pk2(vqi[0], vqi[1]); oki[e2] = pk2(vki[0], vki[1]); oqd[e2] = pk2(vqd[0], vqd[1]); oks[e2] = pk2(vks[0], vks[1]);
;             }
;             *(LAS u32x4*)(Lqi + te * QP + 32 * kc) = (u32x4){oqi[0], oqi[1], oqi[2], oqi[3]}; *(LAS u32x4*)(Lqi + te * QP + 32 * kc + 16) = (u32x4){oqi[4], oqi[5], oqi[6], oqi[7]};
;             *(LAS u32x4*)(Lki + te * QP + 32 * kc) = (u32x4){oki[0], oki[1], oki[2], oki[3]}; *(LAS u32x4*)(Lki + te * QP + 32 * kc + 16) = (u32x4){oki[4], oki[5], oki[6], oki[7]};
;             if (!dry) {
;                 bf16_t* p_ = PJ + ((size_t)bh * SEQ + c * 64 + te) * 128 + 16 * kc;
;                 *(u32x4*)(p_ + T_Q) = (u32x4){oqd[0], oqd[1], oqd[2], oqd[3]}; *(u32x4*)(p_ + T_Q + 8) = (u32x4){oqd[4], oqd[5], oqd[6], oqd[7]};
;                 *(u32x4*)(p_ + T_K) = (u32x4){oks[0], oks[1], oks[2], oks[3]}; *(u32x4*)(p_ + T_K + 8) = (u32x4){oks[4], oks[5], oks[6], oks[7]};
;                 if (te == 63) {
; #pragma unroll
;                     for (int i = 0; i < 4; ++i) *(f32x4*)(DEC + (size_t)item * 128 + 16 * kc + 4 * i) = (f32x4){__expf(bl[i][0]), __expf(bl[i][1]), __expf(bl[i][2]), __expf(bl[i][3])};
	v_sub_f32_e32 v78, v44, v104
	v_sub_f32_e32 v105, v45, v105
	v_exp_f32_e32 v75, v75
	v_mul_f32_e32 v78, 0x3fb8aa3b, v78
	v_mul_f32_e32 v105, 0x3fb8aa3b, v105
	v_exp_f32_e32 v104, v78
	v_pk_mul_f32 v[78:79], v[116:117], v[120:121]
	v_exp_f32_e32 v116, v105
	v_mul_f32_e32 v105, 0x3fb8aa3b, v45
	s_waitcnt lgkmcnt(1)
	v_sub_f32_e32 v45, v29, v45
	v_mul_f32_e32 v45, 0x3fb8aa3b, v45
	v_and_b32_e32 v113, 0xffff0000, v15
	v_and_b32_e32 v112, 0xffff0000, v14
	v_exp_f32_e32 v120, v105
	v_sub_f32_e32 v105, v46, v106
	v_exp_f32_e32 v106, v45
	v_mul_f32_e32 v45, 0x3fb8aa3b, v46
	v_pk_mul_f32 v[110:111], v[110:111], v[112:113]
	v_pk_mul_f32 v[70:71], v[74:75], v[70:71]
	v_pk_mul_f32 v[74:75], v[118:119], v[112:113]
	v_exp_f32_e32 v113, v45
	v_sub_f32_e32 v45, v47, v107
	v_mul_f32_e32 v45, 0x3fb8aa3b, v45
	v_exp_f32_e32 v117, v45
	v_sub_f32_e32 v45, v30, v46
	v_mul_f32_e32 v46, 0x3fb8aa3b, v47
	v_exp_f32_e32 v121, v46
	v_sub_f32_e32 v46, v31, v47
	v_pk_mul_f32 v[76:77], v[108:109], v[76:77]
	v_mul_f32_e32 v109, 0x3fb8aa3b, v44
	v_mul_f32_e32 v105, 0x3fb8aa3b, v105
	v_mul_f32_e32 v46, 0x3fb8aa3b, v46
	v_exp_f32_e32 v112, v109
	v_exp_f32_e32 v105, v105
	v_exp_f32_e32 v107, v46
	v_rcp_f32_e32 v118, v116
	v_rcp_f32_e32 v119, v117
	v_sub_f32_e32 v44, v28, v44
	v_lshlrev_b32_e32 v47, 16, v9
	v_lshlrev_b32_e32 v46, 16, v8
	v_rcp_f32_e32 v108, v104
	v_mul_f32_e32 v44, 0x3fb8aa3b, v44
	v_rcp_f32_e32 v109, v105
	v_mul_f32_e32 v45, 0x3fb8aa3b, v45
	v_pk_mul_f32 v[104:105], v[104:105], v[46:47]
	v_pk_mul_f32 v[112:113], v[112:113], v[46:47]
	v_sub_f32_e32 v40, v36, v40
	v_pk_mul_f32 v[46:47], v[106:107], v[126:127]
	v_mul_f32_e32 v107, 0x3fb8aa3b, v36
	s_waitcnt lgkmcnt(0)
	v_sub_f32_e32 v36, v20, v36
	v_exp_f32_e32 v44, v44
	v_exp_f32_e32 v45, v45
	v_mul_f32_e32 v36, 0x3fb8aa3b, v36
	v_pk_mul_f32 v[118:119], v[118:119], v[126:127]
	v_exp_f32_e32 v126, v36
	v_mul_f32_e32 v36, 0x3fb8aa3b, v37
	v_sub_f32_e32 v41, v37, v41
	v_exp_f32_e32 v130, v36
	v_sub_f32_e32 v36, v38, v42
	v_mul_f32_e32 v41, 0x3fb8aa3b, v41
	v_mul_f32_e32 v36, 0x3fb8aa3b, v36
	v_pk_mul_f32 v[108:109], v[108:109], v[124:125]
	v_pk_mul_f32 v[44:45], v[44:45], v[124:125]
	v_exp_f32_e32 v124, v41
	v_exp_f32_e32 v41, v36
	v_sub_f32_e32 v36, v21, v37
	v_mul_f32_e32 v36, 0x3fb8aa3b, v36
	v_and_b32_e32 v123, 0xffff0000, v9
	v_and_b32_e32 v122, 0xffff0000, v8
	v_exp_f32_e32 v42, v36
	v_mul_f32_e32 v36, 0x3fb8aa3b, v38
	v_pk_mul_f32 v[116:117], v[116:117], v[122:123]
	v_pk_mul_f32 v[120:121], v[120:121], v[122:123]
	v_exp_f32_e32 v123, v36
	v_sub_f32_e32 v36, v39, v43
	v_mul_f32_e32 v36, 0x3fb8aa3b, v36
	v_mul_f32_e32 v40, 0x3fb8aa3b, v40
	v_exp_f32_e32 v125, v36
	v_sub_f32_e32 v36, v22, v38
	v_exp_f32_e32 v40, v40
	v_mul_f32_e32 v36, 0x3fb8aa3b, v36
	v_exp_f32_e32 v127, v36
	v_mul_f32_e32 v36, 0x3fb8aa3b, v39
	v_exp_f32_e32 v131, v36
	v_sub_f32_e32 v36, v23, v39
	v_mul_f32_e32 v36, 0x3fb8aa3b, v36
	v_rcp_f32_e32 v128, v124
	v_rcp_f32_e32 v129, v125
	v_exp_f32_e32 v43, v36
	v_pk_mul_f32 v[36:37], v[40:41], v[132:133]
	v_pk_mul_f32 v[38:39], v[124:125], v[134:135]
	v_rcp_f32_e32 v106, v40
	v_exp_f32_e32 v122, v107
	v_rcp_f32_e32 v107, v41
	v_cvt_pk_bf16_f32 v228, v104, v116
	v_cvt_pk_bf16_f32 v227, v105, v117
	v_cvt_pk_bf16_f32 v38, v36, v38
	v_cvt_pk_bf16_f32 v39, v37, v39
	v_mov_b32_e32 v37, v227
	v_mov_b32_e32 v36, v228
	ds_write_b128 v92, v[100:103]
	ds_write_b128 v92, v[36:39] offset:16
	v_cvt_pk_bf16_f32 v36, v68, v72
	v_cvt_pk_bf16_f32 v37, v69, v73
	v_lshlrev_b32_e32 v41, 16, v19
	v_lshlrev_b32_e32 v40, 16, v18
	v_cvt_pk_bf16_f32 v39, v115, v111
	v_cvt_pk_bf16_f32 v38, v114, v110
	v_and_b32_e32 v105, 0xffff0000, v19
	v_and_b32_e32 v104, 0xffff0000, v18
	v_pk_mul_f32 v[106:107], v[106:107], v[40:41]
	ds_write_b128 v92, v[36:39] offset:17408
	v_pk_mul_f32 v[116:117], v[128:129], v[104:105]
	s_nop 0
	v_cvt_pk_bf16_f32 v39, v107, v117
	v_cvt_pk_bf16_f32 v38, v106, v116
	v_cvt_pk_bf16_f32 v37, v109, v119
	v_cvt_pk_bf16_f32 v36, v108, v118
	ds_write_b128 v92, v[36:39] offset:17424
	v_lshl_add_u64 v[36:37], s[74:75], 0, v[48:49]
	v_lshlrev_b64 v[36:37], 8, v[36:37]
	v_lshl_add_u64 v[38:39], v[52:53], 0, s[36:37]
	v_lshl_add_u64 v[68:69], v[38:39], 0, v[36:37]
	v_cvt_pk_bf16_f32 v36, v64, v66
	v_cvt_pk_bf16_f32 v37, v65, v67
	s_brev_b32 s36, 16
	v_cvt_pk_bf16_f32 v39, v77, v79
	v_add_co_u32_e32 v64, vcc, s36, v68
	v_cvt_pk_bf16_f32 v38, v76, v78
	s_nop 0
	v_addc_co_u32_e32 v65, vcc, 0, v69, vcc
	v_pk_mul_f32 v[122:123], v[122:123], v[132:133]
	global_store_dwordx4 v[64:65], v[36:39], off
	v_pk_mul_f32 v[124:125], v[130:131], v[134:135]
	s_nop 0
	v_cvt_pk_bf16_f32 v39, v123, v125
	v_cvt_pk_bf16_f32 v38, v122, v124
	v_cvt_pk_bf16_f32 v37, v113, v121
	v_cvt_pk_bf16_f32 v36, v112, v120
	global_store_dwordx4 v[64:65], v[36:39], off offset:16
	s_nop 1
	s_nop 0
	v_cvt_pk_bf16_f32 v36, v60, v62
	v_cvt_pk_bf16_f32 v37, v61, v63
	v_cvt_pk_bf16_f32 v39, v71, v75
	v_add_co_u32_e32 v60, vcc, s95, v68
	v_pk_mul_f32 v[42:43], v[42:43], v[104:105]
	v_cvt_pk_bf16_f32 v38, v70, v74
	v_addc_co_u32_e32 v61, vcc, 0, v69, vcc
	v_pk_mul_f32 v[40:41], v[126:127], v[40:41]
	global_store_dwordx4 v[60:61], v[36:39], off
	s_nop 1
	v_cvt_pk_bf16_f32 v36, v44, v46
	v_cvt_pk_bf16_f32 v37, v45, v47
	v_cvt_pk_bf16_f32 v38, v40, v42
	v_cvt_pk_bf16_f32 v39, v41, v43
	global_store_dwordx4 v[60:61], v[36:39], off offset:16
	s_and_saveexec_b64 s[36:37], s[12:13]
	s_cbranch_execz .LBB0_494
	v_mul_f32_e32 v32, 0x3fb8aa3b, v32
	v_mul_f32_e32 v33, 0x3fb8aa3b, v33
	v_mul_f32_e32 v34, 0x3fb8aa3b, v34
	v_mul_f32_e32 v35, 0x3fb8aa3b, v35
	v_exp_f32_e32 v32, v32
	v_exp_f32_e32 v33, v33
	v_exp_f32_e32 v34, v34
	v_exp_f32_e32 v35, v35
	v_mul_f32_e32 v24, 0x3fb8aa3b, v24
	v_mul_f32_e32 v25, 0x3fb8aa3b, v25
	v_mul_f32_e32 v26, 0x3fb8aa3b, v26
	v_mul_f32_e32 v27, 0x3fb8aa3b, v27
	s_ashr_i32 s81, s80, 31
	v_exp_f32_e32 v24, v24
	v_exp_f32_e32 v25, v25
	v_exp_f32_e32 v26, v26
	v_exp_f32_e32 v27, v27
	v_mul_f32_e32 v28, 0x3fb8aa3b, v28
	v_mul_f32_e32 v29, 0x3fb8aa3b, v29
	v_mul_f32_e32 v30, 0x3fb8aa3b, v30
	v_mul_f32_e32 v31, 0x3fb8aa3b, v31
	s_lshl_b64 s[42:43], s[80:81], 9
	v_exp_f32_e32 v28, v28
	v_exp_f32_e32 v29, v29
	v_exp_f32_e32 v30, v30
	v_exp_f32_e32 v31, v31
	v_mul_f32_e32 v20, 0x3fb8aa3b, v20
	v_mul_f32_e32 v21, 0x3fb8aa3b, v21
	v_mul_f32_e32 v22, 0x3fb8aa3b, v22
	v_mul_f32_e32 v23, 0x3fb8aa3b, v23
	v_lshl_add_u64 v[36:37], v[54:55], 0, s[42:43]
	v_exp_f32_e32 v20, v20
	v_exp_f32_e32 v21, v21
	v_exp_f32_e32 v22, v22
	v_exp_f32_e32 v23, v23
	global_store_dwordx4 v[36:37], v[32:35], off
	global_store_dwordx4 v[36:37], v[24:27], off offset:16
	global_store_dwordx4 v[36:37], v[28:31], off offset:32
	global_store_dwordx4 v[36:37], v[20:23], off offset:48

; #define LAS __attribute__((address_space(3)))
; __device__ __forceinline__ float bflo(unsigned w) { return __uint_as_float(w << 16); }
; __device__ __forceinline__ float bfhi(unsigned w) { return __uint_as_float(w & 0xffff0000u); }
; __device__ __forceinline__ unsigned pk2(float lo, float hi) { return f2bf(lo) | (f2bf(hi) << 16); }
; template <bool FULL>
; __device__ __forceinline__ void gla_pass(const Params& P, LAS unsigned char* lds, f32x4 (&S)[8][2], int bh, int c0, int L, bool dry) {
;     ...
; #pragma unroll
;             for (int tt = 0; tt < 4; ++tt) {
;                 const int t = 16 * tt + fr;
;                 const f32x4 r0 = *(const LAS f32x4*)(red + t * 8), r1 = *(const LAS f32x4*)(red + t * 8 + 4);
;                 const float rstd = 1.0f / sqrtf(((r0[0] + r0[1]) + (r0[2] + r0[3]) + (r1[0] + r1[1]) + (r1[2] + r1[3])) * (1.0f / 256.0f) + RMS_EPS);
; #pragma unroll
;                 for (int vt = 0; vt < 2; ++vt) {
;                     bf16_t* op = (bf16_t*)P.out + (row0 + t) * 2048 + 1024 + h * 256 + 32 * w + 16 * vt + 4 * g;
;                     const u32x2 z = zb[vt][tt]; const f32x4 ov = o[vt][tt] * rstd * gn[vt];
;                     u32x2 r; r.x = pk2(ov[0] * bflo(z.x), ov[1] * bfhi(z.x)); r.y = pk2(ov[2] * bflo(z.y), ov[3] * bfhi(z.y));
;                     if (!dry) *(u32x2*)op = r;
;                 }
.LBB0_564:
	global_load_dwordx4 v[140:143], v[162:163], off
	global_load_dwordx4 v[136:139], v[162:163], off offset:64
	ds_read_b128 v[212:215], v200
	ds_read_b128 v[216:219], v200 offset:16
	s_waitcnt vmcnt(9)
	v_lshlrev_b32_e32 v221, 16, v185
	v_lshlrev_b32_e32 v220, 16, v184
	v_and_b32_e32 v223, 0xffff0000, v185
	s_waitcnt lgkmcnt(1)
	v_mov_b32_e32 v224, v213
	v_mov_b32_e32 v225, v214
	v_mov_b32_e32 v213, v215
	s_waitcnt lgkmcnt(0)
	v_mov_b32_e32 v214, v218
	v_mov_b32_e32 v215, v216
	v_mov_b32_e32 v216, v219
	v_pk_add_f32 v[212:213], v[224:225], v[212:213]
	v_pk_add_f32 v[214:215], v[214:215], v[216:217]
	v_add_f32_e32 v211, v212, v213
	v_add_f32_e32 v211, v211, v215
	v_add_f32_e32 v211, v214, v211
	v_fmamk_f32 v211, v211, 0x3b800000, v186
	v_mul_f32_e32 v212, 0x4f800000, v211
	v_cmp_gt_f32_e32 vcc, s91, v211
	v_and_b32_e32 v222, 0xffff0000, v184
	s_waitcnt vmcnt(6)
	v_lshlrev_b32_e32 v213, 16, v183
	v_cndmask_b32_e32 v211, v211, v212, vcc
	v_sqrt_f32_e32 v214, v211
	v_lshlrev_b32_e32 v212, 16, v182
	v_and_b32_e32 v183, 0xffff0000, v183
	v_and_b32_e32 v182, 0xffff0000, v182
	v_add_u32_e32 v215, -1, v214
	v_add_u32_e32 v216, 1, v214
	v_fma_f32 v217, -v215, v214, v211
	v_fma_f32 v218, -v216, v214, v211
	v_cmp_ge_f32_e64 s[8:9], 0, v217
	v_lshl_add_u64 v[184:185], v[176:177], 0, v[172:173]
	s_add_u32 s28, s28, 0x8000
	v_cndmask_b32_e64 v214, v214, v215, s[8:9]
	v_cmp_lt_f32_e64 s[8:9], 0, v218
	s_addc_u32 s29, s29, 0
	s_add_u32 s30, s30, 0x4000
	v_cndmask_b32_e64 v214, v214, v216, s[8:9]
	v_mul_f32_e32 v215, 0x37800000, v214
	v_cndmask_b32_e32 v214, v214, v215, vcc
	v_cmp_class_f32_e32 vcc, v211, v187
	s_addc_u32 s31, s31, 0
	s_add_i32 s27, s27, 1
	v_cndmask_b32_e32 v211, v214, v211, vcc
	v_div_scale_f32 v214, s[8:9], v211, v211, 1.0
	v_rcp_f32_e32 v215, v214
	v_div_scale_f32 v216, vcc, 1.0, v211, 1.0
	v_lshl_add_u64 v[174:175], v[174:175], 0, s[22:23]
	v_fma_f32 v217, -v214, v215, 1.0
	v_fmac_f32_e32 v215, v217, v215
	v_mul_f32_e32 v217, v216, v215
	v_fma_f32 v218, -v214, v217, v216
	v_fmac_f32_e32 v217, v218, v215
	v_fma_f32 v214, -v214, v217, v216
	v_div_fmas_f32 v214, v214, v215, v217
	v_div_fixup_f32 v214, v214, v211, 1.0
	v_pk_mul_f32 v[134:135], v[134:135], v[214:215] op_sel_hi:[1,0]
	v_pk_mul_f32 v[132:133], v[132:133], v[214:215] op_sel_hi:[1,0]
	v_pk_mul_f32 v[130:131], v[130:131], v[214:215] op_sel_hi:[1,0]
	v_pk_mul_f32 v[128:129], v[128:129], v[214:215] op_sel_hi:[1,0]
	s_cmp_lg_u32 s28, 0x200000
	v_lshl_add_u64 v[176:177], v[176:177], 0, s[24:25]
	s_waitcnt vmcnt(1)
	v_pk_mul_f32 v[132:133], v[140:141], v[132:133]
	v_pk_mul_f32 v[134:135], v[142:143], v[134:135]
	s_waitcnt vmcnt(0)
	v_pk_mul_f32 v[128:129], v[136:137], v[128:129]
	v_pk_mul_f32 v[130:131], v[138:139], v[130:131]
	v_mov_b32_e32 v214, v132
	v_mov_b32_e32 v215, v134
	v_mov_b32_e32 v134, v133
	v_mov_b32_e32 v132, v128
	v_mov_b32_e32 v133, v130
	v_mov_b32_e32 v130, v129
	v_pk_mul_f32 v[128:129], v[214:215], v[220:221]
	v_pk_mul_f32 v[134:135], v[134:135], v[222:223]
	v_pk_mul_f32 v[132:133], v[132:133], v[212:213]
	v_pk_mul_f32 v[182:183], v[130:131], v[182:183]
	v_cvt_pk_bf16_f32 v128, v128, v134
	v_cvt_pk_bf16_f32 v129, v129, v135
	v_and_b32_sdwa v214, v132, v189 dst_sel:DWORD dst_unused:UNUSED_PAD src0_sel:WORD_1 src1_sel:DWORD
	global_store_dwordx2 v[184:185], v[128:129], off offset:2048
	v_add3_u32 v211, v132, v214, s89
	ds_read_b128 v[128:131], v208
	v_cvt_pk_bf16_f32 v240, v132, v182
	v_cvt_pk_bf16_f32 v239, v133, v183
	ds_read_b128 v[132:135], v208 offset:16
	s_waitcnt lgkmcnt(1)
	v_mov_b32_e32 v212, v129
	v_mov_b32_e32 v213, v130
	v_mov_b32_e32 v129, v131
	v_pk_add_f32 v[128:129], v[212:213], v[128:129]
	s_waitcnt lgkmcnt(0)
	v_mov_b32_e32 v130, v134
	v_mov_b32_e32 v131, v132
	v_mov_b32_e32 v132, v135
	v_pk_add_f32 v[130:131], v[130:131], v[132:133]
	v_add_f32_e32 v128, v128, v129
	v_add_f32_e32 v128, v128, v131
	v_add_f32_e32 v128, v130, v128
	v_fmamk_f32 v128, v128, 0x3b800000, v186
	v_mul_f32_e32 v129, 0x4f800000, v128
	v_cmp_gt_f32_e32 vcc, s91, v128
	v_and_b32_sdwa v215, v182, v189 dst_sel:DWORD dst_unused:UNUSED_PAD src0_sel:WORD_1 src1_sel:DWORD
	s_nop 0
	v_cndmask_b32_e32 v128, v128, v129, vcc
	v_sqrt_f32_e32 v129, v128
	s_nop 0
	v_add_u32_e32 v132, -1, v129
	v_fma_f32 v133, -v132, v129, v128
	v_cmp_ge_f32_e64 s[8:9], 0, v133
	v_add_u32_e32 v133, 1, v129
	s_nop 0
	v_cndmask_b32_e64 v132, v129, v132, s[8:9]
	v_fma_f32 v129, -v133, v129, v128
	v_cmp_lt_f32_e64 s[8:9], 0, v129
	s_nop 1
	v_cndmask_b32_e64 v129, v132, v133, s[8:9]
	v_mul_f32_e32 v132, 0x37800000, v129
	v_cndmask_b32_e32 v129, v129, v132, vcc
	v_cmp_class_f32_e32 vcc, v128, v187
	s_nop 1
	v_cndmask_b32_e32 v132, v129, v128, vcc
	v_div_scale_f32 v133, s[8:9], v132, v132, 1.0
	v_rcp_f32_e32 v134, v133
	v_mov_b32_e32 v129, v239
	v_mov_b32_e32 v128, v240
	global_store_dwordx2 v[184:185], v[128:129], off offset:2080
	v_fma_f32 v128, -v133, v134, 1.0
	v_fmac_f32_e32 v134, v128, v134
	v_div_scale_f32 v128, vcc, 1.0, v132, 1.0
	v_mul_f32_e32 v129, v128, v134
	v_fma_f32 v130, -v133, v129, v128
	v_fmac_f32_e32 v129, v130, v134
	v_fma_f32 v128, -v133, v129, v128
	v_div_fmas_f32 v128, v128, v134, v129
	v_div_fixup_f32 v128, v128, v132, 1.0
	v_pk_mul_f32 v[126:127], v[126:127], v[128:129] op_sel_hi:[1,0]
	v_pk_mul_f32 v[124:125], v[124:125], v[128:129] op_sel_hi:[1,0]
	v_pk_mul_f32 v[126:127], v[142:143], v[126:127]
	v_pk_mul_f32 v[124:125], v[140:141], v[124:125]
	v_lshlrev_b32_e32 v131, 16, v181
	v_lshlrev_b32_e32 v130, 16, v180
	v_mov_b32_e32 v132, v124
	v_mov_b32_e32 v133, v126
	v_pk_mul_f32 v[130:131], v[132:133], v[130:131]
	v_and_b32_e32 v133, 0xffff0000, v181
	v_and_b32_e32 v132, 0xffff0000, v180
	v_mov_b32_e32 v126, v125
	v_pk_mul_f32 v[124:125], v[126:127], v[132:133]
	s_nop 0
	v_and_b32_sdwa v129, v125, v189 dst_sel:DWORD dst_unused:UNUSED_PAD src0_sel:WORD_1 src1_sel:DWORD
	v_cvt_pk_bf16_f32 v124, v130, v124
	v_cvt_pk_bf16_f32 v125, v131, v125
	v_add_co_u32_e32 v130, vcc, s92, v184
	v_pk_mul_f32 v[122:123], v[122:123], v[128:129] op_sel_hi:[1,0]
	v_pk_mul_f32 v[120:121], v[120:121], v[128:129] op_sel_hi:[1,0]
	v_addc_co_u32_e32 v131, vcc, 0, v185, vcc
	v_pk_mul_f32 v[120:121], v[136:137], v[120:121]
	v_pk_mul_f32 v[122:123], v[138:139], v[122:123]
	global_store_dwordx2 v[130:131], v[124:125], off offset:2048
	v_lshlrev_b32_e32 v125, 16, v179
	v_lshlrev_b32_e32 v124, 16, v178
	v_mov_b32_e32 v126, v120
	v_mov_b32_e32 v127, v122
	v_pk_mul_f32 v[124:125], v[126:127], v[124:125]
	v_and_b32_e32 v127, 0xffff0000, v179
	v_and_b32_e32 v126, 0xffff0000, v178
	v_mov_b32_e32 v122, v121
	v_pk_mul_f32 v[128:129], v[122:123], v[126:127]
	ds_read_b128 v[120:123], v209
	v_cvt_pk_bf16_f32 v244, v124, v128
	v_cvt_pk_bf16_f32 v243, v125, v129
	ds_read_b128 v[124:127], v209 offset:16
	s_waitcnt lgkmcnt(1)
; #define LAS __attribute__((address_space(3)))
; __device__ __forceinline__ float bflo(unsigned w) { return __uint_as_float(w << 16); }
; __device__ __forceinline__ float bfhi(unsigned w) { return __uint_as_float(w & 0xffff0000u); }
; __device__ __forceinline__ unsigned pk2(float lo, float hi) { return f2bf(lo) | (f2bf(hi) << 16); }
; template <bool FULL>
; __device__ __forceinline__ void gla_pass(const Params& P, LAS unsigned char* lds, f32x4 (&S)[8][2], int bh, int c0, int L, bool dry) {
;     ...
; #pragma unroll
;             for (int tt = 0; tt < 4; ++tt) {
;                 const int t = 16 * tt + fr;
;                 const f32x4 r0 = *(const LAS f32x4*)(red + t * 8), r1 = *(const LAS f32x4*)(red + t * 8 + 4);
;                 const float rstd = 1.0f / sqrtf(((r0[0] + r0[1]) + (r0[2] + r0[3]) + (r1[0] + r1[1]) + (r1[2] + r1[3])) * (1.0f / 256.0f) + RMS_EPS);
; #pragma unroll
;                 for (int vt = 0; vt < 2; ++vt) {
;                     bf16_t* op = (bf16_t*)P.out + (row0 + t) * 2048 + 1024 + h * 256 + 32 * w + 16 * vt + 4 * g;
;                     const u32x2 z = zb[vt][tt]; const f32x4 ov = o[vt][tt] * rstd * gn[vt];
;                     u32x2 r; r.x = pk2(ov[0] * bflo(z.x), ov[1] * bfhi(z.x)); r.y = pk2(ov[2] * bflo(z.y), ov[3] * bfhi(z.y));
;                     if (!dry) *(u32x2*)op = r;
;                 }
;             }
;         }
;         __syncthreads();
	v_mov_b32_e32 v132, v121
	v_mov_b32_e32 v133, v122
	v_mov_b32_e32 v121, v123
	v_pk_add_f32 v[120:121], v[132:133], v[120:121]
	s_waitcnt lgkmcnt(0)
	v_mov_b32_e32 v122, v126
	v_mov_b32_e32 v123, v124
	v_mov_b32_e32 v124, v127
	v_pk_add_f32 v[122:123], v[122:123], v[124:125]
	v_add_f32_e32 v120, v120, v121
	v_add_f32_e32 v120, v120, v123
	v_add_f32_e32 v120, v122, v120
	v_fmamk_f32 v120, v120, 0x3b800000, v186
	v_mul_f32_e32 v121, 0x4f800000, v120
	v_cmp_gt_f32_e32 vcc, s91, v120
	s_nop 1
	v_cndmask_b32_e32 v120, v120, v121, vcc
	v_sqrt_f32_e32 v121, v120
	s_nop 0
	v_add_u32_e32 v124, -1, v121
	v_fma_f32 v125, -v124, v121, v120
	v_cmp_ge_f32_e64 s[8:9], 0, v125
	v_add_u32_e32 v125, 1, v121
	s_nop 0
	v_cndmask_b32_e64 v124, v121, v124, s[8:9]
	v_fma_f32 v121, -v125, v121, v120
	v_cmp_lt_f32_e64 s[8:9], 0, v121
	s_nop 1
	v_cndmask_b32_e64 v121, v124, v125, s[8:9]
	v_mul_f32_e32 v124, 0x37800000, v121
	v_cndmask_b32_e32 v121, v121, v124, vcc
	v_cmp_class_f32_e32 vcc, v120, v187
	s_nop 1
	v_cndmask_b32_e32 v124, v121, v120, vcc
	v_div_scale_f32 v125, s[8:9], v124, v124, 1.0
	v_rcp_f32_e32 v126, v125
	v_mov_b32_e32 v121, v243
	v_mov_b32_e32 v120, v244
	global_store_dwordx2 v[130:131], v[120:121], off offset:2080
	v_fma_f32 v120, -v125, v126, 1.0
	v_fmac_f32_e32 v126, v120, v126
	v_div_scale_f32 v120, vcc, 1.0, v124, 1.0
	v_mul_f32_e32 v121, v120, v126
	v_fma_f32 v122, -v125, v121, v120
	v_fmac_f32_e32 v121, v122, v126
	v_fma_f32 v120, -v125, v121, v120
	v_div_fmas_f32 v120, v120, v126, v121
	v_div_fixup_f32 v120, v120, v124, 1.0
	v_pk_mul_f32 v[110:111], v[110:111], v[120:121] op_sel_hi:[1,0]
	v_pk_mul_f32 v[108:109], v[108:109], v[120:121] op_sel_hi:[1,0]
	v_pk_mul_f32 v[110:111], v[142:143], v[110:111]
	v_pk_mul_f32 v[108:109], v[140:141], v[108:109]
	v_lshlrev_b32_e32 v123, 16, v151
	v_lshlrev_b32_e32 v122, 16, v150
	v_mov_b32_e32 v124, v108
	v_mov_b32_e32 v125, v110
	v_pk_mul_f32 v[122:123], v[124:125], v[122:123]
	v_and_b32_e32 v125, 0xffff0000, v151
	v_and_b32_e32 v124, 0xffff0000, v150
	v_mov_b32_e32 v110, v109
	v_pk_mul_f32 v[108:109], v[110:111], v[124:125]
	s_nop 0
	v_and_b32_sdwa v121, v109, v189 dst_sel:DWORD dst_unused:UNUSED_PAD src0_sel:WORD_1 src1_sel:DWORD
	v_cvt_pk_bf16_f32 v108, v122, v108
	v_cvt_pk_bf16_f32 v109, v123, v109
	v_add_co_u32_e32 v122, vcc, s93, v184
	v_pk_mul_f32 v[106:107], v[106:107], v[120:121] op_sel_hi:[1,0]
	v_pk_mul_f32 v[104:105], v[104:105], v[120:121] op_sel_hi:[1,0]
	v_addc_co_u32_e32 v123, vcc, 0, v185, vcc
	v_pk_mul_f32 v[104:105], v[136:137], v[104:105]
	v_pk_mul_f32 v[106:107], v[138:139], v[106:107]
	global_store_dwordx2 v[122:123], v[108:109], off offset:2048
	v_lshlrev_b32_e32 v109, 16, v149
	v_lshlrev_b32_e32 v108, 16, v148
	v_mov_b32_e32 v110, v104
	v_mov_b32_e32 v111, v106
	v_pk_mul_f32 v[108:109], v[110:111], v[108:109]
	v_and_b32_e32 v111, 0xffff0000, v149
	v_and_b32_e32 v110, 0xffff0000, v148
	v_mov_b32_e32 v106, v105
	v_pk_mul_f32 v[120:121], v[106:107], v[110:111]
	ds_read_b128 v[104:107], v210
	v_cvt_pk_bf16_f32 v248, v108, v120
	v_cvt_pk_bf16_f32 v247, v109, v121
	ds_read_b128 v[108:111], v210 offset:16
	s_waitcnt lgkmcnt(1)
	v_mov_b32_e32 v124, v105
	v_mov_b32_e32 v125, v106
	v_mov_b32_e32 v105, v107
	v_pk_add_f32 v[104:105], v[124:125], v[104:105]
	s_waitcnt lgkmcnt(0)
	v_mov_b32_e32 v106, v110
	v_mov_b32_e32 v107, v108
	v_mov_b32_e32 v108, v111
	v_pk_add_f32 v[106:107], v[106:107], v[108:109]
	v_add_f32_e32 v104, v104, v105
	v_add_f32_e32 v104, v104, v107
	v_add_f32_e32 v104, v106, v104
	v_fmamk_f32 v104, v104, 0x3b800000, v186
	v_mul_f32_e32 v105, 0x4f800000, v104
	v_cmp_gt_f32_e32 vcc, s91, v104
	s_nop 1
	v_cndmask_b32_e32 v104, v104, v105, vcc
	v_sqrt_f32_e32 v105, v104
	v_lshlrev_b32_e32 v111, 16, v147
	v_add_u32_e32 v108, -1, v105
	v_fma_f32 v109, -v108, v105, v104
	v_cmp_ge_f32_e64 s[8:9], 0, v109
	v_add_u32_e32 v109, 1, v105
	s_nop 0
	v_cndmask_b32_e64 v108, v105, v108, s[8:9]
	v_fma_f32 v105, -v109, v105, v104
	v_cmp_lt_f32_e64 s[8:9], 0, v105
	s_nop 1
	v_cndmask_b32_e64 v105, v108, v109, s[8:9]
	v_mul_f32_e32 v108, 0x37800000, v105
	v_cndmask_b32_e32 v105, v105, v108, vcc
	v_cmp_class_f32_e32 vcc, v104, v187
	s_nop 1
	v_cndmask_b32_e32 v108, v105, v104, vcc
	v_div_scale_f32 v109, s[8:9], v108, v108, 1.0
	v_rcp_f32_e32 v110, v109
	v_mov_b32_e32 v105, v247
	v_mov_b32_e32 v104, v248
	global_store_dwordx2 v[122:123], v[104:105], off offset:2080
	v_fma_f32 v104, -v109, v110, 1.0
	v_fmac_f32_e32 v110, v104, v110
	v_div_scale_f32 v104, vcc, 1.0, v108, 1.0
	v_mul_f32_e32 v105, v104, v110
	v_fma_f32 v106, -v109, v105, v104
	v_fmac_f32_e32 v105, v106, v110
	v_fma_f32 v104, -v109, v105, v104
	v_div_fmas_f32 v104, v104, v110, v105
	v_div_fixup_f32 v104, v104, v108, 1.0
	v_pk_mul_f32 v[106:107], v[118:119], v[104:105] op_sel_hi:[1,0]
	v_pk_mul_f32 v[108:109], v[116:117], v[104:105] op_sel_hi:[1,0]
	v_pk_mul_f32 v[106:107], v[142:143], v[106:107]
	v_pk_mul_f32 v[108:109], v[140:141], v[108:109]
	v_lshlrev_b32_e32 v110, 16, v146
	v_mov_b32_e32 v116, v108
	v_mov_b32_e32 v117, v106
	v_pk_mul_f32 v[110:111], v[116:117], v[110:111]
	v_and_b32_e32 v117, 0xffff0000, v147
	v_and_b32_e32 v116, 0xffff0000, v146
	v_mov_b32_e32 v106, v109
	v_pk_mul_f32 v[106:107], v[106:107], v[116:117]
	s_nop 0
	v_cvt_pk_bf16_f32 v106, v110, v106
	v_and_b32_sdwa v105, v111, v189 dst_sel:DWORD dst_unused:UNUSED_PAD src0_sel:WORD_1 src1_sel:DWORD
	v_cvt_pk_bf16_f32 v107, v111, v107
	v_add3_u32 v105, v111, v105, s89
	v_add_co_u32_e32 v108, vcc, s94, v184
	s_nop 0
	s_nop 0
	v_addc_co_u32_e32 v109, vcc, 0, v185, vcc
	global_store_dwordx2 v[108:109], v[106:107], off offset:2048
	v_pk_mul_f32 v[106:107], v[114:115], v[104:105] op_sel_hi:[1,0]
	v_pk_mul_f32 v[104:105], v[112:113], v[104:105] op_sel_hi:[1,0]
	v_pk_mul_f32 v[106:107], v[138:139], v[106:107]
	v_pk_mul_f32 v[104:105], v[136:137], v[104:105]
	v_lshlrev_b32_e32 v111, 16, v145
	v_lshlrev_b32_e32 v110, 16, v144
	v_mov_b32_e32 v112, v104
	v_mov_b32_e32 v113, v106
	v_pk_mul_f32 v[110:111], v[112:113], v[110:111]
	v_and_b32_e32 v113, 0xffff0000, v145
	v_and_b32_e32 v112, 0xffff0000, v144
	v_mov_b32_e32 v106, v105
	v_pk_mul_f32 v[104:105], v[106:107], v[112:113]
	s_nop 0
	v_cvt_pk_bf16_f32 v104, v110, v104
	v_cvt_pk_bf16_f32 v105, v111, v105
	global_store_dwordx2 v[108:109], v[104:105], off offset:2080
	s_barrier
	s_cbranch_scc0 .LBB0_557

; #define LAS __attribute__((address_space(3)))
; __device__ __forceinline__ float bflo(unsigned w) { return __uint_as_float(w << 16); }
; __device__ __forceinline__ float bfhi(unsigned w) { return __uint_as_float(w & 0xffff0000u); }
; __device__ __forceinline__ unsigned pk2(float lo, float hi) { return f2bf(lo) | (f2bf(hi) << 16); }
; __device__ __forceinline__ void phase_mixer_a(const Params& P, LAS unsigned char* lds, int ustart, int ustride, bool dry) {
;     ...
;             u32x2 pv[8]; float bsv[8];
; #pragma unroll
;             for (int mt = 0; mt < 8; ++mt) { const int t = 16 * mt + (lane & 15);
;                 pv[mt] = *(const u32x2*)(PJ + T_P + (size_t)(r0 + t) * 1024 + h * 128 + 16 * w + 4 * g4); bsv[mt] = P.b_spatial[h * 128 + t]; }
;             f32x4 acc[8];
; #pragma unroll
;             for (int mt = 0; mt < 8; ++mt) acc[mt] = (f32x4){0.f, 0.f, 0.f, 0.f};
; #pragma unroll
;             for (int ks = 0; ks < 4; ++ks) {
;                 const unsigned a0 = (unsigned)((32 * ks + 8 * g4 + q) * VN_P + 32 * w + 8 * p);
;                 const s16x4 lo = __builtin_amdgcn_ds_read_tr16_b64_v4i16((LAS s16x4*)(lds + a0)), hi = __builtin_amdgcn_ds_read_tr16_b64_v4i16((LAS s16x4*)(lds + a0 + 4 * VN_P));
;                 const bf16x8 vf = (bf16x8){lo[0], lo[1], lo[2], lo[3], hi[0], hi[1], hi[2], hi[3]};
; #pragma unroll
;                 for (int mt = 2 * ks; mt < 8; ++mt) {
;                     const bf16x8 wf = *(const LAS bf16x8*)(lds + W_OFF + (16 * mt + (lane & 15)) * W_P + (32 * ks + 8 * g4) * 2);
;                     acc[mt] = __builtin_amdgcn_mfma_f32_16x16x32_bf16(vf, wf, acc[mt], 0, 0, 0);
;                 }
;             }
; #pragma unroll
;             for (int mt = 0; mt < 8; ++mt) {
;                 const int t = 16 * mt + (lane & 15); const float bs = bsv[mt];
;                 u32x2 o; o.x = pk2(bflo(pv[mt].x) * (acc[mt][0] + bs), bfhi(pv[mt].x) * (acc[mt][1] + bs)); o.y = pk2(bflo(pv[mt].y) * (acc[mt][2] + bs), bfhi(pv[mt].y) * (acc[mt][3] + bs));
;                 if (!dry) *(u32x2*)((bf16_t*)P.out + (size_t)(r0 + t) * 2048 + h * 128 + 16 * w + 4 * g4) = o;
;             }
.LBB0_594:
	ds_read_b64_tr_b16 v[16:17], v171
	ds_read_b64_tr_b16 v[18:19], v171 offset:1152
	v_add_u32_e32 v37, v150, v151
	ds_read_b128 v[20:23], v37 offset:36864
	ds_read_b128 v[24:27], v37 offset:41216
	v_lshl_add_u64 v[136:137], v[102:103], 0, s[12:13]
	v_lshl_add_u64 v[212:213], v[68:69], 0, s[6:7]
	s_waitcnt lgkmcnt(1)
	v_mfma_f32_16x16x32_bf16 v[28:31], v[16:19], v[20:23], 0
	ds_read_b128 v[20:23], v37 offset:45568
	global_load_dwordx2 v[192:193], v[136:137], off
	ds_read_b128 v[136:139], v37 offset:49920
	global_load_dword v214, v[212:213], off
	ds_read_b128 v[176:179], v37 offset:54272
	ds_read_b128 v[180:183], v37 offset:58624
	v_lshl_add_u64 v[200:201], v[104:105], 0, s[12:13]
	v_add_u32_e32 v39, v150, v152
	ds_read_b128 v[184:187], v37 offset:62976
	ds_read_b64_tr_b16 v[188:189], v172
	ds_read_b64_tr_b16 v[190:191], v172 offset:1152
	ds_read_b128 v[196:199], v39 offset:62976
	v_add_u32_e32 v37, v153, v151
	global_load_dwordx2 v[216:217], v[200:201], off
	ds_read_b128 v[200:203], v37 offset:45568
	s_waitcnt lgkmcnt(8)
	v_mfma_f32_16x16x32_bf16 v[20:23], v[16:19], v[20:23], 0
	global_load_dword v218, v[212:213], off offset:64
	v_add_u32_e32 v39, v153, v152
	v_lshl_add_u64 v[208:209], v[106:107], 0, s[12:13]
	v_mfma_f32_16x16x32_bf16 v[24:27], v[16:19], v[24:27], 0
	v_lshl_add_u64 v[210:211], v[108:109], 0, s[12:13]
	v_lshl_add_u64 v[220:221], v[110:111], 0, s[12:13]
	v_lshl_add_u64 v[222:223], v[112:113], 0, s[12:13]
	s_waitcnt lgkmcnt(7)
	v_mfma_f32_16x16x32_bf16 v[136:139], v[16:19], v[136:139], 0
	v_lshl_add_u64 v[224:225], v[114:115], 0, s[12:13]
	v_add_u32_e32 v41, v155, v152
	v_lshl_add_u64 v[226:227], v[116:117], 0, s[12:13]
	s_waitcnt lgkmcnt(6)
	v_mfma_f32_16x16x32_bf16 v[176:179], v[16:19], v[176:179], 0
	v_lshl_add_u64 v[134:135], v[134:135], 0, s[10:11]
	v_lshl_add_u64 v[132:133], v[132:133], 0, s[10:11]
	v_lshl_add_u64 v[130:131], v[130:131], 0, s[10:11]
	s_waitcnt lgkmcnt(5)
	v_mfma_f32_16x16x32_bf16 v[180:183], v[16:19], v[180:183], 0
	v_lshl_add_u64 v[128:129], v[128:129], 0, s[10:11]
	s_waitcnt lgkmcnt(4)
	v_mfma_f32_16x16x32_bf16 v[184:187], v[16:19], v[184:187], 0
	s_waitcnt lgkmcnt(1)
	v_mfma_f32_16x16x32_bf16 v[16:19], v[16:19], v[196:199], 0
	ds_read_b128 v[196:199], v37 offset:49920
	s_waitcnt lgkmcnt(1)
	v_mfma_f32_16x16x32_bf16 v[200:203], v[188:191], v[200:203], v[20:23]
	s_nop 2
	ds_read_b128 v[20:23], v37 offset:54272
	s_waitcnt lgkmcnt(1)
	v_mfma_f32_16x16x32_bf16 v[136:139], v[188:191], v[196:199], v[136:139]
	ds_read_b128 v[196:199], v37 offset:58624
	s_waitcnt lgkmcnt(1)
	v_mfma_f32_16x16x32_bf16 v[20:23], v[188:191], v[20:23], v[176:179]
	s_nop 2
	ds_read_b128 v[176:179], v37 offset:62976
	s_waitcnt lgkmcnt(1)
	v_mfma_f32_16x16x32_bf16 v[180:183], v[188:191], v[196:199], v[180:183]
	ds_read_b64_tr_b16 v[196:197], v173
	ds_read_b64_tr_b16 v[198:199], v173 offset:1152
	ds_read_b128 v[204:207], v39 offset:62976
	v_add_u32_e32 v37, v154, v151
	global_load_dwordx2 v[228:229], v[208:209], off
	s_waitcnt lgkmcnt(3)
	v_mfma_f32_16x16x32_bf16 v[176:179], v[188:191], v[176:179], v[184:187]
	global_load_dword v230, v[212:213], off offset:128
	v_add_u32_e32 v39, v154, v152
	s_nop 0
	ds_read_b128 v[184:187], v37 offset:54272
	s_waitcnt lgkmcnt(1)
	v_mfma_f32_16x16x32_bf16 v[16:19], v[188:191], v[204:207], v[16:19]
	ds_read_b128 v[188:191], v37 offset:58624
	s_waitcnt lgkmcnt(1)
	v_mfma_f32_16x16x32_bf16 v[184:187], v[196:199], v[184:187], v[20:23]
	ds_read_b64_tr_b16 v[204:205], v174
	ds_read_b64_tr_b16 v[206:207], v174 offset:1152
	s_nop 0
	ds_read_b128 v[20:23], v37 offset:62976
	v_add_u32_e32 v37, v155, v151
	s_waitcnt lgkmcnt(3)
	v_mfma_f32_16x16x32_bf16 v[180:183], v[196:199], v[188:191], v[180:183]
	ds_read_b128 v[188:191], v39 offset:62976
	global_load_dwordx2 v[232:233], v[210:211], off
	s_nop 0
	global_load_dwordx2 v[220:221], v[220:221], off
	ds_read_b128 v[208:211], v37 offset:62976
	s_waitcnt lgkmcnt(2)
	v_mfma_f32_16x16x32_bf16 v[176:179], v[196:199], v[20:23], v[176:179]
	s_waitcnt lgkmcnt(1)
	v_mfma_f32_16x16x32_bf16 v[16:19], v[196:199], v[188:191], v[16:19]
	global_load_dwordx2 v[196:197], v[222:223], off
	global_load_dwordx2 v[198:199], v[224:225], off
	global_load_dwordx2 v[20:21], v[226:227], off
	ds_read_b128 v[188:191], v41 offset:62976
	s_waitcnt lgkmcnt(1)
	v_mfma_f32_16x16x32_bf16 v[176:179], v[204:207], v[208:211], v[176:179]
	global_load_dword v208, v[212:213], off offset:192
	global_load_dword v210, v[212:213], off offset:256
	global_load_dword v222, v[212:213], off offset:320
	global_load_dword v224, v[212:213], off offset:384
	global_load_dword v22, v[212:213], off offset:448
	s_waitcnt lgkmcnt(0)
	v_mfma_f32_16x16x32_bf16 v[16:19], v[204:207], v[188:191], v[16:19]
	v_mov_b32_e32 v190, v28
	v_mov_b32_e32 v191, v30
	s_waitcnt vmcnt(15)
	v_lshlrev_b32_e32 v189, 16, v193
	v_lshlrev_b32_e32 v188, 16, v192
	s_waitcnt vmcnt(14)
	v_pk_add_f32 v[190:191], v[214:215], v[190:191] op_sel_hi:[0,1]
	v_mov_b32_e32 v30, v29
	v_pk_mul_f32 v[188:189], v[190:191], v[188:189]
	v_and_b32_e32 v191, 0xffff0000, v193
	v_and_b32_e32 v190, 0xffff0000, v192
	v_pk_add_f32 v[28:29], v[214:215], v[30:31] op_sel_hi:[0,1]
	v_pk_mul_f32 v[28:29], v[28:29], v[190:191]
	s_nop 0
	v_cvt_pk_bf16_f32 v29, v189, v29
	v_cvt_pk_bf16_f32 v28, v188, v28
	v_lshl_add_u64 v[30:31], v[118:119], 0, s[12:13]
	global_store_dwordx2 v[30:31], v[28:29], off
	v_mov_b32_e32 v30, v24
	v_mov_b32_e32 v31, v26
	s_waitcnt vmcnt(14)
	v_lshlrev_b32_e32 v29, 16, v217
	v_lshlrev_b32_e32 v28, 16, v216
	s_waitcnt vmcnt(13)
; __device__ __forceinline__ float bflo(unsigned w) { return __uint_as_float(w << 16); }
; __device__ __forceinline__ float bfhi(unsigned w) { return __uint_as_float(w & 0xffff0000u); }
; __device__ __forceinline__ unsigned pk2(float lo, float hi) { return f2bf(lo) | (f2bf(hi) << 16); }
; __device__ __forceinline__ void phase_mixer_a(const Params& P, LAS unsigned char* lds, int ustart, int ustride, bool dry) {
;     ...
; #pragma unroll
;             for (int mt = 0; mt < 8; ++mt) {
;                 const int t = 16 * mt + (lane & 15); const float bs = bsv[mt];
;                 u32x2 o; o.x = pk2(bflo(pv[mt].x) * (acc[mt][0] + bs), bfhi(pv[mt].x) * (acc[mt][1] + bs)); o.y = pk2(bflo(pv[mt].y) * (acc[mt][2] + bs), bfhi(pv[mt].y) * (acc[mt][3] + bs));
;                 if (!dry) *(u32x2*)((bf16_t*)P.out + (size_t)(r0 + t) * 2048 + h * 128 + 16 * w + 4 * g4) = o;
;             }
;             __syncthreads();
	v_pk_add_f32 v[30:31], v[218:219], v[30:31] op_sel_hi:[0,1]
	v_mov_b32_e32 v26, v25
	v_pk_mul_f32 v[28:29], v[30:31], v[28:29]
	v_and_b32_e32 v31, 0xffff0000, v217
	v_and_b32_e32 v30, 0xffff0000, v216
	v_pk_add_f32 v[24:25], v[218:219], v[26:27] op_sel_hi:[0,1]
	v_pk_mul_f32 v[24:25], v[24:25], v[30:31]
	s_nop 0
	v_cvt_pk_bf16_f32 v24, v28, v24
	v_cvt_pk_bf16_f32 v25, v29, v25
	v_lshl_add_u64 v[26:27], v[120:121], 0, s[12:13]
	global_store_dwordx2 v[26:27], v[24:25], off
	v_mov_b32_e32 v26, v200
	v_mov_b32_e32 v27, v202
	s_waitcnt vmcnt(13)
	v_lshlrev_b32_e32 v25, 16, v229
	v_lshlrev_b32_e32 v24, 16, v228
	s_waitcnt vmcnt(12)
	v_pk_add_f32 v[26:27], v[230:231], v[26:27] op_sel_hi:[0,1]
	v_mov_b32_e32 v202, v201
	v_pk_mul_f32 v[24:25], v[26:27], v[24:25]
	v_and_b32_e32 v27, 0xffff0000, v229
	v_and_b32_e32 v26, 0xffff0000, v228
	v_pk_add_f32 v[28:29], v[230:231], v[202:203] op_sel_hi:[0,1]
	v_pk_mul_f32 v[26:27], v[28:29], v[26:27]
	s_nop 0
	v_cvt_pk_bf16_f32 v24, v24, v26
	v_cvt_pk_bf16_f32 v25, v25, v27
	v_lshl_add_u64 v[26:27], v[122:123], 0, s[12:13]
	global_store_dwordx2 v[26:27], v[24:25], off
	v_mov_b32_e32 v26, v136
	v_mov_b32_e32 v27, v138
	s_waitcnt vmcnt(12)
	v_lshlrev_b32_e32 v25, 16, v233
	v_lshlrev_b32_e32 v24, 16, v232
	s_waitcnt vmcnt(7)
	v_pk_add_f32 v[26:27], v[208:209], v[26:27] op_sel_hi:[0,1]
	v_mov_b32_e32 v138, v137
	v_pk_mul_f32 v[24:25], v[26:27], v[24:25]
	v_and_b32_e32 v27, 0xffff0000, v233
	v_and_b32_e32 v26, 0xffff0000, v232
	v_pk_add_f32 v[28:29], v[208:209], v[138:139] op_sel_hi:[0,1]
	v_pk_mul_f32 v[26:27], v[28:29], v[26:27]
	s_nop 0
	v_cvt_pk_bf16_f32 v24, v24, v26
	v_cvt_pk_bf16_f32 v25, v25, v27
	v_lshl_add_u64 v[26:27], v[124:125], 0, s[12:13]
	global_store_dwordx2 v[26:27], v[24:25], off
	v_mov_b32_e32 v26, v184
	v_mov_b32_e32 v27, v186
	v_lshlrev_b32_e32 v25, 16, v221
	v_lshlrev_b32_e32 v24, 16, v220
	s_waitcnt vmcnt(7)
	v_pk_add_f32 v[26:27], v[210:211], v[26:27] op_sel_hi:[0,1]
	v_mov_b32_e32 v186, v185
	v_pk_mul_f32 v[24:25], v[26:27], v[24:25]
	v_and_b32_e32 v27, 0xffff0000, v221
	v_and_b32_e32 v26, 0xffff0000, v220
	v_pk_add_f32 v[28:29], v[210:211], v[186:187] op_sel_hi:[0,1]
	v_pk_mul_f32 v[26:27], v[28:29], v[26:27]
	s_nop 0
	v_cvt_pk_bf16_f32 v24, v24, v26
	v_cvt_pk_bf16_f32 v25, v25, v27
	v_lshl_add_u64 v[26:27], v[126:127], 0, s[12:13]
	global_store_dwordx2 v[26:27], v[24:25], off
	v_mov_b32_e32 v26, v180
	v_mov_b32_e32 v27, v182
	v_lshlrev_b32_e32 v25, 16, v197
	v_lshlrev_b32_e32 v24, 16, v196
	s_waitcnt vmcnt(7)
	v_pk_add_f32 v[26:27], v[222:223], v[26:27] op_sel_hi:[0,1]
	v_mov_b32_e32 v182, v181
	v_pk_mul_f32 v[24:25], v[26:27], v[24:25]
	v_and_b32_e32 v27, 0xffff0000, v197
	v_and_b32_e32 v26, 0xffff0000, v196
	v_pk_add_f32 v[28:29], v[222:223], v[182:183] op_sel_hi:[0,1]
	v_pk_mul_f32 v[26:27], v[28:29], v[26:27]
	s_nop 0
	v_cvt_pk_bf16_f32 v24, v24, v26
	v_cvt_pk_bf16_f32 v25, v25, v27
	v_lshl_add_u64 v[26:27], v[100:101], 0, s[12:13]
	global_store_dwordx2 v[26:27], v[24:25], off
	v_mov_b32_e32 v26, v176
	v_mov_b32_e32 v27, v178
	v_lshlrev_b32_e32 v25, 16, v199
	v_lshlrev_b32_e32 v24, 16, v198
	s_waitcnt vmcnt(7)
	v_pk_add_f32 v[26:27], v[224:225], v[26:27] op_sel_hi:[0,1]
	v_mov_b32_e32 v178, v177
	v_pk_mul_f32 v[24:25], v[26:27], v[24:25]
	v_and_b32_e32 v27, 0xffff0000, v199
	v_and_b32_e32 v26, 0xffff0000, v198
	v_pk_add_f32 v[28:29], v[224:225], v[178:179] op_sel_hi:[0,1]
	v_pk_mul_f32 v[26:27], v[28:29], v[26:27]
	v_and_b32_sdwa v23, v25, v175 dst_sel:DWORD dst_unused:UNUSED_PAD src0_sel:WORD_1 src1_sel:DWORD
	v_cvt_pk_bf16_f32 v24, v24, v26
	v_add3_u32 v23, v25, v23, s15
	v_cvt_pk_bf16_f32 v25, v25, v27
	v_lshl_add_u64 v[26:27], v[98:99], 0, s[12:13]
	global_store_dwordx2 v[26:27], v[24:25], off
	v_mov_b32_e32 v27, v18
	v_mov_b32_e32 v18, v17
	v_lshlrev_b32_e32 v25, 16, v21
	v_lshlrev_b32_e32 v24, 16, v20
	v_mov_b32_e32 v26, v16
	v_and_b32_e32 v21, 0xffff0000, v21
	v_and_b32_e32 v20, 0xffff0000, v20
	s_waitcnt vmcnt(7)
	v_pk_add_f32 v[16:17], v[22:23], v[18:19] op_sel_hi:[0,1]
	v_pk_add_f32 v[26:27], v[22:23], v[26:27] op_sel_hi:[0,1]
	v_pk_mul_f32 v[16:17], v[16:17], v[20:21]
	v_pk_mul_f32 v[24:25], v[26:27], v[24:25]
	s_nop 0
	v_cvt_pk_bf16_f32 v17, v25, v17
	v_cvt_pk_bf16_f32 v16, v24, v16
	v_lshl_add_u64 v[18:19], v[96:97], 0, s[12:13]
	s_add_u32 s12, s12, 0x100
	s_addc_u32 s13, s13, 0
	s_add_u32 s6, s6, 0x200
	s_addc_u32 s7, s7, 0
	s_cmpk_eq_i32 s12, 0x800
	global_store_dwordx2 v[18:19], v[16:17], off
	s_barrier
	s_cbranch_scc1 .LBB0_582
; #define LAS __attribute__((address_space(3)))
; __device__ __forceinline__ float bflo(unsigned w) { return __uint_as_float(w << 16); }
; __device__ __forceinline__ float bfhi(unsigned w) { return __uint_as_float(w & 0xffff0000u); }
; __device__ __forceinline__ unsigned pk2(float lo, float hi) { return f2bf(lo) | (f2bf(hi) << 16); }
; __device__ __forceinline__ void phase_mixer_a(const Params& P, LAS unsigned char* lds, int ustart, int ustride, bool dry) {
;     ...
; #pragma unroll
;             for (int i = 0; i < 4; ++i) {
;                 const int item = tid + 512 * i, c8 = item & 15, s = item >> 4;
;                 const u32x4 gv = pgv[i];
;                 const float mean = stats[2 * s], rstd = stats[2 * s + 1];
;                 const f32x4 g0 = *(const f32x4*)(P.ln_v_g + h * 128 + c8 * 8), g1 = *(const f32x4*)(P.ln_v_g + h * 128 + c8 * 8 + 4);
;                 const f32x4 b0 = *(const f32x4*)(P.ln_v_b + h * 128 + c8 * 8), b1 = *(const f32x4*)(P.ln_v_b + h * 128 + c8 * 8 + 4);
;                 u32x4 o;
;                 o.x = pk2((bflo(gv.x) - mean) * rstd * g0[0] + b0[0], (bfhi(gv.x) - mean) * rstd * g0[1] + b0[1]);
;                 o.y = pk2((bflo(gv.y) - mean) * rstd * g0[2] + b0[2], (bfhi(gv.y) - mean) * rstd * g0[3] + b0[3]);
;                 o.z = pk2((bflo(gv.z) - mean) * rstd * g1[0] + b1[0], (bfhi(gv.z) - mean) * rstd * g1[1] + b1[1]);
;                 o.w = pk2((bflo(gv.w) - mean) * rstd * g1[2] + b1[2], (bfhi(gv.w) - mean) * rstd * g1[3] + b1[3]);
;                 *(LAS u32x4*)(lds + s * VN_P + c8 * 16) = o;
;                 *(LAS u32x4*)(lds + W_OFF + s * W_P + c8 * 16) = *(const u32x4*)(WsT + h * 16384 + item * 8);
;             }
;             __syncthreads();
;             if (h + 1 < 8) {
; #pragma unroll
;                 for (int i = 0; i < 4; ++i) { const int item = tid + 512 * i, c8 = item & 15, s = item >> 4;
;                     pgv[i] = *(const u32x4*)(PJ + T_GV + (size_t)(r0 + s) * 1024 + (h + 1) * 128 + c8 * 8); }
;             }
.LBB0_595:
	v_lshl_add_u64 v[16:17], v[72:73], 0, s[6:7]
	global_load_dwordx4 v[24:27], v[16:17], off offset:-16
	v_lshl_add_u64 v[20:21], v[76:77], 0, s[6:7]
	global_load_dwordx4 v[28:31], v[20:21], off offset:-16
	s_nop 0
	global_load_dwordx4 v[16:19], v[16:17], off
	s_nop 0
	global_load_dwordx4 v[20:23], v[20:21], off
	s_nop 0
	global_load_dwordx4 v[176:179], v[134:135], off
	global_load_dwordx4 v[180:183], v[132:133], off
	ds_read_b64 v[136:137], v159
	s_waitcnt vmcnt(9)
	v_lshlrev_b32_e32 v139, 16, v1
	v_lshlrev_b32_e32 v138, 16, v0
	v_and_b32_e32 v185, 0xffff0000, v1
	v_and_b32_e32 v184, 0xffff0000, v0
	v_lshlrev_b32_e32 v187, 16, v3
	v_lshlrev_b32_e32 v186, 16, v2
	v_and_b32_e32 v189, 0xffff0000, v3
	v_and_b32_e32 v188, 0xffff0000, v2
	s_waitcnt lgkmcnt(0)
	v_pk_add_f32 v[138:139], v[138:139], v[136:137] op_sel_hi:[1,0] neg_lo:[0,1] neg_hi:[0,1]
	v_pk_add_f32 v[184:185], v[184:185], v[136:137] op_sel_hi:[1,0] neg_lo:[0,1] neg_hi:[0,1]
	v_pk_add_f32 v[186:187], v[186:187], v[136:137] op_sel_hi:[1,0] neg_lo:[0,1] neg_hi:[0,1]
	v_pk_add_f32 v[188:189], v[188:189], v[136:137] op_sel_hi:[1,0] neg_lo:[0,1] neg_hi:[0,1]
	v_pk_mul_f32 v[198:199], v[136:137], v[138:139] op_sel:[1,0]
	v_pk_mul_f32 v[184:185], v[136:137], v[184:185] op_sel:[1,0]
	v_pk_mul_f32 v[186:187], v[136:137], v[186:187] op_sel:[1,0]
	v_pk_mul_f32 v[188:189], v[136:137], v[188:189] op_sel:[1,0]
	s_waitcnt vmcnt(8)
	v_lshlrev_b32_e32 v191, 16, v5
	v_lshlrev_b32_e32 v190, 16, v4
	v_and_b32_e32 v193, 0xffff0000, v5
	v_and_b32_e32 v192, 0xffff0000, v4
	v_lshlrev_b32_e32 v197, 16, v7
	v_lshlrev_b32_e32 v196, 16, v6
	s_cmpk_lg_i32 s12, 0x700
	s_waitcnt vmcnt(4)
	v_mov_b32_e32 v138, v28
	v_mov_b32_e32 v136, v24
	v_mov_b32_e32 v137, v26
	v_mov_b32_e32 v139, v30
	v_mov_b32_e32 v26, v25
	v_mov_b32_e32 v30, v29
	s_waitcnt vmcnt(3)
	v_mov_b32_e32 v24, v16
	v_mov_b32_e32 v25, v18
	s_waitcnt vmcnt(2)
	v_mov_b32_e32 v28, v20
	v_mov_b32_e32 v29, v22
	v_mov_b32_e32 v18, v17
	v_mov_b32_e32 v22, v21
	v_pk_fma_f32 v[16:17], v[198:199], v[136:137], v[138:139]
	v_pk_fma_f32 v[20:21], v[184:185], v[26:27], v[30:31]
	v_pk_fma_f32 v[184:185], v[186:187], v[24:25], v[28:29]
	v_pk_fma_f32 v[186:187], v[188:189], v[18:19], v[22:23]
	v_cvt_pk_bf16_f32 v251, v16, v20
	v_cvt_pk_bf16_f32 v250, v17, v21
	v_cvt_pk_bf16_f32 v187, v185, v187
	v_cvt_pk_bf16_f32 v186, v184, v186
	v_mov_b32_e32 v185, v250
	v_mov_b32_e32 v184, v251
	ds_write_b128 v160, v[184:187]
	s_waitcnt vmcnt(1)
	ds_write_b128 v161, v[176:179] offset:36864
	ds_read_b64 v[16:17], v162
	global_load_dwordx4 v[176:179], v[130:131], off
	v_and_b32_e32 v21, 0xffff0000, v7
	v_and_b32_e32 v20, 0xffff0000, v6
	s_waitcnt lgkmcnt(0)
	v_pk_add_f32 v[184:185], v[190:191], v[16:17] op_sel_hi:[1,0] neg_lo:[0,1] neg_hi:[0,1]
	v_pk_add_f32 v[186:187], v[192:193], v[16:17] op_sel_hi:[1,0] neg_lo:[0,1] neg_hi:[0,1]
	v_pk_add_f32 v[188:189], v[196:197], v[16:17] op_sel_hi:[1,0] neg_lo:[0,1] neg_hi:[0,1]
	v_pk_add_f32 v[20:21], v[20:21], v[16:17] op_sel_hi:[1,0] neg_lo:[0,1] neg_hi:[0,1]
	v_pk_mul_f32 v[184:185], v[16:17], v[184:185] op_sel:[1,0]
	v_pk_mul_f32 v[186:187], v[16:17], v[186:187] op_sel:[1,0]
	v_pk_mul_f32 v[188:189], v[16:17], v[188:189] op_sel:[1,0]
	v_pk_mul_f32 v[16:17], v[16:17], v[20:21] op_sel:[1,0]
	v_pk_fma_f32 v[20:21], v[136:137], v[184:185], v[138:139]
	v_pk_fma_f32 v[16:17], v[18:19], v[16:17], v[22:23]
	v_pk_fma_f32 v[184:185], v[26:27], v[186:187], v[30:31]
	v_pk_fma_f32 v[186:187], v[24:25], v[188:189], v[28:29]
	s_nop 0
	v_cvt_pk_bf16_f32 v186, v186, v16
	v_cvt_pk_bf16_f32 v187, v187, v17
	v_cvt_pk_bf16_f32 v185, v21, v185
	v_cvt_pk_bf16_f32 v184, v20, v184
	ds_write_b128 v163, v[184:187]
	s_waitcnt vmcnt(1)
	ds_write_b128 v164, v[180:183] offset:36864
	ds_read_b64 v[16:17], v165
	v_and_b32_e32 v181, 0xffff0000, v9
	v_and_b32_e32 v180, 0xffff0000, v8
	v_lshlrev_b32_e32 v21, 16, v9
	v_lshlrev_b32_e32 v20, 16, v8
	s_waitcnt lgkmcnt(0)
	v_pk_add_f32 v[180:181], v[180:181], v[16:17] op_sel_hi:[1,0] neg_lo:[0,1] neg_hi:[0,1]
	v_and_b32_e32 v189, 0xffff0000, v11
	v_pk_mul_f32 v[180:181], v[16:17], v[180:181] op_sel:[1,0]
	v_and_b32_e32 v188, 0xffff0000, v10
	v_pk_fma_f32 v[184:185], v[26:27], v[180:181], v[30:31]
	v_lshlrev_b32_e32 v181, 16, v11
	v_lshlrev_b32_e32 v180, 16, v10
	v_pk_add_f32 v[180:181], v[180:181], v[16:17] op_sel_hi:[1,0] neg_lo:[0,1] neg_hi:[0,1]
	v_pk_add_f32 v[20:21], v[20:21], v[16:17] op_sel_hi:[1,0] neg_lo:[0,1] neg_hi:[0,1]
	v_pk_mul_f32 v[180:181], v[16:17], v[180:181] op_sel:[1,0]
	v_pk_add_f32 v[188:189], v[188:189], v[16:17] op_sel_hi:[1,0] neg_lo:[0,1] neg_hi:[0,1]
	v_pk_fma_f32 v[186:187], v[24:25], v[180:181], v[28:29]
	global_load_dwordx4 v[180:183], v[128:129], off
	v_pk_mul_f32 v[20:21], v[16:17], v[20:21] op_sel:[1,0]
	v_pk_mul_f32 v[16:17], v[16:17], v[188:189] op_sel:[1,0]
	v_pk_fma_f32 v[20:21], v[136:137], v[20:21], v[138:139]
	v_pk_fma_f32 v[16:17], v[18:19], v[16:17], v[22:23]
	s_nop 0
	v_cvt_pk_bf16_f32 v186, v186, v16
	v_cvt_pk_bf16_f32 v187, v187, v17
	v_cvt_pk_bf16_f32 v185, v21, v185
	v_cvt_pk_bf16_f32 v184, v20, v184
	ds_write_b128 v166, v[184:187]
	s_waitcnt vmcnt(1)
	ds_write_b128 v167, v[176:179] offset:36864
	ds_read_b64 v[16:17], v168
	v_lshlrev_b32_e32 v21, 16, v13
	v_lshlrev_b32_e32 v20, 16, v12
	s_waitcnt lgkmcnt(0)
	v_pk_add_f32 v[20:21], v[20:21], v[16:17] op_sel_hi:[1,0] neg_lo:[0,1] neg_hi:[0,1]
	s_nop 0
	v_pk_mul_f32 v[20:21], v[16:17], v[20:21] op_sel:[1,0]
	s_nop 0
	v_pk_fma_f32 v[20:21], v[136:137], v[20:21], v[138:139]
	v_and_b32_e32 v137, 0xffff0000, v13
	v_and_b32_e32 v136, 0xffff0000, v12
	v_pk_add_f32 v[136:137], v[136:137], v[16:17] op_sel_hi:[1,0] neg_lo:[0,1] neg_hi:[0,1]
	s_nop 0
	v_pk_mul_f32 v[136:137], v[16:17], v[136:137] op_sel:[1,0]
	s_nop 0
	v_pk_fma_f32 v[26:27], v[26:27], v[136:137], v[30:31]
	v_lshlrev_b32_e32 v31, 16, v15
	v_lshlrev_b32_e32 v30, 16, v14
	v_pk_add_f32 v[30:31], v[30:31], v[16:17] op_sel_hi:[1,0] neg_lo:[0,1] neg_hi:[0,1]
	s_nop 0
	v_pk_mul_f32 v[30:31], v[16:17], v[30:31] op_sel:[1,0]
	s_nop 0
	v_pk_fma_f32 v[24:25], v[24:25], v[30:31], v[28:29]
	v_and_b32_e32 v29, 0xffff0000, v15
	v_and_b32_e32 v28, 0xffff0000, v14
	v_pk_add_f32 v[28:29], v[28:29], v[16:17] op_sel_hi:[1,0] neg_lo:[0,1] neg_hi:[0,1]
	s_nop 0
	v_pk_mul_f32 v[16:17], v[16:17], v[28:29] op_sel:[1,0]
	s_nop 0
	v_pk_fma_f32 v[16:17], v[18:19], v[16:17], v[22:23]
	s_nop 0
	v_cvt_pk_bf16_f32 v18, v24, v16
	v_cvt_pk_bf16_f32 v19, v25, v17
	v_cvt_pk_bf16_f32 v16, v20, v26
	v_cvt_pk_bf16_f32 v17, v21, v27
	ds_write_b128 v169, v[16:19]
	s_waitcnt vmcnt(0)
	ds_write_b128 v170, v[180:183] offset:36864
	s_waitcnt lgkmcnt(0)
	s_barrier
	s_cbranch_scc0 .LBB0_594
	v_lshl_add_u64 v[12:13], v[94:95], 0, s[12:13]
	v_lshl_add_u64 v[8:9], v[92:93], 0, s[12:13]
	v_lshl_add_u64 v[4:5], v[90:91], 0, s[12:13]
	v_lshl_add_u64 v[0:1], v[88:89], 0, s[12:13]
	global_load_dwordx4 v[0:3], v[0:1], off
	s_nop 0
	global_load_dwordx4 v[4:7], v[4:5], off
	s_nop 0
	global_load_dwordx4 v[8:11], v[8:9], off
	s_nop 0
	global_load_dwordx4 v[12:15], v[12:13], off
	s_branch .LBB0_594

; #define LAS __attribute__((address_space(3)))
; __device__ __forceinline__ void tr_item(const float* W, int ldw, int src_col0, int k0, bf16_t* dst, int ldd, int dst_row0, int dst_col0, LAS float* scr, int lane) {
; #pragma unroll 8
;     for (int i = 0; i < 32; ++i) { const int kk = 2 * i + (lane >> 5); scr[kk * 33 + (lane & 31)] = W[(size_t)(k0 + kk) * ldw + src_col0 + (lane & 31)]; }
.LBB0_603:
	s_lshl_b32 s19, s16, 1
	s_lshl_b32 s20, s17, 1
	v_or_b32_e32 v4, s19, v1
	v_or_b32_e32 v19, s20, v0
	s_add_i32 s21, s19, 4
	s_add_i32 s22, s20, 4
	s_add_i32 s23, s19, 8
	s_add_i32 s24, s20, 8
	s_add_i32 s25, s19, 12
	s_add_i32 s26, s20, 12
	s_add_i32 s27, s19, 16
	s_add_i32 s28, s20, 16
	s_add_i32 s29, s19, 20
	s_add_i32 s30, s20, 20
	s_add_i32 s31, s19, 24
	s_add_i32 s34, s20, 24
	s_add_i32 s19, s19, 28
	s_add_i32 s20, s20, 28
	v_add_u32_e32 v32, v19, v18
	v_or_b32_e32 v29, s21, v1
	v_or_b32_e32 v62, s22, v0
	v_or_b32_e32 v63, s23, v1
	v_or_b32_e32 v64, s24, v0
	v_or_b32_e32 v65, s25, v1
	v_or_b32_e32 v66, s26, v0
	v_or_b32_e32 v67, s27, v1
	v_or_b32_e32 v68, s28, v0
	v_or_b32_e32 v69, s29, v1
	v_or_b32_e32 v70, s30, v0
	v_or_b32_e32 v71, s31, v1
	v_or_b32_e32 v72, s34, v0
	v_or_b32_e32 v73, s19, v1
	v_or_b32_e32 v74, s20, v0
	v_add_u32_e32 v30, v4, v3
	v_ashrrev_i32_e32 v33, 31, v32
	v_add_u32_e32 v34, v29, v3
	v_add_u32_e32 v36, v62, v18
	v_add_u32_e32 v38, v63, v3
	v_add_u32_e32 v40, v64, v18
	v_add_u32_e32 v42, v65, v3
	v_add_u32_e32 v44, v66, v18
	v_add_u32_e32 v46, v67, v3
	v_add_u32_e32 v48, v68, v18
	v_add_u32_e32 v50, v69, v3
	v_add_u32_e32 v52, v70, v18
	v_add_u32_e32 v54, v71, v3
	v_add_u32_e32 v56, v72, v18
	v_add_u32_e32 v58, v73, v3
	v_add_u32_e32 v60, v74, v18
	v_ashrrev_i32_e32 v31, 31, v30
	v_lshlrev_b64 v[32:33], 12, v[32:33]
	v_ashrrev_i32_e32 v37, 31, v36
	v_ashrrev_i32_e32 v35, 31, v34
	v_ashrrev_i32_e32 v41, 31, v40
	v_ashrrev_i32_e32 v39, 31, v38
	v_ashrrev_i32_e32 v45, 31, v44
	v_ashrrev_i32_e32 v43, 31, v42
	v_ashrrev_i32_e32 v49, 31, v48
	v_ashrrev_i32_e32 v47, 31, v46
	v_ashrrev_i32_e32 v53, 31, v52
	v_ashrrev_i32_e32 v51, 31, v50
	v_ashrrev_i32_e32 v57, 31, v56
	v_ashrrev_i32_e32 v55, 31, v54
	v_ashrrev_i32_e32 v61, 31, v60
	v_ashrrev_i32_e32 v59, 31, v58
	v_lshlrev_b64 v[30:31], 12, v[30:31]
	v_lshl_add_u64 v[32:33], v[20:21], 0, v[32:33]
	v_lshlrev_b64 v[34:35], 12, v[34:35]
	v_lshlrev_b64 v[36:37], 12, v[36:37]
	v_lshlrev_b64 v[38:39], 12, v[38:39]
	v_lshlrev_b64 v[40:41], 12, v[40:41]
	v_lshlrev_b64 v[42:43], 12, v[42:43]
	v_lshlrev_b64 v[44:45], 12, v[44:45]
	v_lshlrev_b64 v[46:47], 12, v[46:47]
	v_lshlrev_b64 v[48:49], 12, v[48:49]
	v_lshlrev_b64 v[50:51], 12, v[50:51]
	v_lshlrev_b64 v[52:53], 12, v[52:53]
	v_lshlrev_b64 v[54:55], 12, v[54:55]
	v_lshlrev_b64 v[56:57], 12, v[56:57]
	v_lshlrev_b64 v[58:59], 12, v[58:59]
	v_lshlrev_b64 v[60:61], 12, v[60:61]
	v_lshl_add_u64 v[30:31], v[20:21], 0, v[30:31]
	v_lshl_add_u64 v[36:37], v[20:21], 0, v[36:37]
	v_lshl_add_u64 v[34:35], v[20:21], 0, v[34:35]
	v_lshl_add_u64 v[40:41], v[20:21], 0, v[40:41]
	v_lshl_add_u64 v[38:39], v[20:21], 0, v[38:39]
	v_lshl_add_u64 v[44:45], v[20:21], 0, v[44:45]
	v_lshl_add_u64 v[42:43], v[20:21], 0, v[42:43]
	v_lshl_add_u64 v[48:49], v[20:21], 0, v[48:49]
	v_lshl_add_u64 v[46:47], v[20:21], 0, v[46:47]
	v_lshl_add_u64 v[52:53], v[20:21], 0, v[52:53]
	v_lshl_add_u64 v[50:51], v[20:21], 0, v[50:51]
	v_lshl_add_u64 v[56:57], v[20:21], 0, v[56:57]
	v_lshl_add_u64 v[54:55], v[20:21], 0, v[54:55]
	v_lshl_add_u64 v[60:61], v[20:21], 0, v[60:61]
	v_lshl_add_u64 v[58:59], v[20:21], 0, v[58:59]
	global_load_dword v75, v[32:33], off
	global_load_dword v76, v[30:31], off
	global_load_dword v77, v[36:37], off
	global_load_dword v78, v[34:35], off
	global_load_dword v79, v[40:41], off
	global_load_dword v80, v[38:39], off
	global_load_dword v81, v[44:45], off
	global_load_dword v82, v[42:43], off
	global_load_dword v83, v[48:49], off
	global_load_dword v84, v[46:47], off
	global_load_dword v85, v[52:53], off
	global_load_dword v86, v[50:51], off
	global_load_dword v87, v[56:57], off
	global_load_dword v88, v[54:55], off
	global_load_dword v89, v[60:61], off
	global_load_dword v90, v[58:59], off
	s_add_i32 s17, s17, 16
	s_add_i32 s16, s16, 16
	s_add_i32 s18, s18, -16
	v_mad_u64_u32 v[30:31], s[20:21], v19, s1, v[2:3]
	s_cmp_lg_u32 s18, 0
	v_mad_u64_u32 v[32:33], s[20:21], v4, s1, v[2:3]
	v_mad_u64_u32 v[34:35], s[20:21], v62, s1, v[2:3]
	v_mad_u64_u32 v[36:37], s[20:21], v29, s1, v[2:3]
	v_mad_u64_u32 v[38:39], s[20:21], v64, s1, v[2:3]
	v_mad_u64_u32 v[40:41], s[20:21], v63, s1, v[2:3]
	v_mad_u64_u32 v[42:43], s[20:21], v66, s1, v[2:3]
	v_mad_u64_u32 v[44:45], s[20:21], v65, s1, v[2:3]
	v_mad_u64_u32 v[46:47], s[20:21], v68, s1, v[2:3]
	v_mad_u64_u32 v[48:49], s[20:21], v67, s1, v[2:3]
	v_mad_u64_u32 v[50:51], s[20:21], v70, s1, v[2:3]
	v_mad_u64_u32 v[52:53], s[20:21], v69, s1, v[2:3]
	v_mad_u64_u32 v[54:55], s[20:21], v72, s1, v[2:3]
	v_mad_u64_u32 v[56:57], s[20:21], v71, s1, v[2:3]
	v_mad_u64_u32 v[58:59], s[20:21], v74, s1, v[2:3]
	v_mad_u64_u32 v[60:61], s[20:21], v73, s1, v[2:3]
	s_waitcnt vmcnt(15)
	ds_write_b32 v30, v75
	s_waitcnt vmcnt(14)
	ds_write_b32 v32, v76
	s_waitcnt vmcnt(13)
	ds_write_b32 v34, v77
	s_waitcnt vmcnt(12)
	ds_write_b32 v36, v78
	s_waitcnt vmcnt(11)
	ds_write_b32 v38, v79
	s_waitcnt vmcnt(10)
	ds_write_b32 v40, v80
	s_waitcnt vmcnt(9)
	ds_write_b32 v42, v81
	s_waitcnt vmcnt(8)
	ds_write_b32 v44, v82
	s_waitcnt vmcnt(7)
	ds_write_b32 v46, v83
	s_waitcnt vmcnt(6)
	ds_write_b32 v48, v84
	s_waitcnt vmcnt(5)
	ds_write_b32 v50, v85
	s_waitcnt vmcnt(4)
	ds_write_b32 v52, v86
	s_waitcnt vmcnt(3)
	ds_write_b32 v54, v87
	s_waitcnt vmcnt(2)
	ds_write_b32 v56, v88
	s_waitcnt vmcnt(1)
	ds_write_b32 v58, v89
	s_waitcnt vmcnt(0)
	ds_write_b32 v60, v90
	s_cbranch_scc1 .LBB0_603
; #define LAS __attribute__((address_space(3)))
; __device__ __forceinline__ unsigned pk2(float lo, float hi) { return f2bf(lo) | (f2bf(hi) << 16); }
; __device__ __forceinline__ void tr_item(const float* W, int ldw, int src_col0, int k0, bf16_t* dst, int ldd, int dst_row0, int dst_col0, LAS float* scr, int lane) {
;     ...
;     asm volatile("s_waitcnt lgkmcnt(0)" ::: "memory");
;     const int c = lane & 7;
; #pragma unroll
;     for (int j = 0; j < 4; ++j) { const int n = (lane >> 3) + 8 * j; const LAS float* s = scr + (8 * c) * 33 + n;
;         u32x4 o; o.x = pk2(s[0 * 33], s[1 * 33]); o.y = pk2(s[2 * 33], s[3 * 33]); o.z = pk2(s[4 * 33], s[5 * 33]); o.w = pk2(s[6 * 33], s[7 * 33]);
;         *(u32x4*)(dst + (size_t)(dst_row0 + n) * ldd + dst_col0 + k0 + 8 * c) = o; }
;     asm volatile("s_waitcnt lgkmcnt(0)" ::: "memory");
	s_waitcnt lgkmcnt(0)
	ds_read2_b32 v[30:31], v24 offset1:8
	ds_read2_b32 v[34:35], v24 offset0:33 offset1:41
	ds_read2_b32 v[36:37], v24 offset0:66 offset1:74
	ds_read2_b32 v[38:39], v24 offset0:99 offset1:107
	ds_read2_b32 v[40:41], v24 offset0:132 offset1:140
	v_mov_b32_e32 v19, v5
	s_waitcnt lgkmcnt(4)
	s_waitcnt lgkmcnt(3)
	ds_read2_b32 v[42:43], v24 offset0:165 offset1:173
	v_lshl_add_u64 v[32:33], v[18:19], 1, v[6:7]
	v_cvt_pk_bf16_f32 v18, v30, v34
	s_waitcnt lgkmcnt(3)
	s_waitcnt lgkmcnt(2)
	ds_read2_b32 v[44:45], v24 offset0:198 offset1:206
	ds_read2_b32 v[46:47], v24 offset0:231 offset1:239
	v_cvt_pk_bf16_f32 v19, v36, v38
	s_waitcnt lgkmcnt(3)
	s_waitcnt lgkmcnt(2)
	v_cvt_pk_bf16_f32 v20, v40, v42
	s_waitcnt lgkmcnt(1)
	s_waitcnt lgkmcnt(0)
	v_cvt_pk_bf16_f32 v21, v44, v46
	v_or_b32_e32 v3, v28, v23
	v_lshlrev_b32_e32 v4, 11, v3
	v_lshl_add_u64 v[48:49], v[32:33], 0, v[4:5]
	global_store_dwordx4 v[48:49], v[18:21], off
	s_nop 1
	v_cvt_pk_bf16_f32 v18, v31, v35
	ds_read2_b32 v[30:31], v24 offset0:16 offset1:24
	s_nop 0
	v_cvt_pk_bf16_f32 v19, v37, v39
	v_cvt_pk_bf16_f32 v20, v41, v43
	v_cvt_pk_bf16_f32 v21, v45, v47
	v_or_b32_e32 v3, v28, v25
	v_lshlrev_b32_e32 v4, 11, v3
	v_lshl_add_u64 v[34:35], v[32:33], 0, v[4:5]
	global_store_dwordx4 v[34:35], v[18:21], off
	ds_read2_b32 v[34:35], v24 offset0:49 offset1:57
	ds_read2_b32 v[36:37], v24 offset0:82 offset1:90
	ds_read2_b32 v[38:39], v24 offset0:115 offset1:123
	s_waitcnt lgkmcnt(3)
	s_waitcnt lgkmcnt(2)
	ds_read2_b32 v[40:41], v24 offset0:148 offset1:156
	ds_read2_b32 v[42:43], v24 offset0:181 offset1:189
	v_cvt_pk_bf16_f32 v18, v30, v34
	s_waitcnt lgkmcnt(3)
	s_waitcnt lgkmcnt(2)
	ds_read2_b32 v[44:45], v24 offset0:214 offset1:222
	ds_read2_b32 v[46:47], v24 offset0:247 offset1:255
	v_cvt_pk_bf16_f32 v19, v36, v38
	s_waitcnt lgkmcnt(3)
	s_waitcnt lgkmcnt(2)
	v_cvt_pk_bf16_f32 v20, v40, v42
	s_waitcnt lgkmcnt(1)
	s_waitcnt lgkmcnt(0)
	v_cvt_pk_bf16_f32 v21, v44, v46
	v_or_b32_e32 v3, v28, v26
	v_lshlrev_b32_e32 v4, 11, v3
	v_lshl_add_u64 v[48:49], v[32:33], 0, v[4:5]
	global_store_dwordx4 v[48:49], v[18:21], off
	s_nop 1
	v_cvt_pk_bf16_f32 v18, v31, v35
	v_cvt_pk_bf16_f32 v19, v37, v39
	v_cvt_pk_bf16_f32 v20, v41, v43
	v_cvt_pk_bf16_f32 v21, v45, v47
	v_or_b32_e32 v3, v28, v27
	v_lshlrev_b32_e32 v4, 11, v3
	v_lshl_add_u64 v[28:29], v[32:33], 0, v[4:5]
	global_store_dwordx4 v[28:29], v[18:21], off
	s_waitcnt lgkmcnt(0)

; #define LAS __attribute__((address_space(3)))
; __device__ __forceinline__ void tr_item(const float* W, int ldw, int src_col0, int k0, bf16_t* dst, int ldd, int dst_row0, int dst_col0, LAS float* scr, int lane) {
; #pragma unroll 8
;     for (int i = 0; i < 32; ++i) { const int kk = 2 * i + (lane >> 5); scr[kk * 33 + (lane & 31)] = W[(size_t)(k0 + kk) * ldw + src_col0 + (lane & 31)]; }
.LBB0_607:
	s_lshl_b32 s19, s16, 1
	s_lshl_b32 s20, s17, 1
	v_or_b32_e32 v4, s19, v1
	v_or_b32_e32 v19, s20, v0
	s_add_i32 s21, s19, 4
	s_add_i32 s22, s20, 4
	s_add_i32 s23, s19, 8
	s_add_i32 s24, s20, 8
	s_add_i32 s25, s19, 12
	s_add_i32 s26, s20, 12
	s_add_i32 s27, s19, 16
	s_add_i32 s28, s20, 16
	s_add_i32 s29, s19, 20
	s_add_i32 s30, s20, 20
	s_add_i32 s31, s19, 24
	s_add_i32 s34, s20, 24
	s_add_i32 s19, s19, 28
	s_add_i32 s20, s20, 28
	v_add_u32_e32 v32, v19, v18
	v_or_b32_e32 v29, s21, v1
	v_or_b32_e32 v62, s22, v0
	v_or_b32_e32 v63, s23, v1
	v_or_b32_e32 v64, s24, v0
	v_or_b32_e32 v65, s25, v1
	v_or_b32_e32 v66, s26, v0
	v_or_b32_e32 v67, s27, v1
	v_or_b32_e32 v68, s28, v0
	v_or_b32_e32 v69, s29, v1
	v_or_b32_e32 v70, s30, v0
	v_or_b32_e32 v71, s31, v1
	v_or_b32_e32 v72, s34, v0
	v_or_b32_e32 v73, s19, v1
	v_or_b32_e32 v74, s20, v0
	v_add_u32_e32 v30, v4, v3
	v_ashrrev_i32_e32 v33, 31, v32
	v_add_u32_e32 v34, v29, v3
	v_add_u32_e32 v36, v62, v18
	v_add_u32_e32 v38, v63, v3
	v_add_u32_e32 v40, v64, v18
	v_add_u32_e32 v42, v65, v3
	v_add_u32_e32 v44, v66, v18
	v_add_u32_e32 v46, v67, v3
	v_add_u32_e32 v48, v68, v18
	v_add_u32_e32 v50, v69, v3
	v_add_u32_e32 v52, v70, v18
	v_add_u32_e32 v54, v71, v3
	v_add_u32_e32 v56, v72, v18
	v_add_u32_e32 v58, v73, v3
	v_add_u32_e32 v60, v74, v18
	v_ashrrev_i32_e32 v31, 31, v30
	v_lshlrev_b64 v[32:33], 12, v[32:33]
	v_ashrrev_i32_e32 v37, 31, v36
	v_ashrrev_i32_e32 v35, 31, v34
	v_ashrrev_i32_e32 v41, 31, v40
	v_ashrrev_i32_e32 v39, 31, v38
	v_ashrrev_i32_e32 v45, 31, v44
	v_ashrrev_i32_e32 v43, 31, v42
	v_ashrrev_i32_e32 v49, 31, v48
	v_ashrrev_i32_e32 v47, 31, v46
	v_ashrrev_i32_e32 v53, 31, v52
	v_ashrrev_i32_e32 v51, 31, v50
	v_ashrrev_i32_e32 v57, 31, v56
	v_ashrrev_i32_e32 v55, 31, v54
	v_ashrrev_i32_e32 v61, 31, v60
	v_ashrrev_i32_e32 v59, 31, v58
	v_lshlrev_b64 v[30:31], 12, v[30:31]
	v_lshl_add_u64 v[32:33], v[20:21], 0, v[32:33]
	v_lshlrev_b64 v[34:35], 12, v[34:35]
	v_lshlrev_b64 v[36:37], 12, v[36:37]
	v_lshlrev_b64 v[38:39], 12, v[38:39]
	v_lshlrev_b64 v[40:41], 12, v[40:41]
	v_lshlrev_b64 v[42:43], 12, v[42:43]
	v_lshlrev_b64 v[44:45], 12, v[44:45]
	v_lshlrev_b64 v[46:47], 12, v[46:47]
	v_lshlrev_b64 v[48:49], 12, v[48:49]
	v_lshlrev_b64 v[50:51], 12, v[50:51]
	v_lshlrev_b64 v[52:53], 12, v[52:53]
	v_lshlrev_b64 v[54:55], 12, v[54:55]
	v_lshlrev_b64 v[56:57], 12, v[56:57]
	v_lshlrev_b64 v[58:59], 12, v[58:59]
	v_lshlrev_b64 v[60:61], 12, v[60:61]
	v_lshl_add_u64 v[30:31], v[20:21], 0, v[30:31]
	v_lshl_add_u64 v[36:37], v[20:21], 0, v[36:37]
	v_lshl_add_u64 v[34:35], v[20:21], 0, v[34:35]
	v_lshl_add_u64 v[40:41], v[20:21], 0, v[40:41]
	v_lshl_add_u64 v[38:39], v[20:21], 0, v[38:39]
	v_lshl_add_u64 v[44:45], v[20:21], 0, v[44:45]
	v_lshl_add_u64 v[42:43], v[20:21], 0, v[42:43]
	v_lshl_add_u64 v[48:49], v[20:21], 0, v[48:49]
	v_lshl_add_u64 v[46:47], v[20:21], 0, v[46:47]
	v_lshl_add_u64 v[52:53], v[20:21], 0, v[52:53]
	v_lshl_add_u64 v[50:51], v[20:21], 0, v[50:51]
	v_lshl_add_u64 v[56:57], v[20:21], 0, v[56:57]
	v_lshl_add_u64 v[54:55], v[20:21], 0, v[54:55]
	v_lshl_add_u64 v[60:61], v[20:21], 0, v[60:61]
	v_lshl_add_u64 v[58:59], v[20:21], 0, v[58:59]
	global_load_dword v75, v[32:33], off
	global_load_dword v76, v[30:31], off
	global_load_dword v77, v[36:37], off
	global_load_dword v78, v[34:35], off
	global_load_dword v79, v[40:41], off
	global_load_dword v80, v[38:39], off
	global_load_dword v81, v[44:45], off
	global_load_dword v82, v[42:43], off
	global_load_dword v83, v[48:49], off
	global_load_dword v84, v[46:47], off
	global_load_dword v85, v[52:53], off
	global_load_dword v86, v[50:51], off
	global_load_dword v87, v[56:57], off
	global_load_dword v88, v[54:55], off
	global_load_dword v89, v[60:61], off
	global_load_dword v90, v[58:59], off
	s_add_i32 s17, s17, 16
	s_add_i32 s16, s16, 16
	s_add_i32 s18, s18, -16
	v_mad_u64_u32 v[30:31], s[20:21], v19, s1, v[2:3]
	s_cmp_lg_u32 s18, 0
	v_mad_u64_u32 v[32:33], s[20:21], v4, s1, v[2:3]
	v_mad_u64_u32 v[34:35], s[20:21], v62, s1, v[2:3]
	v_mad_u64_u32 v[36:37], s[20:21], v29, s1, v[2:3]
	v_mad_u64_u32 v[38:39], s[20:21], v64, s1, v[2:3]
	v_mad_u64_u32 v[40:41], s[20:21], v63, s1, v[2:3]
	v_mad_u64_u32 v[42:43], s[20:21], v66, s1, v[2:3]
	v_mad_u64_u32 v[44:45], s[20:21], v65, s1, v[2:3]
	v_mad_u64_u32 v[46:47], s[20:21], v68, s1, v[2:3]
	v_mad_u64_u32 v[48:49], s[20:21], v67, s1, v[2:3]
	v_mad_u64_u32 v[50:51], s[20:21], v70, s1, v[2:3]
	v_mad_u64_u32 v[52:53], s[20:21], v69, s1, v[2:3]
	v_mad_u64_u32 v[54:55], s[20:21], v72, s1, v[2:3]
	v_mad_u64_u32 v[56:57], s[20:21], v71, s1, v[2:3]
	v_mad_u64_u32 v[58:59], s[20:21], v74, s1, v[2:3]
	v_mad_u64_u32 v[60:61], s[20:21], v73, s1, v[2:3]
	s_waitcnt vmcnt(15)
	ds_write_b32 v30, v75
	s_waitcnt vmcnt(14)
	ds_write_b32 v32, v76
	s_waitcnt vmcnt(13)
	ds_write_b32 v34, v77
	s_waitcnt vmcnt(12)
	ds_write_b32 v36, v78
	s_waitcnt vmcnt(11)
	ds_write_b32 v38, v79
	s_waitcnt vmcnt(10)
	ds_write_b32 v40, v80
	s_waitcnt vmcnt(9)
	ds_write_b32 v42, v81
	s_waitcnt vmcnt(8)
	ds_write_b32 v44, v82
	s_waitcnt vmcnt(7)
	ds_write_b32 v46, v83
	s_waitcnt vmcnt(6)
	ds_write_b32 v48, v84
	s_waitcnt vmcnt(5)
	ds_write_b32 v50, v85
	s_waitcnt vmcnt(4)
	ds_write_b32 v52, v86
	s_waitcnt vmcnt(3)
	ds_write_b32 v54, v87
	s_waitcnt vmcnt(2)
	ds_write_b32 v56, v88
	s_waitcnt vmcnt(1)
	ds_write_b32 v58, v89
	s_waitcnt vmcnt(0)
	ds_write_b32 v60, v90
	s_cbranch_scc1 .LBB0_607
; #define LAS __attribute__((address_space(3)))
; __device__ __forceinline__ unsigned pk2(float lo, float hi) { return f2bf(lo) | (f2bf(hi) << 16); }
; __device__ __forceinline__ void tr_item(const float* W, int ldw, int src_col0, int k0, bf16_t* dst, int ldd, int dst_row0, int dst_col0, LAS float* scr, int lane) {
;     ...
;     asm volatile("s_waitcnt lgkmcnt(0)" ::: "memory");
;     const int c = lane & 7;
; #pragma unroll
;     for (int j = 0; j < 4; ++j) { const int n = (lane >> 3) + 8 * j; const LAS float* s = scr + (8 * c) * 33 + n;
;         u32x4 o; o.x = pk2(s[0 * 33], s[1 * 33]); o.y = pk2(s[2 * 33], s[3 * 33]); o.z = pk2(s[4 * 33], s[5 * 33]); o.w = pk2(s[6 * 33], s[7 * 33]);
;         *(u32x4*)(dst + (size_t)(dst_row0 + n) * ldd + dst_col0 + k0 + 8 * c) = o; }
;     asm volatile("s_waitcnt lgkmcnt(0)" ::: "memory");
	s_waitcnt lgkmcnt(0)
	ds_read2_b32 v[30:31], v24 offset1:8
	ds_read2_b32 v[34:35], v24 offset0:33 offset1:41
	ds_read2_b32 v[36:37], v24 offset0:66 offset1:74
	ds_read2_b32 v[38:39], v24 offset0:99 offset1:107
	ds_read2_b32 v[40:41], v24 offset0:132 offset1:140
	v_mov_b32_e32 v19, v5
	s_waitcnt lgkmcnt(4)
	s_waitcnt lgkmcnt(3)
	ds_read2_b32 v[42:43], v24 offset0:165 offset1:173
	v_lshl_add_u64 v[32:33], v[18:19], 1, v[8:9]
	v_cvt_pk_bf16_f32 v18, v30, v34
	s_waitcnt lgkmcnt(3)
	s_waitcnt lgkmcnt(2)
	ds_read2_b32 v[44:45], v24 offset0:198 offset1:206
	ds_read2_b32 v[46:47], v24 offset0:231 offset1:239
	v_cvt_pk_bf16_f32 v19, v36, v38
	s_waitcnt lgkmcnt(3)
	s_waitcnt lgkmcnt(2)
	v_cvt_pk_bf16_f32 v20, v40, v42
	s_waitcnt lgkmcnt(1)
	s_waitcnt lgkmcnt(0)
	v_cvt_pk_bf16_f32 v21, v44, v46
	v_or_b32_e32 v3, v28, v23
	v_lshlrev_b32_e32 v4, 12, v3
	v_lshl_add_u64 v[48:49], v[32:33], 0, v[4:5]
	global_store_dwordx4 v[48:49], v[18:21], off
	s_nop 1
	v_cvt_pk_bf16_f32 v18, v31, v35
	ds_read2_b32 v[30:31], v24 offset0:16 offset1:24
	s_nop 0
	v_cvt_pk_bf16_f32 v19, v37, v39
	v_cvt_pk_bf16_f32 v20, v41, v43
	v_cvt_pk_bf16_f32 v21, v45, v47
	v_or_b32_e32 v3, v28, v25
	v_lshlrev_b32_e32 v4, 12, v3
	v_lshl_add_u64 v[34:35], v[32:33], 0, v[4:5]
	global_store_dwordx4 v[34:35], v[18:21], off
	ds_read2_b32 v[34:35], v24 offset0:49 offset1:57
	ds_read2_b32 v[36:37], v24 offset0:82 offset1:90
	ds_read2_b32 v[38:39], v24 offset0:115 offset1:123
	s_waitcnt lgkmcnt(3)
	s_waitcnt lgkmcnt(2)
	ds_read2_b32 v[40:41], v24 offset0:148 offset1:156
	ds_read2_b32 v[42:43], v24 offset0:181 offset1:189
	v_cvt_pk_bf16_f32 v18, v30, v34
	s_waitcnt lgkmcnt(3)
	s_waitcnt lgkmcnt(2)
	ds_read2_b32 v[44:45], v24 offset0:214 offset1:222
	ds_read2_b32 v[46:47], v24 offset0:247 offset1:255
	v_cvt_pk_bf16_f32 v19, v36, v38
	s_waitcnt lgkmcnt(3)
	s_waitcnt lgkmcnt(2)
	v_cvt_pk_bf16_f32 v20, v40, v42
	s_waitcnt lgkmcnt(1)
	s_waitcnt lgkmcnt(0)
	v_cvt_pk_bf16_f32 v21, v44, v46
	v_or_b32_e32 v3, v28, v26
	v_lshlrev_b32_e32 v4, 12, v3
	v_lshl_add_u64 v[48:49], v[32:33], 0, v[4:5]
	global_store_dwordx4 v[48:49], v[18:21], off
	s_nop 1
	v_cvt_pk_bf16_f32 v18, v31, v35
	v_cvt_pk_bf16_f32 v19, v37, v39
	v_cvt_pk_bf16_f32 v20, v41, v43
	v_cvt_pk_bf16_f32 v21, v45, v47
	v_or_b32_e32 v3, v28, v27
	v_lshlrev_b32_e32 v4, 12, v3
	v_lshl_add_u64 v[28:29], v[32:33], 0, v[4:5]
	global_store_dwordx4 v[28:29], v[18:21], off
	s_waitcnt lgkmcnt(0)

; #define LAS __attribute__((address_space(3)))
; __device__ __forceinline__ void tr_item(const float* W, int ldw, int src_col0, int k0, bf16_t* dst, int ldd, int dst_row0, int dst_col0, LAS float* scr, int lane) {
; #pragma unroll 8
;     for (int i = 0; i < 32; ++i) { const int kk = 2 * i + (lane >> 5); scr[kk * 33 + (lane & 31)] = W[(size_t)(k0 + kk) * ldw + src_col0 + (lane & 31)]; }
.LBB0_612:
	s_lshl_b32 s17, s10, 1
	s_lshl_b32 s18, s11, 1
	v_or_b32_e32 v4, s17, v1
	v_or_b32_e32 v19, s18, v0
	s_add_i32 s19, s17, 4
	s_add_i32 s20, s18, 4
	s_add_i32 s21, s17, 8
	s_add_i32 s22, s18, 8
	s_add_i32 s23, s17, 12
	s_add_i32 s24, s18, 12
	s_add_i32 s25, s17, 16
	s_add_i32 s26, s18, 16
	s_add_i32 s27, s17, 20
	s_add_i32 s28, s18, 20
	s_add_i32 s29, s17, 24
	s_add_i32 s30, s18, 24
	s_add_i32 s17, s17, 28
	s_add_i32 s18, s18, 28
	v_add_u32_e32 v32, v19, v18
	v_or_b32_e32 v29, s19, v1
	v_or_b32_e32 v62, s20, v0
	v_or_b32_e32 v63, s21, v1
	v_or_b32_e32 v64, s22, v0
	v_or_b32_e32 v65, s23, v1
	v_or_b32_e32 v66, s24, v0
	v_or_b32_e32 v67, s25, v1
	v_or_b32_e32 v68, s26, v0
	v_or_b32_e32 v69, s27, v1
	v_or_b32_e32 v70, s28, v0
	v_or_b32_e32 v71, s29, v1
	v_or_b32_e32 v72, s30, v0
	v_or_b32_e32 v73, s17, v1
	v_or_b32_e32 v74, s18, v0
	v_add_u32_e32 v30, v4, v3
	v_ashrrev_i32_e32 v33, 31, v32
	v_add_u32_e32 v34, v29, v3
	v_add_u32_e32 v36, v62, v18
	v_add_u32_e32 v38, v63, v3
	v_add_u32_e32 v40, v64, v18
	v_add_u32_e32 v42, v65, v3
	v_add_u32_e32 v44, v66, v18
	v_add_u32_e32 v46, v67, v3
	v_add_u32_e32 v48, v68, v18
	v_add_u32_e32 v50, v69, v3
	v_add_u32_e32 v52, v70, v18
	v_add_u32_e32 v54, v71, v3
	v_add_u32_e32 v56, v72, v18
	v_add_u32_e32 v58, v73, v3
	v_add_u32_e32 v60, v74, v18
	v_ashrrev_i32_e32 v31, 31, v30
	v_lshlrev_b64 v[32:33], 12, v[32:33]
	v_ashrrev_i32_e32 v37, 31, v36
	v_ashrrev_i32_e32 v35, 31, v34
	v_ashrrev_i32_e32 v41, 31, v40
	v_ashrrev_i32_e32 v39, 31, v38
	v_ashrrev_i32_e32 v45, 31, v44
	v_ashrrev_i32_e32 v43, 31, v42
	v_ashrrev_i32_e32 v49, 31, v48
	v_ashrrev_i32_e32 v47, 31, v46
	v_ashrrev_i32_e32 v53, 31, v52
	v_ashrrev_i32_e32 v51, 31, v50
	v_ashrrev_i32_e32 v57, 31, v56
	v_ashrrev_i32_e32 v55, 31, v54
	v_ashrrev_i32_e32 v61, 31, v60
	v_ashrrev_i32_e32 v59, 31, v58
	v_lshlrev_b64 v[30:31], 12, v[30:31]
	v_lshl_add_u64 v[32:33], v[20:21], 0, v[32:33]
	v_lshlrev_b64 v[34:35], 12, v[34:35]
	v_lshlrev_b64 v[36:37], 12, v[36:37]
	v_lshlrev_b64 v[38:39], 12, v[38:39]
	v_lshlrev_b64 v[40:41], 12, v[40:41]
	v_lshlrev_b64 v[42:43], 12, v[42:43]
	v_lshlrev_b64 v[44:45], 12, v[44:45]
	v_lshlrev_b64 v[46:47], 12, v[46:47]
	v_lshlrev_b64 v[48:49], 12, v[48:49]
	v_lshlrev_b64 v[50:51], 12, v[50:51]
	v_lshlrev_b64 v[52:53], 12, v[52:53]
	v_lshlrev_b64 v[54:55], 12, v[54:55]
	v_lshlrev_b64 v[56:57], 12, v[56:57]
	v_lshlrev_b64 v[58:59], 12, v[58:59]
	v_lshlrev_b64 v[60:61], 12, v[60:61]
	v_lshl_add_u64 v[30:31], v[20:21], 0, v[30:31]
	v_lshl_add_u64 v[36:37], v[20:21], 0, v[36:37]
	v_lshl_add_u64 v[34:35], v[20:21], 0, v[34:35]
	v_lshl_add_u64 v[40:41], v[20:21], 0, v[40:41]
	v_lshl_add_u64 v[38:39], v[20:21], 0, v[38:39]
	v_lshl_add_u64 v[44:45], v[20:21], 0, v[44:45]
	v_lshl_add_u64 v[42:43], v[20:21], 0, v[42:43]
	v_lshl_add_u64 v[48:49], v[20:21], 0, v[48:49]
	v_lshl_add_u64 v[46:47], v[20:21], 0, v[46:47]
	v_lshl_add_u64 v[52:53], v[20:21], 0, v[52:53]
	v_lshl_add_u64 v[50:51], v[20:21], 0, v[50:51]
	v_lshl_add_u64 v[56:57], v[20:21], 0, v[56:57]
	v_lshl_add_u64 v[54:55], v[20:21], 0, v[54:55]
	v_lshl_add_u64 v[60:61], v[20:21], 0, v[60:61]
	v_lshl_add_u64 v[58:59], v[20:21], 0, v[58:59]
	global_load_dword v75, v[32:33], off
	global_load_dword v76, v[30:31], off
	global_load_dword v77, v[36:37], off
	global_load_dword v78, v[34:35], off
	global_load_dword v79, v[40:41], off
	global_load_dword v80, v[38:39], off
	global_load_dword v81, v[44:45], off
	global_load_dword v82, v[42:43], off
	global_load_dword v83, v[48:49], off
	global_load_dword v84, v[46:47], off
	global_load_dword v85, v[52:53], off
	global_load_dword v86, v[50:51], off
	global_load_dword v87, v[56:57], off
	global_load_dword v88, v[54:55], off
	global_load_dword v89, v[60:61], off
	global_load_dword v90, v[58:59], off
	s_add_i32 s11, s11, 16
	s_add_i32 s10, s10, 16
	s_add_i32 s16, s16, -16
	v_mad_u64_u32 v[30:31], s[18:19], v19, s1, v[2:3]
	s_cmp_lg_u32 s16, 0
	v_mad_u64_u32 v[32:33], s[18:19], v4, s1, v[2:3]
	v_mad_u64_u32 v[34:35], s[18:19], v62, s1, v[2:3]
	v_mad_u64_u32 v[36:37], s[18:19], v29, s1, v[2:3]
	v_mad_u64_u32 v[38:39], s[18:19], v64, s1, v[2:3]
	v_mad_u64_u32 v[40:41], s[18:19], v63, s1, v[2:3]
	v_mad_u64_u32 v[42:43], s[18:19], v66, s1, v[2:3]
	v_mad_u64_u32 v[44:45], s[18:19], v65, s1, v[2:3]
	v_mad_u64_u32 v[46:47], s[18:19], v68, s1, v[2:3]
	v_mad_u64_u32 v[48:49], s[18:19], v67, s1, v[2:3]
	v_mad_u64_u32 v[50:51], s[18:19], v70, s1, v[2:3]
	v_mad_u64_u32 v[52:53], s[18:19], v69, s1, v[2:3]
	v_mad_u64_u32 v[54:55], s[18:19], v72, s1, v[2:3]
	v_mad_u64_u32 v[56:57], s[18:19], v71, s1, v[2:3]
	v_mad_u64_u32 v[58:59], s[18:19], v74, s1, v[2:3]
	v_mad_u64_u32 v[60:61], s[18:19], v73, s1, v[2:3]
	s_waitcnt vmcnt(15)
	ds_write_b32 v30, v75
	s_waitcnt vmcnt(14)
	ds_write_b32 v32, v76
	s_waitcnt vmcnt(13)
	ds_write_b32 v34, v77
	s_waitcnt vmcnt(12)
	ds_write_b32 v36, v78
	s_waitcnt vmcnt(11)
	ds_write_b32 v38, v79
	s_waitcnt vmcnt(10)
	ds_write_b32 v40, v80
	s_waitcnt vmcnt(9)
	ds_write_b32 v42, v81
	s_waitcnt vmcnt(8)
	ds_write_b32 v44, v82
	s_waitcnt vmcnt(7)
	ds_write_b32 v46, v83
	s_waitcnt vmcnt(6)
	ds_write_b32 v48, v84
	s_waitcnt vmcnt(5)
	ds_write_b32 v50, v85
	s_waitcnt vmcnt(4)
	ds_write_b32 v52, v86
	s_waitcnt vmcnt(3)
	ds_write_b32 v54, v87
	s_waitcnt vmcnt(2)
	ds_write_b32 v56, v88
	s_waitcnt vmcnt(1)
	ds_write_b32 v58, v89
	s_waitcnt vmcnt(0)
	ds_write_b32 v60, v90
	s_cbranch_scc1 .LBB0_612
; #define LAS __attribute__((address_space(3)))
; __device__ __forceinline__ unsigned pk2(float lo, float hi) { return f2bf(lo) | (f2bf(hi) << 16); }
; __device__ __forceinline__ void tr_item(const float* W, int ldw, int src_col0, int k0, bf16_t* dst, int ldd, int dst_row0, int dst_col0, LAS float* scr, int lane) {
;     ...
;     asm volatile("s_waitcnt lgkmcnt(0)" ::: "memory");
;     const int c = lane & 7;
; #pragma unroll
;     for (int j = 0; j < 4; ++j) { const int n = (lane >> 3) + 8 * j; const LAS float* s = scr + (8 * c) * 33 + n;
;         u32x4 o; o.x = pk2(s[0 * 33], s[1 * 33]); o.y = pk2(s[2 * 33], s[3 * 33]); o.z = pk2(s[4 * 33], s[5 * 33]); o.w = pk2(s[6 * 33], s[7 * 33]);
;         *(u32x4*)(dst + (size_t)(dst_row0 + n) * ldd + dst_col0 + k0 + 8 * c) = o; }
;     asm volatile("s_waitcnt lgkmcnt(0)" ::: "memory");
	s_waitcnt lgkmcnt(0)
	ds_read2_b32 v[30:31], v24 offset1:8
	ds_read2_b32 v[34:35], v24 offset0:33 offset1:41
	ds_read2_b32 v[36:37], v24 offset0:66 offset1:74
	ds_read2_b32 v[38:39], v24 offset0:99 offset1:107
	ds_read2_b32 v[40:41], v24 offset0:132 offset1:140
	v_ashrrev_i32_e32 v19, 31, v18
	s_waitcnt lgkmcnt(4)
	s_waitcnt lgkmcnt(3)
	ds_read2_b32 v[42:43], v24 offset0:165 offset1:173
	v_lshl_add_u64 v[32:33], v[18:19], 1, v[10:11]
	v_cvt_pk_bf16_f32 v18, v30, v34
	s_waitcnt lgkmcnt(3)
	s_waitcnt lgkmcnt(2)
	ds_read2_b32 v[44:45], v24 offset0:198 offset1:206
	ds_read2_b32 v[46:47], v24 offset0:231 offset1:239
	v_cvt_pk_bf16_f32 v19, v36, v38
	s_waitcnt lgkmcnt(3)
	s_waitcnt lgkmcnt(2)
	v_cvt_pk_bf16_f32 v20, v40, v42
	s_waitcnt lgkmcnt(1)
	s_waitcnt lgkmcnt(0)
	v_cvt_pk_bf16_f32 v21, v44, v46
	v_or_b32_e32 v3, v28, v23
	v_lshlrev_b32_e32 v4, 12, v3
	v_lshl_add_u64 v[48:49], v[32:33], 0, v[4:5]
	global_store_dwordx4 v[48:49], v[18:21], off
	s_nop 1
	v_cvt_pk_bf16_f32 v18, v31, v35
	ds_read2_b32 v[30:31], v24 offset0:16 offset1:24
	s_nop 0
	v_cvt_pk_bf16_f32 v19, v37, v39
	v_cvt_pk_bf16_f32 v20, v41, v43
	v_cvt_pk_bf16_f32 v21, v45, v47
	v_or_b32_e32 v3, v28, v25
	v_lshlrev_b32_e32 v4, 12, v3
	v_lshl_add_u64 v[34:35], v[32:33], 0, v[4:5]
	global_store_dwordx4 v[34:35], v[18:21], off
	ds_read2_b32 v[34:35], v24 offset0:49 offset1:57
	ds_read2_b32 v[36:37], v24 offset0:82 offset1:90
	ds_read2_b32 v[38:39], v24 offset0:115 offset1:123
	s_waitcnt lgkmcnt(3)
	s_waitcnt lgkmcnt(2)
	ds_read2_b32 v[40:41], v24 offset0:148 offset1:156
	ds_read2_b32 v[42:43], v24 offset0:181 offset1:189
	v_cvt_pk_bf16_f32 v18, v30, v34
	s_waitcnt lgkmcnt(3)
	s_waitcnt lgkmcnt(2)
	ds_read2_b32 v[44:45], v24 offset0:214 offset1:222
	ds_read2_b32 v[46:47], v24 offset0:247 offset1:255
	v_cvt_pk_bf16_f32 v19, v36, v38
	s_waitcnt lgkmcnt(3)
	s_waitcnt lgkmcnt(2)
	v_cvt_pk_bf16_f32 v20, v40, v42
	s_waitcnt lgkmcnt(1)
	s_waitcnt lgkmcnt(0)
	v_cvt_pk_bf16_f32 v21, v44, v46
	v_or_b32_e32 v3, v28, v26
	v_lshlrev_b32_e32 v4, 12, v3
	v_lshl_add_u64 v[48:49], v[32:33], 0, v[4:5]
	global_store_dwordx4 v[48:49], v[18:21], off
	s_nop 1
	v_cvt_pk_bf16_f32 v18, v31, v35
	v_cvt_pk_bf16_f32 v19, v37, v39
	v_cvt_pk_bf16_f32 v20, v41, v43
	v_cvt_pk_bf16_f32 v21, v45, v47
	v_or_b32_e32 v3, v28, v27
	v_lshlrev_b32_e32 v4, 12, v3
	v_lshl_add_u64 v[28:29], v[32:33], 0, v[4:5]
	global_store_dwordx4 v[28:29], v[18:21], off
	s_waitcnt lgkmcnt(0)
	s_branch .LBB0_599

; #define LAS __attribute__((address_space(3)))
; __device__ __forceinline__ float bflo(unsigned w) { return __uint_as_float(w << 16); }
; __device__ __forceinline__ float bfhi(unsigned w) { return __uint_as_float(w & 0xffff0000u); }
; __device__ __forceinline__ unsigned pk2(float lo, float hi) { return f2bf(lo) | (f2bf(hi) << 16); }
; __device__ __forceinline__ void phase_mixer_a(const Params& P, LAS unsigned char* lds, int ustart, int ustride, bool dry) {
;     ...
;             u32x2 pv[8]; float bsv[8];
; #pragma unroll
;             for (int mt = 0; mt < 8; ++mt) { const int t = 16 * mt + (lane & 15);
;                 pv[mt] = *(const u32x2*)(PJ + T_P + (size_t)(r0 + t) * 1024 + h * 128 + 16 * w + 4 * g4); bsv[mt] = P.b_spatial[h * 128 + t]; }
;             f32x4 acc[8];
; #pragma unroll
;             for (int mt = 0; mt < 8; ++mt) acc[mt] = (f32x4){0.f, 0.f, 0.f, 0.f};
; #pragma unroll
;             for (int ks = 0; ks < 4; ++ks) {
;                 const unsigned a0 = (unsigned)((32 * ks + 8 * g4 + q) * VN_P + 32 * w + 8 * p);
;                 const s16x4 lo = __builtin_amdgcn_ds_read_tr16_b64_v4i16((LAS s16x4*)(lds + a0)), hi = __builtin_amdgcn_ds_read_tr16_b64_v4i16((LAS s16x4*)(lds + a0 + 4 * VN_P));
;                 const bf16x8 vf = (bf16x8){lo[0], lo[1], lo[2], lo[3], hi[0], hi[1], hi[2], hi[3]};
; #pragma unroll
;                 for (int mt = 2 * ks; mt < 8; ++mt) {
;                     const bf16x8 wf = *(const LAS bf16x8*)(lds + W_OFF + (16 * mt + (lane & 15)) * W_P + (32 * ks + 8 * g4) * 2);
;                     acc[mt] = __builtin_amdgcn_mfma_f32_16x16x32_bf16(vf, wf, acc[mt], 0, 0, 0);
;                 }
;             }
; #pragma unroll
;             for (int mt = 0; mt < 8; ++mt) {
;                 const int t = 16 * mt + (lane & 15); const float bs = bsv[mt];
;                 u32x2 o; o.x = pk2(bflo(pv[mt].x) * (acc[mt][0] + bs), bfhi(pv[mt].x) * (acc[mt][1] + bs)); o.y = pk2(bflo(pv[mt].y) * (acc[mt][2] + bs), bfhi(pv[mt].y) * (acc[mt][3] + bs));
;                 if (!dry) *(u32x2*)((bf16_t*)P.out + (size_t)(r0 + t) * 2048 + h * 128 + 16 * w + 4 * g4) = o;
;             }
.LBB0_631:
	ds_read_b64_tr_b16 v[16:17], v163
	ds_read_b64_tr_b16 v[18:19], v163 offset:1152
	v_add_u32_e32 v41, v142, v143
	ds_read_b128 v[20:23], v41 offset:36864
	ds_read_b128 v[24:27], v41 offset:41216
	v_lshl_add_u64 v[128:129], v[94:95], 0, s[16:17]
	v_lshl_add_u64 v[204:205], v[58:59], 0, s[6:7]
	s_waitcnt lgkmcnt(1)
	v_mfma_f32_16x16x32_bf16 v[28:31], v[16:19], v[20:23], 0
	ds_read_b128 v[20:23], v41 offset:45568
	global_load_dwordx2 v[192:193], v[128:129], off
	ds_read_b128 v[128:131], v41 offset:49920
	global_load_dword v206, v[204:205], off
	ds_read_b128 v[168:171], v41 offset:54272
	ds_read_b128 v[172:175], v41 offset:58624
	v_lshl_add_u64 v[188:189], v[96:97], 0, s[16:17]
	v_add_u32_e32 v43, v142, v144
	ds_read_b128 v[176:179], v41 offset:62976
	ds_read_b64_tr_b16 v[180:181], v164
	ds_read_b64_tr_b16 v[182:183], v164 offset:1152
	ds_read_b128 v[184:187], v43 offset:62976
	v_add_u32_e32 v41, v145, v143
	global_load_dwordx2 v[208:209], v[188:189], off
	ds_read_b128 v[188:191], v41 offset:45568
	s_waitcnt lgkmcnt(8)
	v_mfma_f32_16x16x32_bf16 v[20:23], v[16:19], v[20:23], 0
	global_load_dword v210, v[204:205], off offset:64
	v_add_u32_e32 v43, v145, v144
	v_lshl_add_u64 v[200:201], v[98:99], 0, s[16:17]
	v_mfma_f32_16x16x32_bf16 v[24:27], v[16:19], v[24:27], 0
	v_lshl_add_u64 v[202:203], v[100:101], 0, s[16:17]
	v_lshl_add_u64 v[212:213], v[102:103], 0, s[16:17]
	v_lshl_add_u64 v[214:215], v[104:105], 0, s[16:17]
	s_waitcnt lgkmcnt(7)
	v_mfma_f32_16x16x32_bf16 v[128:131], v[16:19], v[128:131], 0
	v_lshl_add_u64 v[216:217], v[106:107], 0, s[16:17]
	v_add_u32_e32 v45, v147, v144
	v_lshl_add_u64 v[218:219], v[108:109], 0, s[16:17]
	s_waitcnt lgkmcnt(6)
	v_mfma_f32_16x16x32_bf16 v[168:171], v[16:19], v[168:171], 0
	v_lshl_add_u64 v[126:127], v[126:127], 0, s[14:15]
	v_lshl_add_u64 v[124:125], v[124:125], 0, s[14:15]
	v_lshl_add_u64 v[122:123], v[122:123], 0, s[14:15]
	s_waitcnt lgkmcnt(5)
	v_mfma_f32_16x16x32_bf16 v[172:175], v[16:19], v[172:175], 0
	v_lshl_add_u64 v[120:121], v[120:121], 0, s[14:15]
	s_waitcnt lgkmcnt(4)
	v_mfma_f32_16x16x32_bf16 v[176:179], v[16:19], v[176:179], 0
	s_waitcnt lgkmcnt(1)
	v_mfma_f32_16x16x32_bf16 v[16:19], v[16:19], v[184:187], 0
	ds_read_b128 v[184:187], v41 offset:49920
	s_waitcnt lgkmcnt(1)
	v_mfma_f32_16x16x32_bf16 v[188:191], v[180:183], v[188:191], v[20:23]
	s_nop 2
	ds_read_b128 v[20:23], v41 offset:54272
	s_waitcnt lgkmcnt(1)
	v_mfma_f32_16x16x32_bf16 v[128:131], v[180:183], v[184:187], v[128:131]
	ds_read_b128 v[184:187], v41 offset:58624
	s_waitcnt lgkmcnt(1)
	v_mfma_f32_16x16x32_bf16 v[20:23], v[180:183], v[20:23], v[168:171]
	s_nop 2
	ds_read_b128 v[168:171], v41 offset:62976
	s_waitcnt lgkmcnt(1)
	v_mfma_f32_16x16x32_bf16 v[172:175], v[180:183], v[184:187], v[172:175]
	ds_read_b64_tr_b16 v[184:185], v165
	ds_read_b64_tr_b16 v[186:187], v165 offset:1152
	ds_read_b128 v[196:199], v43 offset:62976
	v_add_u32_e32 v41, v146, v143
	global_load_dwordx2 v[220:221], v[200:201], off
	s_waitcnt lgkmcnt(3)
	v_mfma_f32_16x16x32_bf16 v[168:171], v[180:183], v[168:171], v[176:179]
	global_load_dword v222, v[204:205], off offset:128
	v_add_u32_e32 v43, v146, v144
	s_nop 0
	ds_read_b128 v[176:179], v41 offset:54272
	s_waitcnt lgkmcnt(1)
	v_mfma_f32_16x16x32_bf16 v[16:19], v[180:183], v[196:199], v[16:19]
	ds_read_b128 v[180:183], v41 offset:58624
	s_waitcnt lgkmcnt(1)
	v_mfma_f32_16x16x32_bf16 v[176:179], v[184:187], v[176:179], v[20:23]
	ds_read_b64_tr_b16 v[196:197], v166
	ds_read_b64_tr_b16 v[198:199], v166 offset:1152
	s_nop 0
	ds_read_b128 v[20:23], v41 offset:62976
	v_add_u32_e32 v41, v147, v143
	s_waitcnt lgkmcnt(3)
	v_mfma_f32_16x16x32_bf16 v[172:175], v[184:187], v[180:183], v[172:175]
	ds_read_b128 v[180:183], v43 offset:62976
	global_load_dwordx2 v[224:225], v[202:203], off
	s_nop 0
	global_load_dwordx2 v[212:213], v[212:213], off
	ds_read_b128 v[200:203], v41 offset:62976
	s_waitcnt lgkmcnt(2)
	v_mfma_f32_16x16x32_bf16 v[168:171], v[184:187], v[20:23], v[168:171]
	s_waitcnt lgkmcnt(1)
	v_mfma_f32_16x16x32_bf16 v[16:19], v[184:187], v[180:183], v[16:19]
	global_load_dwordx2 v[184:185], v[214:215], off
	global_load_dwordx2 v[186:187], v[216:217], off
	global_load_dwordx2 v[20:21], v[218:219], off
	ds_read_b128 v[180:183], v45 offset:62976
	s_waitcnt lgkmcnt(1)
	v_mfma_f32_16x16x32_bf16 v[168:171], v[196:199], v[200:203], v[168:171]
	global_load_dword v200, v[204:205], off offset:192
	global_load_dword v202, v[204:205], off offset:256
	global_load_dword v214, v[204:205], off offset:320
	global_load_dword v216, v[204:205], off offset:384
	global_load_dword v22, v[204:205], off offset:448
	s_waitcnt lgkmcnt(0)
	v_mfma_f32_16x16x32_bf16 v[16:19], v[196:199], v[180:183], v[16:19]
	v_mov_b32_e32 v182, v28
	v_mov_b32_e32 v183, v30
	s_waitcnt vmcnt(15)
	v_lshlrev_b32_e32 v181, 16, v193
	v_lshlrev_b32_e32 v180, 16, v192
	s_waitcnt vmcnt(14)
	v_pk_add_f32 v[182:183], v[206:207], v[182:183] op_sel_hi:[0,1]
	v_mov_b32_e32 v30, v29
	v_pk_mul_f32 v[180:181], v[182:183], v[180:181]
	v_and_b32_e32 v183, 0xffff0000, v193
	v_and_b32_e32 v182, 0xffff0000, v192
	v_pk_add_f32 v[28:29], v[206:207], v[30:31] op_sel_hi:[0,1]
	v_pk_mul_f32 v[28:29], v[28:29], v[182:183]
	s_nop 0
	v_cvt_pk_bf16_f32 v29, v181, v29
	v_cvt_pk_bf16_f32 v28, v180, v28
	v_lshl_add_u64 v[30:31], v[110:111], 0, s[16:17]
	global_store_dwordx2 v[30:31], v[28:29], off
	v_mov_b32_e32 v30, v24
	v_mov_b32_e32 v31, v26
	s_waitcnt vmcnt(14)
	v_lshlrev_b32_e32 v29, 16, v209
	v_lshlrev_b32_e32 v28, 16, v208
	s_waitcnt vmcnt(13)
; __device__ __forceinline__ float bflo(unsigned w) { return __uint_as_float(w << 16); }
; __device__ __forceinline__ float bfhi(unsigned w) { return __uint_as_float(w & 0xffff0000u); }
; __device__ __forceinline__ unsigned pk2(float lo, float hi) { return f2bf(lo) | (f2bf(hi) << 16); }
; __device__ __forceinline__ void phase_mixer_a(const Params& P, LAS unsigned char* lds, int ustart, int ustride, bool dry) {
;     ...
; #pragma unroll
;             for (int mt = 0; mt < 8; ++mt) {
;                 const int t = 16 * mt + (lane & 15); const float bs = bsv[mt];
;                 u32x2 o; o.x = pk2(bflo(pv[mt].x) * (acc[mt][0] + bs), bfhi(pv[mt].x) * (acc[mt][1] + bs)); o.y = pk2(bflo(pv[mt].y) * (acc[mt][2] + bs), bfhi(pv[mt].y) * (acc[mt][3] + bs));
;                 if (!dry) *(u32x2*)((bf16_t*)P.out + (size_t)(r0 + t) * 2048 + h * 128 + 16 * w + 4 * g4) = o;
;             }
;             __syncthreads();
	v_pk_add_f32 v[30:31], v[210:211], v[30:31] op_sel_hi:[0,1]
	v_mov_b32_e32 v26, v25
	v_pk_mul_f32 v[28:29], v[30:31], v[28:29]
	v_and_b32_e32 v31, 0xffff0000, v209
	v_and_b32_e32 v30, 0xffff0000, v208
	v_pk_add_f32 v[24:25], v[210:211], v[26:27] op_sel_hi:[0,1]
	v_pk_mul_f32 v[24:25], v[24:25], v[30:31]
	s_nop 0
	v_cvt_pk_bf16_f32 v24, v28, v24
	v_cvt_pk_bf16_f32 v25, v29, v25
	v_lshl_add_u64 v[26:27], v[112:113], 0, s[16:17]
	global_store_dwordx2 v[26:27], v[24:25], off
	v_mov_b32_e32 v26, v188
	v_mov_b32_e32 v27, v190
	s_waitcnt vmcnt(13)
	v_lshlrev_b32_e32 v25, 16, v221
	v_lshlrev_b32_e32 v24, 16, v220
	s_waitcnt vmcnt(12)
	v_pk_add_f32 v[26:27], v[222:223], v[26:27] op_sel_hi:[0,1]
	v_mov_b32_e32 v190, v189
	v_pk_mul_f32 v[24:25], v[26:27], v[24:25]
	v_and_b32_e32 v27, 0xffff0000, v221
	v_and_b32_e32 v26, 0xffff0000, v220
	v_pk_add_f32 v[28:29], v[222:223], v[190:191] op_sel_hi:[0,1]
	v_pk_mul_f32 v[26:27], v[28:29], v[26:27]
	s_nop 0
	v_cvt_pk_bf16_f32 v24, v24, v26
	v_cvt_pk_bf16_f32 v25, v25, v27
	v_lshl_add_u64 v[26:27], v[114:115], 0, s[16:17]
	global_store_dwordx2 v[26:27], v[24:25], off
	v_mov_b32_e32 v26, v128
	v_mov_b32_e32 v27, v130
	s_waitcnt vmcnt(12)
	v_lshlrev_b32_e32 v25, 16, v225
	v_lshlrev_b32_e32 v24, 16, v224
	s_waitcnt vmcnt(7)
	v_pk_add_f32 v[26:27], v[200:201], v[26:27] op_sel_hi:[0,1]
	v_mov_b32_e32 v130, v129
	v_pk_mul_f32 v[24:25], v[26:27], v[24:25]
	v_and_b32_e32 v27, 0xffff0000, v225
	v_and_b32_e32 v26, 0xffff0000, v224
	v_pk_add_f32 v[28:29], v[200:201], v[130:131] op_sel_hi:[0,1]
	v_pk_mul_f32 v[26:27], v[28:29], v[26:27]
	s_nop 0
	v_cvt_pk_bf16_f32 v24, v24, v26
	v_cvt_pk_bf16_f32 v25, v25, v27
	v_lshl_add_u64 v[26:27], v[116:117], 0, s[16:17]
	global_store_dwordx2 v[26:27], v[24:25], off
	v_mov_b32_e32 v26, v176
	v_mov_b32_e32 v27, v178
	v_lshlrev_b32_e32 v25, 16, v213
	v_lshlrev_b32_e32 v24, 16, v212
	s_waitcnt vmcnt(7)
	v_pk_add_f32 v[26:27], v[202:203], v[26:27] op_sel_hi:[0,1]
	v_mov_b32_e32 v178, v177
	v_pk_mul_f32 v[24:25], v[26:27], v[24:25]
	v_and_b32_e32 v27, 0xffff0000, v213
	v_and_b32_e32 v26, 0xffff0000, v212
	v_pk_add_f32 v[28:29], v[202:203], v[178:179] op_sel_hi:[0,1]
	v_pk_mul_f32 v[26:27], v[28:29], v[26:27]
	s_nop 0
	v_cvt_pk_bf16_f32 v24, v24, v26
	v_cvt_pk_bf16_f32 v25, v25, v27
	v_lshl_add_u64 v[26:27], v[118:119], 0, s[16:17]
	global_store_dwordx2 v[26:27], v[24:25], off
	v_mov_b32_e32 v26, v172
	v_mov_b32_e32 v27, v174
	v_lshlrev_b32_e32 v25, 16, v185
	v_lshlrev_b32_e32 v24, 16, v184
	s_waitcnt vmcnt(7)
	v_pk_add_f32 v[26:27], v[214:215], v[26:27] op_sel_hi:[0,1]
	v_mov_b32_e32 v174, v173
	v_pk_mul_f32 v[24:25], v[26:27], v[24:25]
	v_and_b32_e32 v27, 0xffff0000, v185
	v_and_b32_e32 v26, 0xffff0000, v184
	v_pk_add_f32 v[28:29], v[214:215], v[174:175] op_sel_hi:[0,1]
	v_pk_mul_f32 v[26:27], v[28:29], v[26:27]
	s_nop 0
	v_cvt_pk_bf16_f32 v24, v24, v26
	v_cvt_pk_bf16_f32 v25, v25, v27
	v_lshl_add_u64 v[26:27], v[92:93], 0, s[16:17]
	global_store_dwordx2 v[26:27], v[24:25], off
	v_mov_b32_e32 v26, v168
	v_mov_b32_e32 v27, v170
	v_lshlrev_b32_e32 v25, 16, v187
	v_lshlrev_b32_e32 v24, 16, v186
	s_waitcnt vmcnt(7)
	v_pk_add_f32 v[26:27], v[216:217], v[26:27] op_sel_hi:[0,1]
	v_mov_b32_e32 v170, v169
	v_pk_mul_f32 v[24:25], v[26:27], v[24:25]
	v_and_b32_e32 v27, 0xffff0000, v187
	v_and_b32_e32 v26, 0xffff0000, v186
	v_pk_add_f32 v[28:29], v[216:217], v[170:171] op_sel_hi:[0,1]
	v_pk_mul_f32 v[26:27], v[28:29], v[26:27]
	v_and_b32_sdwa v23, v25, v167 dst_sel:DWORD dst_unused:UNUSED_PAD src0_sel:WORD_1 src1_sel:DWORD
	v_cvt_pk_bf16_f32 v24, v24, v26
	v_add3_u32 v23, v25, v23, s18
	v_cvt_pk_bf16_f32 v25, v25, v27
	v_lshl_add_u64 v[26:27], v[90:91], 0, s[16:17]
	global_store_dwordx2 v[26:27], v[24:25], off
	v_mov_b32_e32 v27, v18
	v_mov_b32_e32 v18, v17
	v_lshlrev_b32_e32 v25, 16, v21
	v_lshlrev_b32_e32 v24, 16, v20
	v_mov_b32_e32 v26, v16
	v_and_b32_e32 v21, 0xffff0000, v21
	v_and_b32_e32 v20, 0xffff0000, v20
	s_waitcnt vmcnt(7)
	v_pk_add_f32 v[16:17], v[22:23], v[18:19] op_sel_hi:[0,1]
	v_pk_add_f32 v[26:27], v[22:23], v[26:27] op_sel_hi:[0,1]
	v_pk_mul_f32 v[16:17], v[16:17], v[20:21]
	v_pk_mul_f32 v[24:25], v[26:27], v[24:25]
	s_nop 0
	v_cvt_pk_bf16_f32 v17, v25, v17
	v_cvt_pk_bf16_f32 v16, v24, v16
	v_lshl_add_u64 v[18:19], v[88:89], 0, s[16:17]
	s_add_u32 s16, s16, 0x100
	s_addc_u32 s17, s17, 0
	s_add_u32 s6, s6, 0x200
	s_addc_u32 s7, s7, 0
	s_cmpk_eq_i32 s16, 0x800
	global_store_dwordx2 v[18:19], v[16:17], off
	s_barrier
	s_cbranch_scc1 .LBB0_619
; #define LAS __attribute__((address_space(3)))
; __device__ __forceinline__ float bflo(unsigned w) { return __uint_as_float(w << 16); }
; __device__ __forceinline__ float bfhi(unsigned w) { return __uint_as_float(w & 0xffff0000u); }
; __device__ __forceinline__ unsigned pk2(float lo, float hi) { return f2bf(lo) | (f2bf(hi) << 16); }
; __device__ __forceinline__ void phase_mixer_a(const Params& P, LAS unsigned char* lds, int ustart, int ustride, bool dry) {
;     ...
; #pragma unroll
;             for (int i = 0; i < 4; ++i) {
;                 const int item = tid + 512 * i, c8 = item & 15, s = item >> 4;
;                 const u32x4 gv = pgv[i];
;                 const float mean = stats[2 * s], rstd = stats[2 * s + 1];
;                 const f32x4 g0 = *(const f32x4*)(P.ln_v_g + h * 128 + c8 * 8), g1 = *(const f32x4*)(P.ln_v_g + h * 128 + c8 * 8 + 4);
;                 const f32x4 b0 = *(const f32x4*)(P.ln_v_b + h * 128 + c8 * 8), b1 = *(const f32x4*)(P.ln_v_b + h * 128 + c8 * 8 + 4);
;                 u32x4 o;
;                 o.x = pk2((bflo(gv.x) - mean) * rstd * g0[0] + b0[0], (bfhi(gv.x) - mean) * rstd * g0[1] + b0[1]);
;                 o.y = pk2((bflo(gv.y) - mean) * rstd * g0[2] + b0[2], (bfhi(gv.y) - mean) * rstd * g0[3] + b0[3]);
;                 o.z = pk2((bflo(gv.z) - mean) * rstd * g1[0] + b1[0], (bfhi(gv.z) - mean) * rstd * g1[1] + b1[1]);
;                 o.w = pk2((bflo(gv.w) - mean) * rstd * g1[2] + b1[2], (bfhi(gv.w) - mean) * rstd * g1[3] + b1[3]);
;                 *(LAS u32x4*)(lds + s * VN_P + c8 * 16) = o;
;                 *(LAS u32x4*)(lds + W_OFF + s * W_P + c8 * 16) = *(const u32x4*)(WsT + h * 16384 + item * 8);
;             }
;             __syncthreads();
;             if (h + 1 < 8) {
; #pragma unroll
;                 for (int i = 0; i < 4; ++i) { const int item = tid + 512 * i, c8 = item & 15, s = item >> 4;
;                     pgv[i] = *(const u32x4*)(PJ + T_GV + (size_t)(r0 + s) * 1024 + (h + 1) * 128 + c8 * 8); }
;             }
.LBB0_632:
	v_lshl_add_u64 v[16:17], v[62:63], 0, s[6:7]
	global_load_dwordx4 v[24:27], v[16:17], off offset:-16
	v_lshl_add_u64 v[20:21], v[66:67], 0, s[6:7]
	global_load_dwordx4 v[28:31], v[20:21], off offset:-16
	s_nop 0
	global_load_dwordx4 v[16:19], v[16:17], off
	s_nop 0
	global_load_dwordx4 v[20:23], v[20:21], off
	s_nop 0
	global_load_dwordx4 v[168:171], v[126:127], off
	global_load_dwordx4 v[172:175], v[124:125], off
	ds_read_b64 v[128:129], v151
	s_waitcnt vmcnt(9)
	v_lshlrev_b32_e32 v131, 16, v1
	v_lshlrev_b32_e32 v130, 16, v0
	v_and_b32_e32 v177, 0xffff0000, v1
	v_and_b32_e32 v176, 0xffff0000, v0
	v_lshlrev_b32_e32 v179, 16, v3
	v_lshlrev_b32_e32 v178, 16, v2
	v_and_b32_e32 v181, 0xffff0000, v3
	v_and_b32_e32 v180, 0xffff0000, v2
	s_waitcnt lgkmcnt(0)
	v_pk_add_f32 v[130:131], v[130:131], v[128:129] op_sel_hi:[1,0] neg_lo:[0,1] neg_hi:[0,1]
	v_pk_add_f32 v[176:177], v[176:177], v[128:129] op_sel_hi:[1,0] neg_lo:[0,1] neg_hi:[0,1]
	v_pk_add_f32 v[178:179], v[178:179], v[128:129] op_sel_hi:[1,0] neg_lo:[0,1] neg_hi:[0,1]
	v_pk_add_f32 v[180:181], v[180:181], v[128:129] op_sel_hi:[1,0] neg_lo:[0,1] neg_hi:[0,1]
	v_pk_mul_f32 v[188:189], v[128:129], v[130:131] op_sel:[1,0]
	v_pk_mul_f32 v[176:177], v[128:129], v[176:177] op_sel:[1,0]
	v_pk_mul_f32 v[178:179], v[128:129], v[178:179] op_sel:[1,0]
	v_pk_mul_f32 v[180:181], v[128:129], v[180:181] op_sel:[1,0]
	s_waitcnt vmcnt(8)
	v_lshlrev_b32_e32 v183, 16, v5
	v_lshlrev_b32_e32 v182, 16, v4
	v_and_b32_e32 v185, 0xffff0000, v5
	v_and_b32_e32 v184, 0xffff0000, v4
	v_lshlrev_b32_e32 v187, 16, v7
	v_lshlrev_b32_e32 v186, 16, v6
	s_cmpk_lg_i32 s16, 0x700
	s_waitcnt vmcnt(4)
	v_mov_b32_e32 v130, v28
	v_mov_b32_e32 v128, v24
	v_mov_b32_e32 v129, v26
	v_mov_b32_e32 v131, v30
	v_mov_b32_e32 v26, v25
	v_mov_b32_e32 v30, v29
	s_waitcnt vmcnt(3)
	v_mov_b32_e32 v24, v16
	v_mov_b32_e32 v25, v18
	s_waitcnt vmcnt(2)
	v_mov_b32_e32 v28, v20
	v_mov_b32_e32 v29, v22
	v_mov_b32_e32 v18, v17
	v_mov_b32_e32 v22, v21
	v_pk_fma_f32 v[16:17], v[188:189], v[128:129], v[130:131]
	v_pk_fma_f32 v[20:21], v[176:177], v[26:27], v[30:31]
	v_pk_fma_f32 v[176:177], v[178:179], v[24:25], v[28:29]
	v_pk_fma_f32 v[178:179], v[180:181], v[18:19], v[22:23]
	v_cvt_pk_bf16_f32 v255, v16, v20
	v_cvt_pk_bf16_f32 v254, v17, v21
	v_cvt_pk_bf16_f32 v179, v177, v179
	v_cvt_pk_bf16_f32 v178, v176, v178
	v_mov_b32_e32 v177, v254
	v_mov_b32_e32 v176, v255
	ds_write_b128 v152, v[176:179]
	s_waitcnt vmcnt(1)
	ds_write_b128 v153, v[168:171] offset:36864
	ds_read_b64 v[16:17], v154
	global_load_dwordx4 v[168:171], v[122:123], off
	v_and_b32_e32 v21, 0xffff0000, v7
	v_and_b32_e32 v20, 0xffff0000, v6
	s_waitcnt lgkmcnt(0)
	v_pk_add_f32 v[176:177], v[182:183], v[16:17] op_sel_hi:[1,0] neg_lo:[0,1] neg_hi:[0,1]
	v_pk_add_f32 v[178:179], v[184:185], v[16:17] op_sel_hi:[1,0] neg_lo:[0,1] neg_hi:[0,1]
	v_pk_add_f32 v[180:181], v[186:187], v[16:17] op_sel_hi:[1,0] neg_lo:[0,1] neg_hi:[0,1]
	v_pk_add_f32 v[20:21], v[20:21], v[16:17] op_sel_hi:[1,0] neg_lo:[0,1] neg_hi:[0,1]
	v_pk_mul_f32 v[176:177], v[16:17], v[176:177] op_sel:[1,0]
	v_pk_mul_f32 v[178:179], v[16:17], v[178:179] op_sel:[1,0]
	v_pk_mul_f32 v[180:181], v[16:17], v[180:181] op_sel:[1,0]
	v_pk_mul_f32 v[16:17], v[16:17], v[20:21] op_sel:[1,0]
	v_pk_fma_f32 v[20:21], v[128:129], v[176:177], v[130:131]
	v_pk_fma_f32 v[16:17], v[18:19], v[16:17], v[22:23]
	v_pk_fma_f32 v[176:177], v[26:27], v[178:179], v[30:31]
	v_pk_fma_f32 v[178:179], v[24:25], v[180:181], v[28:29]
	s_nop 0
	v_cvt_pk_bf16_f32 v178, v178, v16
	v_cvt_pk_bf16_f32 v179, v179, v17
	v_cvt_pk_bf16_f32 v177, v21, v177
	v_cvt_pk_bf16_f32 v176, v20, v176
	ds_write_b128 v155, v[176:179]
	s_waitcnt vmcnt(1)
	ds_write_b128 v156, v[172:175] offset:36864
	ds_read_b64 v[16:17], v157
	v_and_b32_e32 v173, 0xffff0000, v9
	v_and_b32_e32 v172, 0xffff0000, v8
	v_lshlrev_b32_e32 v21, 16, v9
	v_lshlrev_b32_e32 v20, 16, v8
	s_waitcnt lgkmcnt(0)
	v_pk_add_f32 v[172:173], v[172:173], v[16:17] op_sel_hi:[1,0] neg_lo:[0,1] neg_hi:[0,1]
	v_and_b32_e32 v181, 0xffff0000, v11
	v_pk_mul_f32 v[172:173], v[16:17], v[172:173] op_sel:[1,0]
	v_and_b32_e32 v180, 0xffff0000, v10
	v_pk_fma_f32 v[176:177], v[26:27], v[172:173], v[30:31]
	v_lshlrev_b32_e32 v173, 16, v11
	v_lshlrev_b32_e32 v172, 16, v10
	v_pk_add_f32 v[172:173], v[172:173], v[16:17] op_sel_hi:[1,0] neg_lo:[0,1] neg_hi:[0,1]
	v_pk_add_f32 v[20:21], v[20:21], v[16:17] op_sel_hi:[1,0] neg_lo:[0,1] neg_hi:[0,1]
	v_pk_mul_f32 v[172:173], v[16:17], v[172:173] op_sel:[1,0]
	v_pk_add_f32 v[180:181], v[180:181], v[16:17] op_sel_hi:[1,0] neg_lo:[0,1] neg_hi:[0,1]
	v_pk_fma_f32 v[178:179], v[24:25], v[172:173], v[28:29]
	global_load_dwordx4 v[172:175], v[120:121], off
	v_pk_mul_f32 v[20:21], v[16:17], v[20:21] op_sel:[1,0]
	v_pk_mul_f32 v[16:17], v[16:17], v[180:181] op_sel:[1,0]
	v_pk_fma_f32 v[20:21], v[128:129], v[20:21], v[130:131]
	v_pk_fma_f32 v[16:17], v[18:19], v[16:17], v[22:23]
	s_nop 0
	v_cvt_pk_bf16_f32 v178, v178, v16
	v_cvt_pk_bf16_f32 v179, v179, v17
	v_cvt_pk_bf16_f32 v177, v21, v177
	v_cvt_pk_bf16_f32 v176, v20, v176
	ds_write_b128 v158, v[176:179]
	s_waitcnt vmcnt(1)
	ds_write_b128 v159, v[168:171] offset:36864
	ds_read_b64 v[16:17], v160
	v_lshlrev_b32_e32 v21, 16, v13
	v_lshlrev_b32_e32 v20, 16, v12
	s_waitcnt lgkmcnt(0)
	v_pk_add_f32 v[20:21], v[20:21], v[16:17] op_sel_hi:[1,0] neg_lo:[0,1] neg_hi:[0,1]
	s_nop 0
	v_pk_mul_f32 v[20:21], v[16:17], v[20:21] op_sel:[1,0]
	s_nop 0
	v_pk_fma_f32 v[20:21], v[128:129], v[20:21], v[130:131]
	v_and_b32_e32 v129, 0xffff0000, v13
	v_and_b32_e32 v128, 0xffff0000, v12
	v_pk_add_f32 v[128:129], v[128:129], v[16:17] op_sel_hi:[1,0] neg_lo:[0,1] neg_hi:[0,1]
	s_nop 0
	v_pk_mul_f32 v[128:129], v[16:17], v[128:129] op_sel:[1,0]
	s_nop 0
	v_pk_fma_f32 v[26:27], v[26:27], v[128:129], v[30:31]
	v_lshlrev_b32_e32 v31, 16, v15
	v_lshlrev_b32_e32 v30, 16, v14
	v_pk_add_f32 v[30:31], v[30:31], v[16:17] op_sel_hi:[1,0] neg_lo:[0,1] neg_hi:[0,1]
	s_nop 0
	v_pk_mul_f32 v[30:31], v[16:17], v[30:31] op_sel:[1,0]
	s_nop 0
	v_pk_fma_f32 v[24:25], v[24:25], v[30:31], v[28:29]
	v_and_b32_e32 v29, 0xffff0000, v15
	v_and_b32_e32 v28, 0xffff0000, v14
	v_pk_add_f32 v[28:29], v[28:29], v[16:17] op_sel_hi:[1,0] neg_lo:[0,1] neg_hi:[0,1]
	s_nop 0
	v_pk_mul_f32 v[16:17], v[16:17], v[28:29] op_sel:[1,0]
	s_nop 0
	v_pk_fma_f32 v[16:17], v[18:19], v[16:17], v[22:23]
	s_nop 0
	v_cvt_pk_bf16_f32 v18, v24, v16
	v_cvt_pk_bf16_f32 v19, v25, v17
	v_cvt_pk_bf16_f32 v16, v20, v26
	v_cvt_pk_bf16_f32 v17, v21, v27
	ds_write_b128 v161, v[16:19]
	s_waitcnt vmcnt(0)
	ds_write_b128 v162, v[172:175] offset:36864
	s_waitcnt lgkmcnt(0)
	s_barrier
	s_cbranch_scc0 .LBB0_631
	v_lshl_add_u64 v[12:13], v[86:87], 0, s[16:17]
	v_lshl_add_u64 v[8:9], v[84:85], 0, s[16:17]
	v_lshl_add_u64 v[4:5], v[82:83], 0, s[16:17]
	v_lshl_add_u64 v[0:1], v[80:81], 0, s[16:17]
	global_load_dwordx4 v[0:3], v[0:1], off
	s_nop 0
	global_load_dwordx4 v[4:7], v[4:5], off
	s_nop 0
	global_load_dwordx4 v[8:11], v[8:9], off
	s_nop 0
	global_load_dwordx4 v[12:15], v[12:13], off
	s_branch .LBB0_631

; #define LAS __attribute__((address_space(3)))
; __device__ __forceinline__ float bflo(unsigned w) { return __uint_as_float(w << 16); }
; __device__ __forceinline__ float bfhi(unsigned w) { return __uint_as_float(w & 0xffff0000u); }
; __device__ __forceinline__ unsigned pk2(float lo, float hi) { return f2bf(lo) | (f2bf(hi) << 16); }
; template <bool FULL>
; __device__ __forceinline__ void gla_pass(const Params& P, LAS unsigned char* lds, f32x4 (&S)[8][2], int bh, int c0, int L, bool dry) {
;     ...
;         if (FULL) {
;             f32x4 gn[2];
; #pragma unroll
;             for (int vt = 0; vt < 2; ++vt) gn[vt] = *(const f32x4*)(P.gla_norm_g + 32 * w + 4 * g + 16 * vt);
; #pragma unroll
;             for (int tt = 0; tt < 4; ++tt) {
;                 const int t = 16 * tt + fr;
;                 const f32x4 r0 = *(const LAS f32x4*)(red + t * 8), r1 = *(const LAS f32x4*)(red + t * 8 + 4);
;                 const float rstd = 1.0f / sqrtf(((r0[0] + r0[1]) + (r0[2] + r0[3]) + (r1[0] + r1[1]) + (r1[2] + r1[3])) * (1.0f / 256.0f) + RMS_EPS);
; #pragma unroll
;                 for (int vt = 0; vt < 2; ++vt) {
;                     bf16_t* op = (bf16_t*)P.out + (row0 + t) * 2048 + 1024 + h * 256 + 32 * w + 16 * vt + 4 * g;
;                     const u32x2 z = zb[vt][tt]; const f32x4 ov = o[vt][tt] * rstd * gn[vt];
;                     u32x2 r; r.x = pk2(ov[0] * bflo(z.x), ov[1] * bfhi(z.x)); r.y = pk2(ov[2] * bflo(z.y), ov[3] * bfhi(z.y));
;                     if (!dry) *(u32x2*)op = r;
;                 }
;             }
.LBB0_698:
	v_mov_b32_e32 v140, v238
	v_mov_b32_e32 v141, v239
	v_mov_b32_e32 v142, v240
	v_mov_b32_e32 v143, v241
	v_mov_b32_e32 v136, v242
	v_mov_b32_e32 v137, v243
	v_mov_b32_e32 v138, v244
	v_mov_b32_e32 v139, v245
	ds_read_b128 v[208:211], v190
	ds_read_b128 v[212:215], v190 offset:16
	s_waitcnt vmcnt(7)
	v_lshlrev_b32_e32 v217, 16, v181
	v_lshlrev_b32_e32 v216, 16, v180
	v_and_b32_e32 v181, 0xffff0000, v181
	s_waitcnt lgkmcnt(1)
	v_mov_b32_e32 v220, v209
	v_mov_b32_e32 v221, v210
	v_mov_b32_e32 v209, v211
	s_waitcnt lgkmcnt(0)
	v_mov_b32_e32 v210, v214
	v_mov_b32_e32 v211, v212
	v_mov_b32_e32 v212, v215
	v_pk_add_f32 v[208:209], v[220:221], v[208:209]
	v_pk_add_f32 v[210:211], v[210:211], v[212:213]
	v_add_f32_e32 v208, v208, v209
	v_add_f32_e32 v208, v208, v211
	v_add_f32_e32 v208, v210, v208
	v_fmamk_f32 v208, v208, 0x3b800000, v202
	v_mul_f32_e32 v209, 0x4f800000, v208
	v_cmp_gt_f32_e32 vcc, s26, v208
	v_and_b32_e32 v180, 0xffff0000, v180
	s_waitcnt vmcnt(4)
	v_lshlrev_b32_e32 v219, 16, v179
	v_cndmask_b32_e32 v210, v208, v209, vcc
	v_sqrt_f32_e32 v211, v210
	v_lshlrev_b32_e32 v218, 16, v178
	v_and_b32_e32 v179, 0xffff0000, v179
	v_and_b32_e32 v178, 0xffff0000, v178
	v_add_u32_e32 v212, -1, v211
	v_add_u32_e32 v213, 1, v211
	v_fma_f32 v214, -v212, v211, v210
	v_fma_f32 v215, -v213, v211, v210
	v_cmp_ge_f32_e64 s[8:9], 0, v214
	v_add_u32_e32 v160, s27, v193
	v_lshlrev_b64 v[208:209], 12, v[160:161]
	v_cndmask_b32_e64 v211, v211, v212, s[8:9]
	v_cmp_lt_f32_e64 s[8:9], 0, v215
	v_lshl_add_u64 v[208:209], v[168:169], 0, v[208:209]
	s_add_i32 s27, s27, 64
	v_cndmask_b32_e64 v211, v211, v213, s[8:9]
	v_mul_f32_e32 v212, 0x37800000, v211
	v_cndmask_b32_e32 v211, v211, v212, vcc
	v_cmp_class_f32_e32 vcc, v210, v203
	s_add_i32 s0, s0, 1
	v_lshl_add_u64 v[170:171], v[170:171], 0, s[14:15]
	v_cndmask_b32_e32 v210, v211, v210, vcc
	v_div_scale_f32 v211, s[8:9], v210, v210, 1.0
	v_rcp_f32_e32 v212, v211
	v_div_scale_f32 v213, vcc, 1.0, v210, 1.0
	s_cmpk_eq_i32 s27, 0x400
	v_fma_f32 v214, -v211, v212, 1.0
	v_fmac_f32_e32 v212, v214, v212
	v_mul_f32_e32 v214, v213, v212
	v_fma_f32 v215, -v211, v214, v213
	v_fmac_f32_e32 v214, v215, v212
	v_fma_f32 v211, -v211, v214, v213
	v_div_fmas_f32 v211, v211, v212, v214
	v_div_fixup_f32 v210, v211, v210, 1.0
	v_pk_mul_f32 v[134:135], v[134:135], v[210:211] op_sel_hi:[1,0]
	v_pk_mul_f32 v[132:133], v[132:133], v[210:211] op_sel_hi:[1,0]
	v_pk_mul_f32 v[130:131], v[130:131], v[210:211] op_sel_hi:[1,0]
	v_pk_mul_f32 v[128:129], v[128:129], v[210:211] op_sel_hi:[1,0]
	v_lshl_add_u64 v[172:173], v[172:173], 0, s[16:17]
	s_waitcnt vmcnt(0)
	v_pk_mul_f32 v[132:133], v[140:141], v[132:133]
	v_pk_mul_f32 v[134:135], v[142:143], v[134:135]
	v_pk_mul_f32 v[128:129], v[136:137], v[128:129]
	v_pk_mul_f32 v[130:131], v[138:139], v[130:131]
	v_mov_b32_e32 v210, v132
	v_mov_b32_e32 v211, v134
	v_mov_b32_e32 v134, v133
	v_mov_b32_e32 v132, v128
	v_mov_b32_e32 v133, v130
	v_mov_b32_e32 v130, v129
	v_pk_mul_f32 v[128:129], v[210:211], v[216:217]
	v_pk_mul_f32 v[134:135], v[134:135], v[180:181]
	v_pk_mul_f32 v[178:179], v[130:131], v[178:179]
	v_cvt_pk_bf16_f32 v128, v128, v134
	v_cvt_pk_bf16_f32 v129, v129, v135
	v_pk_mul_f32 v[132:133], v[132:133], v[218:219]
	global_store_dwordx2 v[208:209], v[128:129], off offset:2048
	ds_read_b128 v[128:131], v205
	v_cvt_pk_bf16_f32 v232, v132, v178
	v_cvt_pk_bf16_f32 v255, v133, v179
	ds_read_b128 v[132:135], v205 offset:16
	s_waitcnt lgkmcnt(1)
	v_mov_b32_e32 v180, v129
	v_mov_b32_e32 v181, v130
	v_mov_b32_e32 v129, v131
	v_pk_add_f32 v[128:129], v[180:181], v[128:129]
	s_waitcnt lgkmcnt(0)
	v_mov_b32_e32 v130, v134
	v_mov_b32_e32 v131, v132
	v_mov_b32_e32 v132, v135
	v_pk_add_f32 v[130:131], v[130:131], v[132:133]
	v_add_f32_e32 v128, v128, v129
	v_add_f32_e32 v128, v128, v131
	v_add_f32_e32 v128, v130, v128
	v_fmamk_f32 v128, v128, 0x3b800000, v202
	v_mul_f32_e32 v129, 0x4f800000, v128
	v_cmp_gt_f32_e32 vcc, s26, v128
	s_nop 1
	v_cndmask_b32_e32 v128, v128, v129, vcc
	v_sqrt_f32_e32 v129, v128
	s_nop 0
	v_add_u32_e32 v132, -1, v129
	v_fma_f32 v133, -v132, v129, v128
	v_cmp_ge_f32_e64 s[8:9], 0, v133
	v_add_u32_e32 v133, 1, v129
	s_nop 0
	v_cndmask_b32_e64 v132, v129, v132, s[8:9]
	v_fma_f32 v129, -v133, v129, v128
	v_cmp_lt_f32_e64 s[8:9], 0, v129
	s_nop 1
	v_cndmask_b32_e64 v129, v132, v133, s[8:9]
	v_mul_f32_e32 v132, 0x37800000, v129
	v_cndmask_b32_e32 v129, v129, v132, vcc
	v_cmp_class_f32_e32 vcc, v128, v203
	s_nop 1
	v_cndmask_b32_e32 v132, v129, v128, vcc
	v_div_scale_f32 v133, s[8:9], v132, v132, 1.0
	v_rcp_f32_e32 v134, v133
	v_mov_b32_e32 v129, v255
	v_mov_b32_e32 v128, v232
	global_store_dwordx2 v[208:209], v[128:129], off offset:2080
	v_fma_f32 v128, -v133, v134, 1.0
	v_fmac_f32_e32 v134, v128, v134
	v_div_scale_f32 v128, vcc, 1.0, v132, 1.0
	v_mul_f32_e32 v129, v128, v134
	v_fma_f32 v130, -v133, v129, v128
	v_fmac_f32_e32 v129, v130, v134
	v_fma_f32 v128, -v133, v129, v128
	v_div_fmas_f32 v128, v128, v134, v129
	v_div_fixup_f32 v128, v128, v132, 1.0
	v_pk_mul_f32 v[126:127], v[126:127], v[128:129] op_sel_hi:[1,0]
	v_pk_mul_f32 v[124:125], v[124:125], v[128:129] op_sel_hi:[1,0]
	v_pk_mul_f32 v[126:127], v[142:143], v[126:127]
	v_pk_mul_f32 v[124:125], v[140:141], v[124:125]
	v_lshlrev_b32_e32 v133, 16, v177
	v_lshlrev_b32_e32 v132, 16, v176
	v_mov_b32_e32 v134, v124
	v_mov_b32_e32 v135, v126
	v_pk_mul_f32 v[132:133], v[134:135], v[132:133]
	v_and_b32_e32 v135, 0xffff0000, v177
	v_and_b32_e32 v134, 0xffff0000, v176
	v_mov_b32_e32 v126, v125
	v_pk_mul_f32 v[124:125], v[126:127], v[134:135]
	s_nop 0
	v_and_b32_sdwa v129, v125, v204 dst_sel:DWORD dst_unused:UNUSED_PAD src0_sel:WORD_1 src1_sel:DWORD
	v_cvt_pk_bf16_f32 v124, v132, v124
	v_add_u32_e32 v130, 16, v160
	v_mov_b32_e32 v131, v161
	v_cvt_pk_bf16_f32 v125, v133, v125
	v_lshlrev_b64 v[130:131], 12, v[130:131]
	v_pk_mul_f32 v[122:123], v[122:123], v[128:129] op_sel_hi:[1,0]
	v_pk_mul_f32 v[120:121], v[120:121], v[128:129] op_sel_hi:[1,0]
	v_lshl_add_u64 v[130:131], v[168:169], 0, v[130:131]
	v_pk_mul_f32 v[120:121], v[136:137], v[120:121]
	v_pk_mul_f32 v[122:123], v[138:139], v[122:123]
	global_store_dwordx2 v[130:131], v[124:125], off offset:2048
	v_lshlrev_b32_e32 v125, 16, v175
	v_lshlrev_b32_e32 v124, 16, v174
	v_mov_b32_e32 v126, v120
	v_mov_b32_e32 v127, v122
	v_pk_mul_f32 v[124:125], v[126:127], v[124:125]
	v_and_b32_e32 v127, 0xffff0000, v175
	v_and_b32_e32 v126, 0xffff0000, v174
	v_mov_b32_e32 v122, v121
	v_pk_mul_f32 v[128:129], v[122:123], v[126:127]
	ds_read_b128 v[120:123], v206
	v_cvt_pk_bf16_f32 v237, v124, v128
	v_cvt_pk_bf16_f32 v235, v125, v129
	ds_read_b128 v[124:127], v206 offset:16
	s_waitcnt lgkmcnt(1)
; #define LAS __attribute__((address_space(3)))
; __device__ __forceinline__ float bflo(unsigned w) { return __uint_as_float(w << 16); }
; __device__ __forceinline__ float bfhi(unsigned w) { return __uint_as_float(w & 0xffff0000u); }
; __device__ __forceinline__ unsigned pk2(float lo, float hi) { return f2bf(lo) | (f2bf(hi) << 16); }
; template <bool FULL>
; __device__ __forceinline__ void gla_pass(const Params& P, LAS unsigned char* lds, f32x4 (&S)[8][2], int bh, int c0, int L, bool dry) {
;     ...
;         if (FULL) {
;             f32x4 gn[2];
; #pragma unroll
;             for (int vt = 0; vt < 2; ++vt) gn[vt] = *(const f32x4*)(P.gla_norm_g + 32 * w + 4 * g + 16 * vt);
; #pragma unroll
;             for (int tt = 0; tt < 4; ++tt) {
;                 const int t = 16 * tt + fr;
;                 const f32x4 r0 = *(const LAS f32x4*)(red + t * 8), r1 = *(const LAS f32x4*)(red + t * 8 + 4);
;                 const float rstd = 1.0f / sqrtf(((r0[0] + r0[1]) + (r0[2] + r0[3]) + (r1[0] + r1[1]) + (r1[2] + r1[3])) * (1.0f / 256.0f) + RMS_EPS);
; #pragma unroll
;                 for (int vt = 0; vt < 2; ++vt) {
;                     bf16_t* op = (bf16_t*)P.out + (row0 + t) * 2048 + 1024 + h * 256 + 32 * w + 16 * vt + 4 * g;
;                     const u32x2 z = zb[vt][tt]; const f32x4 ov = o[vt][tt] * rstd * gn[vt];
;                     u32x2 r; r.x = pk2(ov[0] * bflo(z.x), ov[1] * bfhi(z.x)); r.y = pk2(ov[2] * bflo(z.y), ov[3] * bfhi(z.y));
;                     if (!dry) *(u32x2*)op = r;
;                 }
;             }
	v_mov_b32_e32 v132, v121
	v_mov_b32_e32 v133, v122
	v_mov_b32_e32 v121, v123
	v_pk_add_f32 v[120:121], v[132:133], v[120:121]
	s_waitcnt lgkmcnt(0)
	v_mov_b32_e32 v122, v126
	v_mov_b32_e32 v123, v124
	v_mov_b32_e32 v124, v127
	v_pk_add_f32 v[122:123], v[122:123], v[124:125]
	v_add_f32_e32 v120, v120, v121
	v_add_f32_e32 v120, v120, v123
	v_add_f32_e32 v120, v122, v120
	v_fmamk_f32 v120, v120, 0x3b800000, v202
	v_mul_f32_e32 v121, 0x4f800000, v120
	v_cmp_gt_f32_e32 vcc, s26, v120
	s_nop 1
	v_cndmask_b32_e32 v120, v120, v121, vcc
	v_sqrt_f32_e32 v121, v120
	s_nop 0
	v_add_u32_e32 v124, -1, v121
	v_fma_f32 v125, -v124, v121, v120
	v_cmp_ge_f32_e64 s[8:9], 0, v125
	v_add_u32_e32 v125, 1, v121
	s_nop 0
	v_cndmask_b32_e64 v124, v121, v124, s[8:9]
	v_fma_f32 v121, -v125, v121, v120
	v_cmp_lt_f32_e64 s[8:9], 0, v121
	s_nop 1
	v_cndmask_b32_e64 v121, v124, v125, s[8:9]
	v_mul_f32_e32 v124, 0x37800000, v121
	v_cndmask_b32_e32 v121, v121, v124, vcc
	v_cmp_class_f32_e32 vcc, v120, v203
	s_nop 1
	v_cndmask_b32_e32 v124, v121, v120, vcc
	v_div_scale_f32 v125, s[8:9], v124, v124, 1.0
	v_rcp_f32_e32 v126, v125
	v_mov_b32_e32 v121, v235
	v_mov_b32_e32 v120, v237
	global_store_dwordx2 v[130:131], v[120:121], off offset:2080
	v_fma_f32 v120, -v125, v126, 1.0
	v_fmac_f32_e32 v126, v120, v126
	v_div_scale_f32 v120, vcc, 1.0, v124, 1.0
	v_mul_f32_e32 v121, v120, v126
	v_fma_f32 v122, -v125, v121, v120
	v_fmac_f32_e32 v121, v122, v126
	v_fma_f32 v120, -v125, v121, v120
	v_div_fmas_f32 v120, v120, v126, v121
	v_div_fixup_f32 v120, v120, v124, 1.0
	v_pk_mul_f32 v[110:111], v[110:111], v[120:121] op_sel_hi:[1,0]
	v_pk_mul_f32 v[108:109], v[108:109], v[120:121] op_sel_hi:[1,0]
	v_pk_mul_f32 v[110:111], v[142:143], v[110:111]
	v_pk_mul_f32 v[108:109], v[140:141], v[108:109]
	v_lshlrev_b32_e32 v125, 16, v151
	v_lshlrev_b32_e32 v124, 16, v150
	v_mov_b32_e32 v126, v108
	v_mov_b32_e32 v127, v110
	v_pk_mul_f32 v[124:125], v[126:127], v[124:125]
	v_and_b32_e32 v127, 0xffff0000, v151
	v_and_b32_e32 v126, 0xffff0000, v150
	v_mov_b32_e32 v110, v109
	v_pk_mul_f32 v[108:109], v[110:111], v[126:127]
	s_nop 0
	v_and_b32_sdwa v121, v109, v204 dst_sel:DWORD dst_unused:UNUSED_PAD src0_sel:WORD_1 src1_sel:DWORD
	v_cvt_pk_bf16_f32 v108, v124, v108
	v_add_u32_e32 v122, 32, v160
	v_mov_b32_e32 v123, v161
	v_cvt_pk_bf16_f32 v109, v125, v109
	v_lshlrev_b64 v[122:123], 12, v[122:123]
	v_pk_mul_f32 v[106:107], v[106:107], v[120:121] op_sel_hi:[1,0]
	v_pk_mul_f32 v[104:105], v[104:105], v[120:121] op_sel_hi:[1,0]
	v_lshl_add_u64 v[122:123], v[168:169], 0, v[122:123]
	v_pk_mul_f32 v[104:105], v[136:137], v[104:105]
	v_pk_mul_f32 v[106:107], v[138:139], v[106:107]
	global_store_dwordx2 v[122:123], v[108:109], off offset:2048
	v_lshlrev_b32_e32 v109, 16, v149
	v_lshlrev_b32_e32 v108, 16, v148
	v_mov_b32_e32 v110, v104
	v_mov_b32_e32 v111, v106
	v_pk_mul_f32 v[108:109], v[110:111], v[108:109]
	v_and_b32_e32 v111, 0xffff0000, v149
	v_and_b32_e32 v110, 0xffff0000, v148
	v_mov_b32_e32 v106, v105
	v_pk_mul_f32 v[120:121], v[106:107], v[110:111]
	ds_read_b128 v[104:107], v207
	v_cvt_pk_bf16_f32 v255, v108, v120
	v_cvt_pk_bf16_f32 v254, v109, v121
	ds_read_b128 v[108:111], v207 offset:16
	s_waitcnt lgkmcnt(1)
	v_mov_b32_e32 v124, v105
	v_mov_b32_e32 v125, v106
	v_mov_b32_e32 v105, v107
	v_pk_add_f32 v[104:105], v[124:125], v[104:105]
	s_waitcnt lgkmcnt(0)
	v_mov_b32_e32 v106, v110
	v_mov_b32_e32 v107, v108
	v_mov_b32_e32 v108, v111
	v_pk_add_f32 v[106:107], v[106:107], v[108:109]
	v_add_f32_e32 v104, v104, v105
	v_add_f32_e32 v104, v104, v107
	v_add_f32_e32 v104, v106, v104
	v_fmamk_f32 v104, v104, 0x3b800000, v202
	v_mul_f32_e32 v105, 0x4f800000, v104
	v_cmp_gt_f32_e32 vcc, s26, v104
	s_nop 1
	v_cndmask_b32_e32 v104, v104, v105, vcc
	v_sqrt_f32_e32 v105, v104
	v_add_u32_e32 v160, 48, v160
	v_add_u32_e32 v108, -1, v105
	v_fma_f32 v109, -v108, v105, v104
	v_cmp_ge_f32_e64 s[8:9], 0, v109
	v_add_u32_e32 v109, 1, v105
	s_nop 0
	v_cndmask_b32_e64 v108, v105, v108, s[8:9]
	v_fma_f32 v105, -v109, v105, v104
	v_cmp_lt_f32_e64 s[8:9], 0, v105
	s_nop 1
	v_cndmask_b32_e64 v105, v108, v109, s[8:9]
	v_mul_f32_e32 v108, 0x37800000, v105
	v_cndmask_b32_e32 v105, v105, v108, vcc
	v_cmp_class_f32_e32 vcc, v104, v203
	s_nop 1
	v_cndmask_b32_e32 v108, v105, v104, vcc
	v_div_scale_f32 v109, s[8:9], v108, v108, 1.0
	v_rcp_f32_e32 v110, v109
	v_mov_b32_e32 v105, v254
	v_mov_b32_e32 v104, v255
	global_store_dwordx2 v[122:123], v[104:105], off offset:2080
	v_fma_f32 v104, -v109, v110, 1.0
	v_fmac_f32_e32 v110, v104, v110
	v_div_scale_f32 v104, vcc, 1.0, v108, 1.0
	v_mul_f32_e32 v105, v104, v110
	v_fma_f32 v106, -v109, v105, v104
	v_fmac_f32_e32 v105, v106, v110
	v_fma_f32 v104, -v109, v105, v104
	v_div_fmas_f32 v104, v104, v110, v105
	v_div_fixup_f32 v104, v104, v108, 1.0
	v_pk_mul_f32 v[108:109], v[118:119], v[104:105] op_sel_hi:[1,0]
	v_pk_mul_f32 v[110:111], v[116:117], v[104:105] op_sel_hi:[1,0]
	v_pk_mul_f32 v[108:109], v[142:143], v[108:109]
	v_pk_mul_f32 v[110:111], v[140:141], v[110:111]
	v_lshlrev_b32_e32 v117, 16, v147
	v_lshlrev_b32_e32 v116, 16, v146
	v_mov_b32_e32 v118, v110
	v_mov_b32_e32 v119, v108
	v_pk_mul_f32 v[116:117], v[118:119], v[116:117]
	v_and_b32_e32 v119, 0xffff0000, v147
	v_and_b32_e32 v118, 0xffff0000, v146
	v_mov_b32_e32 v108, v111
	v_pk_mul_f32 v[108:109], v[108:109], v[118:119]
	s_nop 0
	v_cvt_pk_bf16_f32 v108, v116, v108
	v_and_b32_sdwa v105, v117, v204 dst_sel:DWORD dst_unused:UNUSED_PAD src0_sel:WORD_1 src1_sel:DWORD
	v_cvt_pk_bf16_f32 v109, v117, v109
	v_lshlrev_b64 v[106:107], 12, v[160:161]
	v_add3_u32 v105, v117, v105, s1
	v_lshl_add_u64 v[106:107], v[168:169], 0, v[106:107]
	global_store_dwordx2 v[106:107], v[108:109], off offset:2048
	v_pk_mul_f32 v[108:109], v[114:115], v[104:105] op_sel_hi:[1,0]
	v_pk_mul_f32 v[104:105], v[112:113], v[104:105] op_sel_hi:[1,0]
	v_pk_mul_f32 v[108:109], v[138:139], v[108:109]
	v_pk_mul_f32 v[104:105], v[136:137], v[104:105]
	v_lshlrev_b32_e32 v111, 16, v145
	v_lshlrev_b32_e32 v110, 16, v144
	v_mov_b32_e32 v112, v104
	v_mov_b32_e32 v113, v108
	v_pk_mul_f32 v[110:111], v[112:113], v[110:111]
	v_and_b32_e32 v113, 0xffff0000, v145
	v_and_b32_e32 v112, 0xffff0000, v144
	v_mov_b32_e32 v108, v105
	v_pk_mul_f32 v[104:105], v[108:109], v[112:113]
	s_nop 0
	v_cvt_pk_bf16_f32 v104, v110, v104
	v_cvt_pk_bf16_f32 v105, v111, v105
	global_store_dwordx2 v[106:107], v[104:105], off offset:2080
	s_barrier
	s_cbranch_scc1 .LBB0_714
